# k20 plus: the 36 duplicate s_waitcnt lgkmcnt(0) that follow s_barrier + s_setprio 1 in the GEMM mainloops removed (the inline-asm wait two lines earlier already drained LDS)
# speedup vs baseline: 1.0032x; 1.0032x over previous
; #define PG8_STAGE(bufoff, gbase, voff) do { _Pragma("unroll") for (int _i = 0; _i < 2; ++_i) \
;         __builtin_amdgcn_global_load_lds((const unsigned*)((const char*)(gbase) + (voff)[_i]), (LAS unsigned*)(lds + (bufoff) + ldsw + _i * 8192), 16, 0, 0); } while (0)
; #define PG8_LDA(dst, b, h) do { _Pragma("unroll") for (int m = 0; m < 4; ++m) _Pragma("unroll") for (int k = 0; k < 2; ++k) dst[m][k] = *(const LAS bf16x8*)(lds + PG8_SA(b, h) + aoff + m * 2048 + k * 1024); } while (0)
; #define PG8_LDB(dst, b, h) do { _Pragma("unroll") for (int n = 0; n < 2; ++n) _Pragma("unroll") for (int k = 0; k < 2; ++k) dst[n][k] = *(const LAS bf16x8*)(lds + PG8_SB(b, h) + boff + n * 2048 + k * 1024); } while (0)
; #define PG8_WAIT_V(n) asm volatile("s_waitcnt vmcnt(" #n ")" ::: "memory")
; template <class Epi, class Sched, bool ALIGN_EPI = true, bool SP2 = true>
; __device__ __forceinline__ void gemm_phase(LAS unsigned char* lds, const Gemm g, const Sched& S, const Epi& E) {
;     ...
;         for (int t = 0; t < nt; t += 2) {
;             const bool last = (t == nt - 2);
;             const char* a1 = cA + (size_t)(t + 1) * kstep;
;             const char* a2 = last ? nA : cA + (size_t)(t + 2) * kstep; const char* b2 = last ? nB : cB + (size_t)(t + 2) * kstep;
;             const char* a3 = a2 + kstep; const char* b3 = b2 + kstep;
;             PG8_LDB(B0, 0, 0); PG8_LDB(B1, 0, 1); PG8_SCHED; PG8_LDA(At, 0, 0); PG8_STAGE(PG8_SA(1, 1), a1 + hstepA, voffA);
;             PG8_WAIT_V(8); PG8_WAIT_L(0); PG8_BAR; PG8_MMA(0, 0, At, B0); PG8_MMA(0, 1, At, B1); PG8_BAR; PG8_SCHED;
;             PG8_LDA(At, 0, 1); PG8_STAGE(PG8_SB(0, 0), b2, voffB); PG8_STAGE(PG8_SB(0, 1), b2 + hstepB, voffB); PG8_STAGE(PG8_SA(0, 0), a2, voffA);
;             PG8_WAIT_V(8); PG8_WAIT_L(0); PG8_BAR; PG8_MMA(1, 0, At, B0); PG8_MMA(1, 1, At, B1); PG8_BAR; PG8_SCHED;
;             PG8_LDB(B0, 1, 0); PG8_LDB(B1, 1, 1); PG8_SCHED; PG8_LDA(At, 1, 0); PG8_STAGE(PG8_SA(0, 1), a2 + hstepA, voffA);
;             PG8_WAIT_V(8); PG8_WAIT_L(0); PG8_BAR; PG8_MMA(0, 0, At, B0); PG8_MMA(0, 1, At, B1); PG8_BAR; PG8_SCHED;
;             PG8_LDA(At, 1, 1); PG8_STAGE(PG8_SB(1, 0), b3, voffB); PG8_STAGE(PG8_SB(1, 1), b3 + hstepB, voffB); PG8_STAGE(PG8_SA(1, 0), a3, voffA);
;             PG8_WAIT_V(8); PG8_WAIT_L(0); PG8_BAR; PG8_MMA(1, 0, At, B0); PG8_MMA(1, 1, At, B1); PG8_BAR; PG8_SCHED;
.LBB0_205:
	s_add_u32 s35, s36, 0xfffc0080
	s_addc_u32 s42, s37, -1
	s_add_i32 s58, 0, 0x10000
	s_cmp_eq_u32 s27, 12
	s_cselect_b32 s45, s1, s42
	s_cselect_b32 s44, s2, s35
	v_add_u32_e32 v140, s58, v141
	s_cselect_b32 s43, s8, s25
	s_cselect_b32 s42, s9, s15
	s_add_i32 s35, 0, 0x14000
	ds_read_b128 v[142:145], v140
	ds_read_b128 v[148:151], v140 offset:1024
	ds_read_b128 v[152:155], v140 offset:2048
	ds_read_b128 v[156:159], v140 offset:3072
	v_add_u32_e32 v140, s35, v141
	ds_read_b128 v[160:163], v140
	ds_read_b128 v[164:167], v140 offset:1024
	ds_read_b128 v[168:171], v140 offset:2048
	ds_read_b128 v[172:175], v140 offset:3072
	v_lshl_add_u64 v[212:213], s[36:37], 0, v[136:137]
	s_add_i32 m0, s64, 0xc000
	ds_read_b128 v[176:179], v146
	ds_read_b128 v[180:183], v146 offset:1024
	ds_read_b128 v[184:187], v146 offset:2048
	ds_read_b128 v[188:191], v146 offset:3072
	ds_read_b128 v[196:199], v146 offset:4096
	ds_read_b128 v[200:203], v146 offset:5120
	ds_read_b128 v[204:207], v146 offset:6144
	ds_read_b128 v[208:211], v146 offset:7168
	global_load_lds_dwordx4 v[212:213], off
	v_lshl_add_u64 v[212:213], s[36:37], 0, v[138:139]
	s_add_i32 m0, s64, 0xe000
	s_nop 0
	global_load_lds_dwordx4 v[212:213], off
	s_waitcnt vmcnt(8)
	s_waitcnt lgkmcnt(0)
	s_barrier
	s_setprio 1
	v_mfma_f32_16x16x32_bf16 v[126:129], v[142:145], v[176:179], v[126:129]
	v_mfma_f32_16x16x32_bf16 v[122:125], v[152:155], v[176:179], v[122:125]
	v_mfma_f32_16x16x32_bf16 v[110:113], v[142:145], v[184:187], v[110:113]
	v_mfma_f32_16x16x32_bf16 v[106:109], v[152:155], v[184:187], v[106:109]
	v_mfma_f32_16x16x32_bf16 v[94:97], v[142:145], v[196:199], v[94:97]
	v_mfma_f32_16x16x32_bf16 v[90:93], v[152:155], v[196:199], v[90:93]
	v_mfma_f32_16x16x32_bf16 v[78:81], v[142:145], v[204:207], v[78:81]
	v_mfma_f32_16x16x32_bf16 v[74:77], v[152:155], v[204:207], v[74:77]
	v_mfma_f32_16x16x32_bf16 v[126:129], v[148:151], v[180:183], v[126:129]
	v_mfma_f32_16x16x32_bf16 v[122:125], v[156:159], v[180:183], v[122:125]
	v_mfma_f32_16x16x32_bf16 v[110:113], v[148:151], v[188:191], v[110:113]
	v_mfma_f32_16x16x32_bf16 v[106:109], v[156:159], v[188:191], v[106:109]
	v_mfma_f32_16x16x32_bf16 v[94:97], v[148:151], v[200:203], v[94:97]
	v_mfma_f32_16x16x32_bf16 v[90:93], v[156:159], v[200:203], v[90:93]
	v_mfma_f32_16x16x32_bf16 v[78:81], v[148:151], v[208:211], v[78:81]
	v_mfma_f32_16x16x32_bf16 v[74:77], v[156:159], v[208:211], v[74:77]
	s_setprio 0
	s_setprio 1
	v_mfma_f32_16x16x32_bf16 v[118:121], v[160:163], v[176:179], v[118:121]
	v_mfma_f32_16x16x32_bf16 v[114:117], v[168:171], v[176:179], v[114:117]
	v_mfma_f32_16x16x32_bf16 v[102:105], v[160:163], v[184:187], v[102:105]
	v_mfma_f32_16x16x32_bf16 v[98:101], v[168:171], v[184:187], v[98:101]
	v_mfma_f32_16x16x32_bf16 v[86:89], v[160:163], v[196:199], v[86:89]
	v_mfma_f32_16x16x32_bf16 v[82:85], v[168:171], v[196:199], v[82:85]
	v_mfma_f32_16x16x32_bf16 v[70:73], v[160:163], v[204:207], v[70:73]
	v_mfma_f32_16x16x32_bf16 v[66:69], v[168:171], v[204:207], v[66:69]
	v_mfma_f32_16x16x32_bf16 v[118:121], v[164:167], v[180:183], v[118:121]
	v_mfma_f32_16x16x32_bf16 v[114:117], v[172:175], v[180:183], v[114:117]
	v_mfma_f32_16x16x32_bf16 v[102:105], v[164:167], v[188:191], v[102:105]
	v_mfma_f32_16x16x32_bf16 v[98:101], v[172:175], v[188:191], v[98:101]
	v_mfma_f32_16x16x32_bf16 v[86:89], v[164:167], v[200:203], v[86:89]
	v_mfma_f32_16x16x32_bf16 v[82:85], v[172:175], v[200:203], v[82:85]
	v_mfma_f32_16x16x32_bf16 v[70:73], v[164:167], v[208:211], v[70:73]
	v_mfma_f32_16x16x32_bf16 v[66:69], v[172:175], v[208:211], v[66:69]
	s_setprio 0
	s_barrier
	s_add_i32 s58, s58, s62
	v_lshl_add_u64 v[212:213], s[42:43], 0, v[0:1]
	s_mov_b32 m0, s58
	ds_read_b128 v[176:179], v146 offset:16384
	ds_read_b128 v[180:183], v146 offset:17408
	ds_read_b128 v[184:187], v146 offset:18432
	ds_read_b128 v[188:191], v146 offset:19456
	ds_read_b128 v[196:199], v146 offset:20480
	ds_read_b128 v[200:203], v146 offset:21504
	ds_read_b128 v[204:207], v146 offset:22528
	ds_read_b128 v[208:211], v146 offset:23552
	global_load_lds_dwordx4 v[212:213], off
	s_add_i32 m0, s58, 0x2000
	s_add_u32 s58, s42, 0x40000
	v_lshl_add_u64 v[214:215], s[42:43], 0, v[130:131]
	s_addc_u32 s59, s43, 0
	s_add_i32 s35, s35, s62
	global_load_lds_dwordx4 v[214:215], off
	v_lshl_add_u64 v[220:221], s[58:59], 0, v[0:1]
	s_mov_b32 m0, s35
	v_lshl_add_u64 v[222:223], s[44:45], 0, v[132:133]
	global_load_lds_dwordx4 v[220:221], off
	v_lshl_add_u64 v[220:221], s[58:59], 0, v[130:131]
	s_add_i32 m0, s35, 0x2000
	s_nop 0
	global_load_lds_dwordx4 v[220:221], off
	v_lshl_add_u64 v[220:221], s[44:45], 0, v[134:135]
	s_mov_b32 m0, s64
	s_nop 0
	global_load_lds_dwordx4 v[220:221], off
	s_mov_b32 m0, s65
	s_nop 0
	global_load_lds_dwordx4 v[222:223], off
	s_waitcnt vmcnt(8)
	s_waitcnt lgkmcnt(0)
	s_barrier
; #define PG8_STAGE(bufoff, gbase, voff) do { _Pragma("unroll") for (int _i = 0; _i < 2; ++_i) \
;         __builtin_amdgcn_global_load_lds((const unsigned*)((const char*)(gbase) + (voff)[_i]), (LAS unsigned*)(lds + (bufoff) + ldsw + _i * 8192), 16, 0, 0); } while (0)
; #define PG8_LDA(dst, b, h) do { _Pragma("unroll") for (int m = 0; m < 4; ++m) _Pragma("unroll") for (int k = 0; k < 2; ++k) dst[m][k] = *(const LAS bf16x8*)(lds + PG8_SA(b, h) + aoff + m * 2048 + k * 1024); } while (0)
; #define PG8_LDB(dst, b, h) do { _Pragma("unroll") for (int n = 0; n < 2; ++n) _Pragma("unroll") for (int k = 0; k < 2; ++k) dst[n][k] = *(const LAS bf16x8*)(lds + PG8_SB(b, h) + boff + n * 2048 + k * 1024); } while (0)
; #define PG8_MMA(ai, bj, At, Bt) do { __builtin_amdgcn_s_setprio(1); _Pragma("unroll") for (int m = 0; m < 4; ++m) _Pragma("unroll") for (int n = 0; n < 2; ++n) _Pragma("unroll") for (int k = 0; k < 2; ++k) \
;         acc[ai][bj][m][n] = __builtin_amdgcn_mfma_f32_16x16x32_bf16(Bt[n][k], At[m][k], acc[ai][bj][m][n], 0, 0, 0); __builtin_amdgcn_s_setprio(0); } while (0)
; #define PG8_WAIT_V(n) asm volatile("s_waitcnt vmcnt(" #n ")" ::: "memory")
; template <class Epi, class Sched, bool ALIGN_EPI = true, bool SP2 = true>
; __device__ __forceinline__ void gemm_phase(LAS unsigned char* lds, const Gemm g, const Sched& S, const Epi& E) {
;     ...
;             PG8_LDB(B0, 0, 0); PG8_LDB(B1, 0, 1); PG8_SCHED; PG8_LDA(At, 0, 0); PG8_STAGE(PG8_SA(1, 1), a1 + hstepA, voffA);
;             PG8_WAIT_V(8); PG8_WAIT_L(0); PG8_BAR; PG8_MMA(0, 0, At, B0); PG8_MMA(0, 1, At, B1); PG8_BAR; PG8_SCHED;
;             PG8_LDA(At, 0, 1); PG8_STAGE(PG8_SB(0, 0), b2, voffB); PG8_STAGE(PG8_SB(0, 1), b2 + hstepB, voffB); PG8_STAGE(PG8_SA(0, 0), a2, voffA);
;             PG8_WAIT_V(8); PG8_WAIT_L(0); PG8_BAR; PG8_MMA(1, 0, At, B0); PG8_MMA(1, 1, At, B1); PG8_BAR; PG8_SCHED;
;             PG8_LDB(B0, 1, 0); PG8_LDB(B1, 1, 1); PG8_SCHED; PG8_LDA(At, 1, 0); PG8_STAGE(PG8_SA(0, 1), a2 + hstepA, voffA);
;             PG8_WAIT_V(8); PG8_WAIT_L(0); PG8_BAR; PG8_MMA(0, 0, At, B0); PG8_MMA(0, 1, At, B1); PG8_BAR; PG8_SCHED;
;             PG8_LDA(At, 1, 1); PG8_STAGE(PG8_SB(1, 0), b3, voffB); PG8_STAGE(PG8_SB(1, 1), b3 + hstepB, voffB); PG8_STAGE(PG8_SA(1, 0), a3, voffA);
;             PG8_WAIT_V(8); PG8_WAIT_L(0); PG8_BAR; PG8_MMA(1, 0, At, B0); PG8_MMA(1, 1, At, B1); PG8_BAR; PG8_SCHED;
	s_setprio 1
	v_mfma_f32_16x16x32_bf16 v[62:65], v[142:145], v[176:179], v[62:65]
	v_mfma_f32_16x16x32_bf16 v[58:61], v[152:155], v[176:179], v[58:61]
	v_mfma_f32_16x16x32_bf16 v[46:49], v[142:145], v[184:187], v[46:49]
	v_mfma_f32_16x16x32_bf16 v[42:45], v[152:155], v[184:187], v[42:45]
	v_mfma_f32_16x16x32_bf16 v[30:33], v[142:145], v[196:199], v[30:33]
	v_mfma_f32_16x16x32_bf16 v[26:29], v[152:155], v[196:199], v[26:29]
	v_mfma_f32_16x16x32_bf16 v[14:17], v[142:145], v[204:207], v[14:17]
	v_mfma_f32_16x16x32_bf16 v[10:13], v[152:155], v[204:207], v[10:13]
	v_mfma_f32_16x16x32_bf16 v[62:65], v[148:151], v[180:183], v[62:65]
	v_mfma_f32_16x16x32_bf16 v[58:61], v[156:159], v[180:183], v[58:61]
	v_mfma_f32_16x16x32_bf16 v[46:49], v[148:151], v[188:191], v[46:49]
	v_mfma_f32_16x16x32_bf16 v[42:45], v[156:159], v[188:191], v[42:45]
	v_mfma_f32_16x16x32_bf16 v[30:33], v[148:151], v[200:203], v[30:33]
	v_mfma_f32_16x16x32_bf16 v[26:29], v[156:159], v[200:203], v[26:29]
	v_mfma_f32_16x16x32_bf16 v[14:17], v[148:151], v[208:211], v[14:17]
	v_mfma_f32_16x16x32_bf16 v[10:13], v[156:159], v[208:211], v[10:13]
	s_setprio 0
	s_setprio 1
	v_mfma_f32_16x16x32_bf16 v[54:57], v[160:163], v[176:179], v[54:57]
	v_mfma_f32_16x16x32_bf16 v[50:53], v[168:171], v[176:179], v[50:53]
	v_mfma_f32_16x16x32_bf16 v[38:41], v[160:163], v[184:187], v[38:41]
	v_mfma_f32_16x16x32_bf16 v[34:37], v[168:171], v[184:187], v[34:37]
	v_mfma_f32_16x16x32_bf16 v[22:25], v[160:163], v[196:199], v[22:25]
	v_mfma_f32_16x16x32_bf16 v[18:21], v[168:171], v[196:199], v[18:21]
	v_mfma_f32_16x16x32_bf16 v[6:9], v[160:163], v[204:207], v[6:9]
	v_mfma_f32_16x16x32_bf16 v[2:5], v[168:171], v[204:207], v[2:5]
	v_mfma_f32_16x16x32_bf16 v[54:57], v[164:167], v[180:183], v[54:57]
	v_mfma_f32_16x16x32_bf16 v[50:53], v[172:175], v[180:183], v[50:53]
	v_mfma_f32_16x16x32_bf16 v[38:41], v[164:167], v[188:191], v[38:41]
	v_mfma_f32_16x16x32_bf16 v[34:37], v[172:175], v[188:191], v[34:37]
	v_mfma_f32_16x16x32_bf16 v[22:25], v[164:167], v[200:203], v[22:25]
	v_mfma_f32_16x16x32_bf16 v[18:21], v[172:175], v[200:203], v[18:21]
	v_mfma_f32_16x16x32_bf16 v[6:9], v[164:167], v[208:211], v[6:9]
	v_mfma_f32_16x16x32_bf16 v[2:5], v[172:175], v[208:211], v[2:5]
	s_setprio 0
	s_barrier
	s_add_i32 s35, 0, 0x18000
	v_add_u32_e32 v140, s35, v141
	s_add_i32 s58, 0, 0x1c000
	ds_read_b128 v[142:145], v140
	ds_read_b128 v[148:151], v140 offset:1024
	ds_read_b128 v[152:155], v140 offset:2048
	ds_read_b128 v[156:159], v140 offset:3072
	v_add_u32_e32 v140, s58, v141
	ds_read_b128 v[160:163], v140
	ds_read_b128 v[164:167], v140 offset:1024
	ds_read_b128 v[168:171], v140 offset:2048
	ds_read_b128 v[172:175], v140 offset:3072
	s_add_u32 s44, s44, 0x40000
	s_addc_u32 s45, s45, 0
	s_mov_b32 m0, s46
	v_lshl_add_u64 v[224:225], s[44:45], 0, v[134:135]
	ds_read_b128 v[176:179], v146 offset:32768
	ds_read_b128 v[180:183], v146 offset:33792
	ds_read_b128 v[184:187], v146 offset:34816
	ds_read_b128 v[188:191], v146 offset:35840
	ds_read_b128 v[196:199], v146 offset:36864
	ds_read_b128 v[200:203], v146 offset:37888
	ds_read_b128 v[204:207], v146 offset:38912
	ds_read_b128 v[208:211], v146 offset:39936
	global_load_lds_dwordx4 v[224:225], off
	v_lshl_add_u64 v[224:225], s[44:45], 0, v[132:133]
	s_mov_b32 m0, s51
	s_nop 0
	global_load_lds_dwordx4 v[224:225], off
	s_waitcnt vmcnt(8)
	s_waitcnt lgkmcnt(0)
	s_barrier
	s_setprio 1
	v_mfma_f32_16x16x32_bf16 v[126:129], v[142:145], v[176:179], v[126:129]
	v_mfma_f32_16x16x32_bf16 v[122:125], v[152:155], v[176:179], v[122:125]
	v_mfma_f32_16x16x32_bf16 v[110:113], v[142:145], v[184:187], v[110:113]
	v_mfma_f32_16x16x32_bf16 v[106:109], v[152:155], v[184:187], v[106:109]
	v_mfma_f32_16x16x32_bf16 v[94:97], v[142:145], v[196:199], v[94:97]
	v_mfma_f32_16x16x32_bf16 v[90:93], v[152:155], v[196:199], v[90:93]
	v_mfma_f32_16x16x32_bf16 v[78:81], v[142:145], v[204:207], v[78:81]
	v_mfma_f32_16x16x32_bf16 v[74:77], v[152:155], v[204:207], v[74:77]
	v_mfma_f32_16x16x32_bf16 v[126:129], v[148:151], v[180:183], v[126:129]
	v_mfma_f32_16x16x32_bf16 v[122:125], v[156:159], v[180:183], v[122:125]
	v_mfma_f32_16x16x32_bf16 v[110:113], v[148:151], v[188:191], v[110:113]
	v_mfma_f32_16x16x32_bf16 v[106:109], v[156:159], v[188:191], v[106:109]
	v_mfma_f32_16x16x32_bf16 v[94:97], v[148:151], v[200:203], v[94:97]
	v_mfma_f32_16x16x32_bf16 v[90:93], v[156:159], v[200:203], v[90:93]
	v_mfma_f32_16x16x32_bf16 v[78:81], v[148:151], v[208:211], v[78:81]
	v_mfma_f32_16x16x32_bf16 v[74:77], v[156:159], v[208:211], v[74:77]
	s_setprio 0
	s_setprio 1
	v_mfma_f32_16x16x32_bf16 v[118:121], v[160:163], v[176:179], v[118:121]
	v_mfma_f32_16x16x32_bf16 v[114:117], v[168:171], v[176:179], v[114:117]
	v_mfma_f32_16x16x32_bf16 v[102:105], v[160:163], v[184:187], v[102:105]
	v_mfma_f32_16x16x32_bf16 v[98:101], v[168:171], v[184:187], v[98:101]
	v_mfma_f32_16x16x32_bf16 v[86:89], v[160:163], v[196:199], v[86:89]
	v_mfma_f32_16x16x32_bf16 v[82:85], v[168:171], v[196:199], v[82:85]
	v_mfma_f32_16x16x32_bf16 v[70:73], v[160:163], v[204:207], v[70:73]
	v_mfma_f32_16x16x32_bf16 v[66:69], v[168:171], v[204:207], v[66:69]
	v_mfma_f32_16x16x32_bf16 v[118:121], v[164:167], v[180:183], v[118:121]
	v_mfma_f32_16x16x32_bf16 v[114:117], v[172:175], v[180:183], v[114:117]
	v_mfma_f32_16x16x32_bf16 v[102:105], v[164:167], v[188:191], v[102:105]
	v_mfma_f32_16x16x32_bf16 v[98:101], v[172:175], v[188:191], v[98:101]
	v_mfma_f32_16x16x32_bf16 v[86:89], v[164:167], v[200:203], v[86:89]
	v_mfma_f32_16x16x32_bf16 v[82:85], v[172:175], v[200:203], v[82:85]
	v_mfma_f32_16x16x32_bf16 v[70:73], v[164:167], v[208:211], v[70:73]
	v_mfma_f32_16x16x32_bf16 v[66:69], v[172:175], v[208:211], v[66:69]
	s_setprio 0
	s_barrier
; #define PG8_STAGE(bufoff, gbase, voff) do { _Pragma("unroll") for (int _i = 0; _i < 2; ++_i) \
;         __builtin_amdgcn_global_load_lds((const unsigned*)((const char*)(gbase) + (voff)[_i]), (LAS unsigned*)(lds + (bufoff) + ldsw + _i * 8192), 16, 0, 0); } while (0)
; #define PG8_LDA(dst, b, h) do { _Pragma("unroll") for (int m = 0; m < 4; ++m) _Pragma("unroll") for (int k = 0; k < 2; ++k) dst[m][k] = *(const LAS bf16x8*)(lds + PG8_SA(b, h) + aoff + m * 2048 + k * 1024); } while (0)
; #define PG8_LDB(dst, b, h) do { _Pragma("unroll") for (int n = 0; n < 2; ++n) _Pragma("unroll") for (int k = 0; k < 2; ++k) dst[n][k] = *(const LAS bf16x8*)(lds + PG8_SB(b, h) + boff + n * 2048 + k * 1024); } while (0)
; #define PG8_MMA(ai, bj, At, Bt) do { __builtin_amdgcn_s_setprio(1); _Pragma("unroll") for (int m = 0; m < 4; ++m) _Pragma("unroll") for (int n = 0; n < 2; ++n) _Pragma("unroll") for (int k = 0; k < 2; ++k) \
;         acc[ai][bj][m][n] = __builtin_amdgcn_mfma_f32_16x16x32_bf16(Bt[n][k], At[m][k], acc[ai][bj][m][n], 0, 0, 0); __builtin_amdgcn_s_setprio(0); } while (0)
; template <class Epi, class Sched, bool ALIGN_EPI = true, bool SP2 = true>
; __device__ __forceinline__ void gemm_phase(LAS unsigned char* lds, const Gemm g, const Sched& S, const Epi& E) {
;     ...
;             PG8_LDB(B0, 0, 0); PG8_LDB(B1, 0, 1); PG8_SCHED; PG8_LDA(At, 0, 0); PG8_STAGE(PG8_SA(1, 1), a1 + hstepA, voffA);
;             PG8_WAIT_V(8); PG8_WAIT_L(0); PG8_BAR; PG8_MMA(0, 0, At, B0); PG8_MMA(0, 1, At, B1); PG8_BAR; PG8_SCHED;
;             PG8_LDA(At, 0, 1); PG8_STAGE(PG8_SB(0, 0), b2, voffB); PG8_STAGE(PG8_SB(0, 1), b2 + hstepB, voffB); PG8_STAGE(PG8_SA(0, 0), a2, voffA);
;             PG8_WAIT_V(8); PG8_WAIT_L(0); PG8_BAR; PG8_MMA(1, 0, At, B0); PG8_MMA(1, 1, At, B1); PG8_BAR; PG8_SCHED;
;             PG8_LDB(B0, 1, 0); PG8_LDB(B1, 1, 1); PG8_SCHED; PG8_LDA(At, 1, 0); PG8_STAGE(PG8_SA(0, 1), a2 + hstepA, voffA);
;             PG8_WAIT_V(8); PG8_WAIT_L(0); PG8_BAR; PG8_MMA(0, 0, At, B0); PG8_MMA(0, 1, At, B1); PG8_BAR; PG8_SCHED;
;             PG8_LDA(At, 1, 1); PG8_STAGE(PG8_SB(1, 0), b3, voffB); PG8_STAGE(PG8_SB(1, 1), b3 + hstepB, voffB); PG8_STAGE(PG8_SA(1, 0), a3, voffA);
;             PG8_WAIT_V(8); PG8_WAIT_L(0); PG8_BAR; PG8_MMA(1, 0, At, B0); PG8_MMA(1, 1, At, B1); PG8_BAR; PG8_SCHED;
;         }
;         if constexpr (ALIGN_EPI) { if (wr == 0) PG8_BAR; }
	s_add_i32 s35, s35, s62
	v_lshl_add_u64 v[212:213], v[212:213], 0, s[12:13]
	s_mov_b32 m0, s35
	ds_read_b128 v[176:179], v146 offset:49152
	ds_read_b128 v[180:183], v146 offset:50176
	ds_read_b128 v[184:187], v146 offset:51200
	ds_read_b128 v[188:191], v146 offset:52224
	ds_read_b128 v[196:199], v146 offset:53248
	ds_read_b128 v[200:203], v146 offset:54272
	ds_read_b128 v[204:207], v146 offset:55296
	ds_read_b128 v[208:211], v146 offset:56320
	global_load_lds_dwordx4 v[212:213], off
	s_add_i32 m0, s35, 0x2000
	s_add_u32 s42, s42, 0x40080
	v_lshl_add_u64 v[212:213], v[214:215], 0, s[12:13]
	s_addc_u32 s43, s43, 0
	s_add_i32 s35, s58, s62
	global_load_lds_dwordx4 v[212:213], off
	v_lshl_add_u64 v[212:213], s[42:43], 0, v[0:1]
	s_mov_b32 m0, s35
	s_nop 0
	global_load_lds_dwordx4 v[212:213], off
	v_lshl_add_u64 v[212:213], s[42:43], 0, v[130:131]
	s_add_i32 m0, s35, 0x2000
	s_nop 0
	global_load_lds_dwordx4 v[212:213], off
	v_lshl_add_u64 v[212:213], v[220:221], 0, s[12:13]
	s_mov_b32 m0, s16
	s_nop 0
	global_load_lds_dwordx4 v[212:213], off
	v_lshl_add_u64 v[212:213], v[222:223], 0, s[12:13]
	s_mov_b32 m0, s17
	s_nop 0
	global_load_lds_dwordx4 v[212:213], off
	s_waitcnt vmcnt(8)
	s_waitcnt lgkmcnt(0)
	s_barrier
	s_setprio 1
	v_mfma_f32_16x16x32_bf16 v[62:65], v[142:145], v[176:179], v[62:65]
	v_mfma_f32_16x16x32_bf16 v[58:61], v[152:155], v[176:179], v[58:61]
	v_mfma_f32_16x16x32_bf16 v[46:49], v[142:145], v[184:187], v[46:49]
	v_mfma_f32_16x16x32_bf16 v[42:45], v[152:155], v[184:187], v[42:45]
	v_mfma_f32_16x16x32_bf16 v[30:33], v[142:145], v[196:199], v[30:33]
	v_mfma_f32_16x16x32_bf16 v[26:29], v[152:155], v[196:199], v[26:29]
	v_mfma_f32_16x16x32_bf16 v[14:17], v[142:145], v[204:207], v[14:17]
	v_mfma_f32_16x16x32_bf16 v[10:13], v[152:155], v[204:207], v[10:13]
	v_mfma_f32_16x16x32_bf16 v[62:65], v[148:151], v[180:183], v[62:65]
	v_mfma_f32_16x16x32_bf16 v[58:61], v[156:159], v[180:183], v[58:61]
	v_mfma_f32_16x16x32_bf16 v[46:49], v[148:151], v[188:191], v[46:49]
	v_mfma_f32_16x16x32_bf16 v[42:45], v[156:159], v[188:191], v[42:45]
	v_mfma_f32_16x16x32_bf16 v[30:33], v[148:151], v[200:203], v[30:33]
	v_mfma_f32_16x16x32_bf16 v[26:29], v[156:159], v[200:203], v[26:29]
	v_mfma_f32_16x16x32_bf16 v[14:17], v[148:151], v[208:211], v[14:17]
	v_mfma_f32_16x16x32_bf16 v[10:13], v[156:159], v[208:211], v[10:13]
	s_setprio 0
	s_setprio 1
	v_mfma_f32_16x16x32_bf16 v[54:57], v[160:163], v[176:179], v[54:57]
	v_mfma_f32_16x16x32_bf16 v[50:53], v[168:171], v[176:179], v[50:53]
	v_mfma_f32_16x16x32_bf16 v[38:41], v[160:163], v[184:187], v[38:41]
	v_mfma_f32_16x16x32_bf16 v[34:37], v[168:171], v[184:187], v[34:37]
	v_mfma_f32_16x16x32_bf16 v[22:25], v[160:163], v[196:199], v[22:25]
	v_mfma_f32_16x16x32_bf16 v[18:21], v[168:171], v[196:199], v[18:21]
	v_mfma_f32_16x16x32_bf16 v[6:9], v[160:163], v[204:207], v[6:9]
	v_mfma_f32_16x16x32_bf16 v[2:5], v[168:171], v[204:207], v[2:5]
	v_mfma_f32_16x16x32_bf16 v[54:57], v[164:167], v[180:183], v[54:57]
	v_mfma_f32_16x16x32_bf16 v[50:53], v[172:175], v[180:183], v[50:53]
	v_mfma_f32_16x16x32_bf16 v[38:41], v[164:167], v[188:191], v[38:41]
	v_mfma_f32_16x16x32_bf16 v[34:37], v[172:175], v[188:191], v[34:37]
	v_mfma_f32_16x16x32_bf16 v[22:25], v[164:167], v[200:203], v[22:25]
	v_mfma_f32_16x16x32_bf16 v[18:21], v[172:175], v[200:203], v[18:21]
	v_mfma_f32_16x16x32_bf16 v[6:9], v[164:167], v[208:211], v[6:9]
	v_mfma_f32_16x16x32_bf16 v[2:5], v[172:175], v[208:211], v[2:5]
	s_setprio 0
	s_barrier
	s_add_i32 s27, s27, 2
	s_add_u32 s36, s36, 0x100
	s_addc_u32 s37, s37, 0
	s_add_u32 s15, s15, 0x100
	s_addc_u32 s25, s25, 0
	s_cmp_gt_u32 s27, 13
	s_cbranch_scc0 .LBB0_205
	s_and_b64 vcc, exec, s[22:23]
	s_cbranch_vccz .LBB0_208
	s_barrier

; #define PG8_STAGE(bufoff, gbase, voff) do { _Pragma("unroll") for (int _i = 0; _i < 2; ++_i) \
;         __builtin_amdgcn_global_load_lds((const unsigned*)((const char*)(gbase) + (voff)[_i]), (LAS unsigned*)(lds + (bufoff) + ldsw + _i * 8192), 16, 0, 0); } while (0)
; #define PG8_LDA(dst, b, h) do { _Pragma("unroll") for (int m = 0; m < 4; ++m) _Pragma("unroll") for (int k = 0; k < 2; ++k) dst[m][k] = *(const LAS bf16x8*)(lds + PG8_SA(b, h) + aoff + m * 2048 + k * 1024); } while (0)
; #define PG8_LDB(dst, b, h) do { _Pragma("unroll") for (int n = 0; n < 2; ++n) _Pragma("unroll") for (int k = 0; k < 2; ++k) dst[n][k] = *(const LAS bf16x8*)(lds + PG8_SB(b, h) + boff + n * 2048 + k * 1024); } while (0)
; #define PG8_WAIT_V(n) asm volatile("s_waitcnt vmcnt(" #n ")" ::: "memory")
; template <class Epi, class Sched, bool ALIGN_EPI = true, bool SP2 = true>
; __device__ __forceinline__ void gemm_phase(LAS unsigned char* lds, const Gemm g, const Sched& S, const Epi& E) {
;     ...
;         for (int t = 0; t < nt; t += 2) {
;             const bool last = (t == nt - 2);
;             const char* a1 = cA + (size_t)(t + 1) * kstep;
;             const char* a2 = last ? nA : cA + (size_t)(t + 2) * kstep; const char* b2 = last ? nB : cB + (size_t)(t + 2) * kstep;
;             const char* a3 = a2 + kstep; const char* b3 = b2 + kstep;
;             PG8_LDB(B0, 0, 0); PG8_LDB(B1, 0, 1); PG8_SCHED; PG8_LDA(At, 0, 0); PG8_STAGE(PG8_SA(1, 1), a1 + hstepA, voffA);
;             PG8_WAIT_V(8); PG8_WAIT_L(0); PG8_BAR; PG8_MMA(0, 0, At, B0); PG8_MMA(0, 1, At, B1); PG8_BAR; PG8_SCHED;
;             PG8_LDA(At, 0, 1); PG8_STAGE(PG8_SB(0, 0), b2, voffB); PG8_STAGE(PG8_SB(0, 1), b2 + hstepB, voffB); PG8_STAGE(PG8_SA(0, 0), a2, voffA);
;             PG8_WAIT_V(8); PG8_WAIT_L(0); PG8_BAR; PG8_MMA(1, 0, At, B0); PG8_MMA(1, 1, At, B1); PG8_BAR; PG8_SCHED;
;             PG8_LDB(B0, 1, 0); PG8_LDB(B1, 1, 1); PG8_SCHED; PG8_LDA(At, 1, 0); PG8_STAGE(PG8_SA(0, 1), a2 + hstepA, voffA);
;             PG8_WAIT_V(8); PG8_WAIT_L(0); PG8_BAR; PG8_MMA(0, 0, At, B0); PG8_MMA(0, 1, At, B1); PG8_BAR; PG8_SCHED;
;             PG8_LDA(At, 1, 1); PG8_STAGE(PG8_SB(1, 0), b3, voffB); PG8_STAGE(PG8_SB(1, 1), b3 + hstepB, voffB); PG8_STAGE(PG8_SA(1, 0), a3, voffA);
;             PG8_WAIT_V(8); PG8_WAIT_L(0); PG8_BAR; PG8_MMA(1, 0, At, B0); PG8_MMA(1, 1, At, B1); PG8_BAR; PG8_SCHED;
.LBB0_458:
	s_add_u32 s18, s50, 0xfffc0080
	s_addc_u32 s19, s51, -1
	s_add_i32 s58, 0, 0x10000
	s_cmp_eq_u32 s60, 12
	s_cselect_b32 s21, s22, s19
	s_cselect_b32 s20, s23, s18
	v_add_u32_e32 v146, s58, v144
	s_cselect_b32 s19, s2, s45
	s_cselect_b32 s18, s43, s30
	s_add_i32 s61, 0, 0x14000
	ds_read_b128 v[140:143], v146
	ds_read_b128 v[164:167], v146 offset:1024
	ds_read_b128 v[168:171], v146 offset:2048
	ds_read_b128 v[172:175], v146 offset:3072
	v_add_u32_e32 v146, s61, v144
	ds_read_b128 v[198:201], v146
	ds_read_b128 v[202:205], v146 offset:1024
	ds_read_b128 v[206:209], v146 offset:2048
	ds_read_b128 v[210:213], v146 offset:3072
	v_lshl_add_u64 v[146:147], s[50:51], 0, v[136:137]
	s_add_i32 m0, s53, 0xc000
	ds_read_b128 v[218:221], v145
	ds_read_b128 v[222:225], v145 offset:1024
	ds_read_b128 v[226:229], v145 offset:2048
	ds_read_b128 v[230:233], v145 offset:3072
	ds_read_b128 v[234:237], v145 offset:4096
	ds_read_b128 v[238:241], v145 offset:5120
	ds_read_b128 v[242:245], v145 offset:6144
	ds_read_b128 v[246:249], v145 offset:7168
	global_load_lds_dwordx4 v[146:147], off
	v_lshl_add_u64 v[146:147], s[50:51], 0, v[138:139]
	s_add_i32 m0, s53, 0xe000
	s_nop 0
	global_load_lds_dwordx4 v[146:147], off
	s_waitcnt vmcnt(8)
	s_waitcnt lgkmcnt(0)
	s_barrier
	s_setprio 1
	v_mfma_f32_16x16x32_bf16 v[128:131], v[140:143], v[218:221], v[128:131]
	v_mfma_f32_16x16x32_bf16 v[124:127], v[168:171], v[218:221], v[124:127]
	v_mfma_f32_16x16x32_bf16 v[120:123], v[140:143], v[226:229], v[120:123]
	v_mfma_f32_16x16x32_bf16 v[112:115], v[168:171], v[226:229], v[112:115]
	v_mfma_f32_16x16x32_bf16 v[104:107], v[140:143], v[234:237], v[104:107]
	v_mfma_f32_16x16x32_bf16 v[96:99], v[168:171], v[234:237], v[96:99]
	v_mfma_f32_16x16x32_bf16 v[88:91], v[140:143], v[242:245], v[88:91]
	v_mfma_f32_16x16x32_bf16 v[80:83], v[168:171], v[242:245], v[80:83]
	v_mfma_f32_16x16x32_bf16 v[128:131], v[164:167], v[222:225], v[128:131]
	v_mfma_f32_16x16x32_bf16 v[124:127], v[172:175], v[222:225], v[124:127]
	v_mfma_f32_16x16x32_bf16 v[120:123], v[164:167], v[230:233], v[120:123]
	v_mfma_f32_16x16x32_bf16 v[112:115], v[172:175], v[230:233], v[112:115]
	v_mfma_f32_16x16x32_bf16 v[104:107], v[164:167], v[238:241], v[104:107]
	v_mfma_f32_16x16x32_bf16 v[96:99], v[172:175], v[238:241], v[96:99]
	v_mfma_f32_16x16x32_bf16 v[88:91], v[164:167], v[246:249], v[88:91]
	v_mfma_f32_16x16x32_bf16 v[80:83], v[172:175], v[246:249], v[80:83]
	s_setprio 0
	s_setprio 1
	v_mfma_f32_16x16x32_bf16 v[116:119], v[198:201], v[218:221], v[116:119]
	v_mfma_f32_16x16x32_bf16 v[108:111], v[206:209], v[218:221], v[108:111]
	v_mfma_f32_16x16x32_bf16 v[100:103], v[198:201], v[226:229], v[100:103]
	v_mfma_f32_16x16x32_bf16 v[92:95], v[206:209], v[226:229], v[92:95]
	v_mfma_f32_16x16x32_bf16 v[84:87], v[198:201], v[234:237], v[84:87]
	v_mfma_f32_16x16x32_bf16 v[76:79], v[206:209], v[234:237], v[76:79]
	v_mfma_f32_16x16x32_bf16 v[72:75], v[198:201], v[242:245], v[72:75]
	v_mfma_f32_16x16x32_bf16 v[68:71], v[206:209], v[242:245], v[68:71]
	v_mfma_f32_16x16x32_bf16 v[116:119], v[202:205], v[222:225], v[116:119]
	v_mfma_f32_16x16x32_bf16 v[108:111], v[210:213], v[222:225], v[108:111]
	v_mfma_f32_16x16x32_bf16 v[100:103], v[202:205], v[230:233], v[100:103]
	v_mfma_f32_16x16x32_bf16 v[92:95], v[210:213], v[230:233], v[92:95]
	v_mfma_f32_16x16x32_bf16 v[84:87], v[202:205], v[238:241], v[84:87]
	v_mfma_f32_16x16x32_bf16 v[76:79], v[210:213], v[238:241], v[76:79]
	v_mfma_f32_16x16x32_bf16 v[72:75], v[202:205], v[246:249], v[72:75]
	v_mfma_f32_16x16x32_bf16 v[68:71], v[210:213], v[246:249], v[68:71]
	s_setprio 0
	s_barrier
	s_add_i32 s58, s58, s39
	v_lshl_add_u64 v[146:147], s[18:19], 0, v[18:19]
	s_mov_b32 m0, s58
	ds_read_b128 v[218:221], v145 offset:16384
	ds_read_b128 v[222:225], v145 offset:17408
	ds_read_b128 v[226:229], v145 offset:18432
	ds_read_b128 v[230:233], v145 offset:19456
	ds_read_b128 v[234:237], v145 offset:20480
	ds_read_b128 v[238:241], v145 offset:21504
	ds_read_b128 v[242:245], v145 offset:22528
	ds_read_b128 v[246:249], v145 offset:23552
	global_load_lds_dwordx4 v[146:147], off
	s_add_i32 m0, s58, 0x2000
	s_add_u32 s58, s18, 0x40000
	v_lshl_add_u64 v[148:149], s[18:19], 0, v[16:17]
	s_addc_u32 s59, s19, 0
	s_add_i32 s61, s61, s39
	global_load_lds_dwordx4 v[148:149], off
	v_lshl_add_u64 v[150:151], s[58:59], 0, v[18:19]
	s_mov_b32 m0, s61
	v_lshl_add_u64 v[152:153], s[20:21], 0, v[132:133]
	global_load_lds_dwordx4 v[150:151], off
	v_lshl_add_u64 v[150:151], s[58:59], 0, v[16:17]
	s_add_i32 m0, s61, 0x2000
	s_nop 0
	global_load_lds_dwordx4 v[150:151], off
	v_lshl_add_u64 v[150:151], s[20:21], 0, v[134:135]
	s_mov_b32 m0, s53
	s_nop 0
	global_load_lds_dwordx4 v[150:151], off
	s_mov_b32 m0, s0
	s_nop 0
	global_load_lds_dwordx4 v[152:153], off
	s_waitcnt vmcnt(8)
	s_waitcnt lgkmcnt(0)
	s_barrier
; #define PG8_STAGE(bufoff, gbase, voff) do { _Pragma("unroll") for (int _i = 0; _i < 2; ++_i) \
;         __builtin_amdgcn_global_load_lds((const unsigned*)((const char*)(gbase) + (voff)[_i]), (LAS unsigned*)(lds + (bufoff) + ldsw + _i * 8192), 16, 0, 0); } while (0)
; #define PG8_LDA(dst, b, h) do { _Pragma("unroll") for (int m = 0; m < 4; ++m) _Pragma("unroll") for (int k = 0; k < 2; ++k) dst[m][k] = *(const LAS bf16x8*)(lds + PG8_SA(b, h) + aoff + m * 2048 + k * 1024); } while (0)
; #define PG8_LDB(dst, b, h) do { _Pragma("unroll") for (int n = 0; n < 2; ++n) _Pragma("unroll") for (int k = 0; k < 2; ++k) dst[n][k] = *(const LAS bf16x8*)(lds + PG8_SB(b, h) + boff + n * 2048 + k * 1024); } while (0)
; #define PG8_MMA(ai, bj, At, Bt) do { __builtin_amdgcn_s_setprio(1); _Pragma("unroll") for (int m = 0; m < 4; ++m) _Pragma("unroll") for (int n = 0; n < 2; ++n) _Pragma("unroll") for (int k = 0; k < 2; ++k) \
;         acc[ai][bj][m][n] = __builtin_amdgcn_mfma_f32_16x16x32_bf16(Bt[n][k], At[m][k], acc[ai][bj][m][n], 0, 0, 0); __builtin_amdgcn_s_setprio(0); } while (0)
; #define PG8_WAIT_V(n) asm volatile("s_waitcnt vmcnt(" #n ")" ::: "memory")
; template <class Epi, class Sched, bool ALIGN_EPI = true, bool SP2 = true>
; __device__ __forceinline__ void gemm_phase(LAS unsigned char* lds, const Gemm g, const Sched& S, const Epi& E) {
;     ...
;             PG8_LDB(B0, 0, 0); PG8_LDB(B1, 0, 1); PG8_SCHED; PG8_LDA(At, 0, 0); PG8_STAGE(PG8_SA(1, 1), a1 + hstepA, voffA);
;             PG8_WAIT_V(8); PG8_WAIT_L(0); PG8_BAR; PG8_MMA(0, 0, At, B0); PG8_MMA(0, 1, At, B1); PG8_BAR; PG8_SCHED;
;             PG8_LDA(At, 0, 1); PG8_STAGE(PG8_SB(0, 0), b2, voffB); PG8_STAGE(PG8_SB(0, 1), b2 + hstepB, voffB); PG8_STAGE(PG8_SA(0, 0), a2, voffA);
;             PG8_WAIT_V(8); PG8_WAIT_L(0); PG8_BAR; PG8_MMA(1, 0, At, B0); PG8_MMA(1, 1, At, B1); PG8_BAR; PG8_SCHED;
;             PG8_LDB(B0, 1, 0); PG8_LDB(B1, 1, 1); PG8_SCHED; PG8_LDA(At, 1, 0); PG8_STAGE(PG8_SA(0, 1), a2 + hstepA, voffA);
;             PG8_WAIT_V(8); PG8_WAIT_L(0); PG8_BAR; PG8_MMA(0, 0, At, B0); PG8_MMA(0, 1, At, B1); PG8_BAR; PG8_SCHED;
;             PG8_LDA(At, 1, 1); PG8_STAGE(PG8_SB(1, 0), b3, voffB); PG8_STAGE(PG8_SB(1, 1), b3 + hstepB, voffB); PG8_STAGE(PG8_SA(1, 0), a3, voffA);
;             PG8_WAIT_V(8); PG8_WAIT_L(0); PG8_BAR; PG8_MMA(1, 0, At, B0); PG8_MMA(1, 1, At, B1); PG8_BAR; PG8_SCHED;
	s_setprio 1
	v_mfma_f32_16x16x32_bf16 v[64:67], v[140:143], v[218:221], v[64:67]
	v_mfma_f32_16x16x32_bf16 v[60:63], v[168:171], v[218:221], v[60:63]
	v_mfma_f32_16x16x32_bf16 v[56:59], v[140:143], v[226:229], v[56:59]
	v_mfma_f32_16x16x32_bf16 v[48:51], v[168:171], v[226:229], v[48:51]
	v_mfma_f32_16x16x32_bf16 v[40:43], v[140:143], v[234:237], v[40:43]
	v_mfma_f32_16x16x32_bf16 v[32:35], v[168:171], v[234:237], v[32:35]
	v_mfma_f32_16x16x32_bf16 v[24:27], v[140:143], v[242:245], v[24:27]
	v_mfma_f32_16x16x32_bf16 v[12:15], v[168:171], v[242:245], v[12:15]
	v_mfma_f32_16x16x32_bf16 v[64:67], v[164:167], v[222:225], v[64:67]
	v_mfma_f32_16x16x32_bf16 v[60:63], v[172:175], v[222:225], v[60:63]
	v_mfma_f32_16x16x32_bf16 v[56:59], v[164:167], v[230:233], v[56:59]
	v_mfma_f32_16x16x32_bf16 v[48:51], v[172:175], v[230:233], v[48:51]
	v_mfma_f32_16x16x32_bf16 v[40:43], v[164:167], v[238:241], v[40:43]
	v_mfma_f32_16x16x32_bf16 v[32:35], v[172:175], v[238:241], v[32:35]
	v_mfma_f32_16x16x32_bf16 v[24:27], v[164:167], v[246:249], v[24:27]
	v_mfma_f32_16x16x32_bf16 v[12:15], v[172:175], v[246:249], v[12:15]
	s_setprio 0
	s_setprio 1
	v_mfma_f32_16x16x32_bf16 v[52:55], v[198:201], v[218:221], v[52:55]
	v_mfma_f32_16x16x32_bf16 v[44:47], v[206:209], v[218:221], v[44:47]
	v_mfma_f32_16x16x32_bf16 v[36:39], v[198:201], v[226:229], v[36:39]
	v_mfma_f32_16x16x32_bf16 v[28:31], v[206:209], v[226:229], v[28:31]
	v_mfma_f32_16x16x32_bf16 v[20:23], v[198:201], v[234:237], v[20:23]
	v_mfma_f32_16x16x32_bf16 v[8:11], v[206:209], v[234:237], v[8:11]
	v_mfma_f32_16x16x32_bf16 v[4:7], v[198:201], v[242:245], v[4:7]
	v_mfma_f32_16x16x32_bf16 v[0:3], v[206:209], v[242:245], v[0:3]
	v_mfma_f32_16x16x32_bf16 v[52:55], v[202:205], v[222:225], v[52:55]
	v_mfma_f32_16x16x32_bf16 v[44:47], v[210:213], v[222:225], v[44:47]
	v_mfma_f32_16x16x32_bf16 v[36:39], v[202:205], v[230:233], v[36:39]
	v_mfma_f32_16x16x32_bf16 v[28:31], v[210:213], v[230:233], v[28:31]
	v_mfma_f32_16x16x32_bf16 v[20:23], v[202:205], v[238:241], v[20:23]
	v_mfma_f32_16x16x32_bf16 v[8:11], v[210:213], v[238:241], v[8:11]
	v_mfma_f32_16x16x32_bf16 v[4:7], v[202:205], v[246:249], v[4:7]
	v_mfma_f32_16x16x32_bf16 v[0:3], v[210:213], v[246:249], v[0:3]
	s_setprio 0
	s_barrier
	s_add_i32 s58, 0, 0x18000
	v_add_u32_e32 v154, s58, v144
	s_add_i32 s59, 0, 0x1c000
	ds_read_b128 v[140:143], v154
	ds_read_b128 v[164:167], v154 offset:1024
	ds_read_b128 v[168:171], v154 offset:2048
	ds_read_b128 v[172:175], v154 offset:3072
	v_add_u32_e32 v154, s59, v144
	ds_read_b128 v[198:201], v154
	ds_read_b128 v[202:205], v154 offset:1024
	ds_read_b128 v[206:209], v154 offset:2048
	ds_read_b128 v[210:213], v154 offset:3072
	s_add_u32 s20, s20, 0x40000
	s_addc_u32 s21, s21, 0
	s_mov_b32 m0, s1
	v_lshl_add_u64 v[154:155], s[20:21], 0, v[134:135]
	ds_read_b128 v[218:221], v145 offset:32768
	ds_read_b128 v[222:225], v145 offset:33792
	ds_read_b128 v[226:229], v145 offset:34816
	ds_read_b128 v[230:233], v145 offset:35840
	ds_read_b128 v[234:237], v145 offset:36864
	ds_read_b128 v[238:241], v145 offset:37888
	ds_read_b128 v[242:245], v145 offset:38912
	ds_read_b128 v[246:249], v145 offset:39936
	global_load_lds_dwordx4 v[154:155], off
	v_lshl_add_u64 v[154:155], s[20:21], 0, v[132:133]
	s_mov_b32 m0, s8
	s_nop 0
	global_load_lds_dwordx4 v[154:155], off
	s_waitcnt vmcnt(8)
	s_waitcnt lgkmcnt(0)
	s_barrier
	s_setprio 1
	v_mfma_f32_16x16x32_bf16 v[128:131], v[140:143], v[218:221], v[128:131]
	v_mfma_f32_16x16x32_bf16 v[124:127], v[168:171], v[218:221], v[124:127]
	v_mfma_f32_16x16x32_bf16 v[120:123], v[140:143], v[226:229], v[120:123]
	v_mfma_f32_16x16x32_bf16 v[112:115], v[168:171], v[226:229], v[112:115]
	v_mfma_f32_16x16x32_bf16 v[104:107], v[140:143], v[234:237], v[104:107]
	v_mfma_f32_16x16x32_bf16 v[96:99], v[168:171], v[234:237], v[96:99]
	v_mfma_f32_16x16x32_bf16 v[88:91], v[140:143], v[242:245], v[88:91]
	v_mfma_f32_16x16x32_bf16 v[80:83], v[168:171], v[242:245], v[80:83]
	v_mfma_f32_16x16x32_bf16 v[128:131], v[164:167], v[222:225], v[128:131]
	v_mfma_f32_16x16x32_bf16 v[124:127], v[172:175], v[222:225], v[124:127]
	v_mfma_f32_16x16x32_bf16 v[120:123], v[164:167], v[230:233], v[120:123]
	v_mfma_f32_16x16x32_bf16 v[112:115], v[172:175], v[230:233], v[112:115]
	v_mfma_f32_16x16x32_bf16 v[104:107], v[164:167], v[238:241], v[104:107]
	v_mfma_f32_16x16x32_bf16 v[96:99], v[172:175], v[238:241], v[96:99]
	v_mfma_f32_16x16x32_bf16 v[88:91], v[164:167], v[246:249], v[88:91]
	v_mfma_f32_16x16x32_bf16 v[80:83], v[172:175], v[246:249], v[80:83]
	s_setprio 0
	s_setprio 1
	v_mfma_f32_16x16x32_bf16 v[116:119], v[198:201], v[218:221], v[116:119]
	v_mfma_f32_16x16x32_bf16 v[108:111], v[206:209], v[218:221], v[108:111]
	v_mfma_f32_16x16x32_bf16 v[100:103], v[198:201], v[226:229], v[100:103]
	v_mfma_f32_16x16x32_bf16 v[92:95], v[206:209], v[226:229], v[92:95]
	v_mfma_f32_16x16x32_bf16 v[84:87], v[198:201], v[234:237], v[84:87]
	v_mfma_f32_16x16x32_bf16 v[76:79], v[206:209], v[234:237], v[76:79]
	v_mfma_f32_16x16x32_bf16 v[72:75], v[198:201], v[242:245], v[72:75]
	v_mfma_f32_16x16x32_bf16 v[68:71], v[206:209], v[242:245], v[68:71]
	v_mfma_f32_16x16x32_bf16 v[116:119], v[202:205], v[222:225], v[116:119]
	v_mfma_f32_16x16x32_bf16 v[108:111], v[210:213], v[222:225], v[108:111]
	v_mfma_f32_16x16x32_bf16 v[100:103], v[202:205], v[230:233], v[100:103]
	v_mfma_f32_16x16x32_bf16 v[92:95], v[210:213], v[230:233], v[92:95]
	v_mfma_f32_16x16x32_bf16 v[84:87], v[202:205], v[238:241], v[84:87]
	v_mfma_f32_16x16x32_bf16 v[76:79], v[210:213], v[238:241], v[76:79]
	v_mfma_f32_16x16x32_bf16 v[72:75], v[202:205], v[246:249], v[72:75]
	v_mfma_f32_16x16x32_bf16 v[68:71], v[210:213], v[246:249], v[68:71]
	s_setprio 0
	s_barrier
; #define PG8_STAGE(bufoff, gbase, voff) do { _Pragma("unroll") for (int _i = 0; _i < 2; ++_i) \
;         __builtin_amdgcn_global_load_lds((const unsigned*)((const char*)(gbase) + (voff)[_i]), (LAS unsigned*)(lds + (bufoff) + ldsw + _i * 8192), 16, 0, 0); } while (0)
; #define PG8_LDA(dst, b, h) do { _Pragma("unroll") for (int m = 0; m < 4; ++m) _Pragma("unroll") for (int k = 0; k < 2; ++k) dst[m][k] = *(const LAS bf16x8*)(lds + PG8_SA(b, h) + aoff + m * 2048 + k * 1024); } while (0)
; #define PG8_LDB(dst, b, h) do { _Pragma("unroll") for (int n = 0; n < 2; ++n) _Pragma("unroll") for (int k = 0; k < 2; ++k) dst[n][k] = *(const LAS bf16x8*)(lds + PG8_SB(b, h) + boff + n * 2048 + k * 1024); } while (0)
; #define PG8_MMA(ai, bj, At, Bt) do { __builtin_amdgcn_s_setprio(1); _Pragma("unroll") for (int m = 0; m < 4; ++m) _Pragma("unroll") for (int n = 0; n < 2; ++n) _Pragma("unroll") for (int k = 0; k < 2; ++k) \
;         acc[ai][bj][m][n] = __builtin_amdgcn_mfma_f32_16x16x32_bf16(Bt[n][k], At[m][k], acc[ai][bj][m][n], 0, 0, 0); __builtin_amdgcn_s_setprio(0); } while (0)
; template <class Epi, class Sched, bool ALIGN_EPI = true, bool SP2 = true>
; __device__ __forceinline__ void gemm_phase(LAS unsigned char* lds, const Gemm g, const Sched& S, const Epi& E) {
;     ...
;             PG8_LDB(B0, 0, 0); PG8_LDB(B1, 0, 1); PG8_SCHED; PG8_LDA(At, 0, 0); PG8_STAGE(PG8_SA(1, 1), a1 + hstepA, voffA);
;             PG8_WAIT_V(8); PG8_WAIT_L(0); PG8_BAR; PG8_MMA(0, 0, At, B0); PG8_MMA(0, 1, At, B1); PG8_BAR; PG8_SCHED;
;             PG8_LDA(At, 0, 1); PG8_STAGE(PG8_SB(0, 0), b2, voffB); PG8_STAGE(PG8_SB(0, 1), b2 + hstepB, voffB); PG8_STAGE(PG8_SA(0, 0), a2, voffA);
;             PG8_WAIT_V(8); PG8_WAIT_L(0); PG8_BAR; PG8_MMA(1, 0, At, B0); PG8_MMA(1, 1, At, B1); PG8_BAR; PG8_SCHED;
;             PG8_LDB(B0, 1, 0); PG8_LDB(B1, 1, 1); PG8_SCHED; PG8_LDA(At, 1, 0); PG8_STAGE(PG8_SA(0, 1), a2 + hstepA, voffA);
;             PG8_WAIT_V(8); PG8_WAIT_L(0); PG8_BAR; PG8_MMA(0, 0, At, B0); PG8_MMA(0, 1, At, B1); PG8_BAR; PG8_SCHED;
;             PG8_LDA(At, 1, 1); PG8_STAGE(PG8_SB(1, 0), b3, voffB); PG8_STAGE(PG8_SB(1, 1), b3 + hstepB, voffB); PG8_STAGE(PG8_SA(1, 0), a3, voffA);
;             PG8_WAIT_V(8); PG8_WAIT_L(0); PG8_BAR; PG8_MMA(1, 0, At, B0); PG8_MMA(1, 1, At, B1); PG8_BAR; PG8_SCHED;
;         }
;         if constexpr (ALIGN_EPI) { if (wr == 0) PG8_BAR; }
	s_add_i32 s20, s58, s39
	v_lshl_add_u64 v[146:147], v[146:147], 0, s[14:15]
	s_mov_b32 m0, s20
	ds_read_b128 v[218:221], v145 offset:49152
	ds_read_b128 v[222:225], v145 offset:50176
	ds_read_b128 v[226:229], v145 offset:51200
	ds_read_b128 v[230:233], v145 offset:52224
	ds_read_b128 v[234:237], v145 offset:53248
	ds_read_b128 v[238:241], v145 offset:54272
	ds_read_b128 v[242:245], v145 offset:55296
	ds_read_b128 v[246:249], v145 offset:56320
	global_load_lds_dwordx4 v[146:147], off
	s_add_i32 m0, s20, 0x2000
	s_add_u32 s18, s18, 0x40080
	v_lshl_add_u64 v[146:147], v[148:149], 0, s[14:15]
	s_addc_u32 s19, s19, 0
	s_add_i32 s20, s59, s39
	global_load_lds_dwordx4 v[146:147], off
	v_lshl_add_u64 v[146:147], s[18:19], 0, v[18:19]
	s_mov_b32 m0, s20
	s_nop 0
	global_load_lds_dwordx4 v[146:147], off
	v_lshl_add_u64 v[146:147], s[18:19], 0, v[16:17]
	s_add_i32 m0, s20, 0x2000
	s_nop 0
	global_load_lds_dwordx4 v[146:147], off
	v_lshl_add_u64 v[146:147], v[150:151], 0, s[14:15]
	s_mov_b32 m0, s54
	s_nop 0
	global_load_lds_dwordx4 v[146:147], off
	v_lshl_add_u64 v[146:147], v[152:153], 0, s[14:15]
	s_mov_b32 m0, s55
	s_nop 0
	global_load_lds_dwordx4 v[146:147], off
	s_waitcnt vmcnt(8)
	s_waitcnt lgkmcnt(0)
	s_barrier
	s_setprio 1
	v_mfma_f32_16x16x32_bf16 v[64:67], v[140:143], v[218:221], v[64:67]
	v_mfma_f32_16x16x32_bf16 v[60:63], v[168:171], v[218:221], v[60:63]
	v_mfma_f32_16x16x32_bf16 v[56:59], v[140:143], v[226:229], v[56:59]
	v_mfma_f32_16x16x32_bf16 v[48:51], v[168:171], v[226:229], v[48:51]
	v_mfma_f32_16x16x32_bf16 v[40:43], v[140:143], v[234:237], v[40:43]
	v_mfma_f32_16x16x32_bf16 v[32:35], v[168:171], v[234:237], v[32:35]
	v_mfma_f32_16x16x32_bf16 v[24:27], v[140:143], v[242:245], v[24:27]
	v_mfma_f32_16x16x32_bf16 v[12:15], v[168:171], v[242:245], v[12:15]
	v_mfma_f32_16x16x32_bf16 v[64:67], v[164:167], v[222:225], v[64:67]
	v_mfma_f32_16x16x32_bf16 v[60:63], v[172:175], v[222:225], v[60:63]
	v_mfma_f32_16x16x32_bf16 v[56:59], v[164:167], v[230:233], v[56:59]
	v_mfma_f32_16x16x32_bf16 v[48:51], v[172:175], v[230:233], v[48:51]
	v_mfma_f32_16x16x32_bf16 v[40:43], v[164:167], v[238:241], v[40:43]
	v_mfma_f32_16x16x32_bf16 v[32:35], v[172:175], v[238:241], v[32:35]
	v_mfma_f32_16x16x32_bf16 v[24:27], v[164:167], v[246:249], v[24:27]
	v_mfma_f32_16x16x32_bf16 v[12:15], v[172:175], v[246:249], v[12:15]
	s_setprio 0
	s_setprio 1
	v_mfma_f32_16x16x32_bf16 v[52:55], v[198:201], v[218:221], v[52:55]
	v_mfma_f32_16x16x32_bf16 v[44:47], v[206:209], v[218:221], v[44:47]
	v_mfma_f32_16x16x32_bf16 v[36:39], v[198:201], v[226:229], v[36:39]
	v_mfma_f32_16x16x32_bf16 v[28:31], v[206:209], v[226:229], v[28:31]
	v_mfma_f32_16x16x32_bf16 v[20:23], v[198:201], v[234:237], v[20:23]
	v_mfma_f32_16x16x32_bf16 v[8:11], v[206:209], v[234:237], v[8:11]
	v_mfma_f32_16x16x32_bf16 v[4:7], v[198:201], v[242:245], v[4:7]
	v_mfma_f32_16x16x32_bf16 v[0:3], v[206:209], v[242:245], v[0:3]
	v_mfma_f32_16x16x32_bf16 v[52:55], v[202:205], v[222:225], v[52:55]
	v_mfma_f32_16x16x32_bf16 v[44:47], v[210:213], v[222:225], v[44:47]
	v_mfma_f32_16x16x32_bf16 v[36:39], v[202:205], v[230:233], v[36:39]
	v_mfma_f32_16x16x32_bf16 v[28:31], v[210:213], v[230:233], v[28:31]
	v_mfma_f32_16x16x32_bf16 v[20:23], v[202:205], v[238:241], v[20:23]
	v_mfma_f32_16x16x32_bf16 v[8:11], v[210:213], v[238:241], v[8:11]
	v_mfma_f32_16x16x32_bf16 v[4:7], v[202:205], v[246:249], v[4:7]
	v_mfma_f32_16x16x32_bf16 v[0:3], v[210:213], v[246:249], v[0:3]
	s_setprio 0
	s_barrier
	s_add_i32 s60, s60, 2
	s_add_u32 s50, s50, 0x100
	s_addc_u32 s51, s51, 0
	s_add_u32 s30, s30, 0x100
	s_addc_u32 s45, s45, 0
	s_cmp_gt_u32 s60, 13
	s_cbranch_scc0 .LBB0_458
	s_and_b64 vcc, exec, s[36:37]
	s_cbranch_vccz .LBB0_461
	s_barrier

; #define PG8_STAGE(bufoff, gbase, voff) do { _Pragma("unroll") for (int _i = 0; _i < 2; ++_i) \
;         __builtin_amdgcn_global_load_lds((const unsigned*)((const char*)(gbase) + (voff)[_i]), (LAS unsigned*)(lds + (bufoff) + ldsw + _i * 8192), 16, 0, 0); } while (0)
; #define PG8_LDA(dst, b, h) do { _Pragma("unroll") for (int m = 0; m < 4; ++m) _Pragma("unroll") for (int k = 0; k < 2; ++k) dst[m][k] = *(const LAS bf16x8*)(lds + PG8_SA(b, h) + aoff + m * 2048 + k * 1024); } while (0)
; #define PG8_LDB(dst, b, h) do { _Pragma("unroll") for (int n = 0; n < 2; ++n) _Pragma("unroll") for (int k = 0; k < 2; ++k) dst[n][k] = *(const LAS bf16x8*)(lds + PG8_SB(b, h) + boff + n * 2048 + k * 1024); } while (0)
; #define PG8_MMA(ai, bj, At, Bt) do { __builtin_amdgcn_s_setprio(1); _Pragma("unroll") for (int m = 0; m < 4; ++m) _Pragma("unroll") for (int n = 0; n < 2; ++n) _Pragma("unroll") for (int k = 0; k < 2; ++k) \
;         acc[ai][bj][m][n] = __builtin_amdgcn_mfma_f32_16x16x32_bf16(Bt[n][k], At[m][k], acc[ai][bj][m][n], 0, 0, 0); __builtin_amdgcn_s_setprio(0); } while (0)
; #define PG8_WAIT_V(n) asm volatile("s_waitcnt vmcnt(" #n ")" ::: "memory")
; #define PG8_WAIT_L(n) asm volatile("s_waitcnt lgkmcnt(" #n ")" ::: "memory")
; #define PG8_BAR __builtin_amdgcn_s_barrier()
; #define PG8_SCHED __builtin_amdgcn_sched_barrier(0)
; template <class Epi, class Sched, bool ALIGN_EPI = true, bool SP2 = true>
; __device__ __forceinline__ void gemm_phase(LAS unsigned char* lds, const Gemm g, const Sched& S, const Epi& E) {
;     ...
;             const bool last = (t == nt - 2);
;             const char* a1 = cA + (size_t)(t + 1) * kstep;
;             const char* a2 = last ? nA : cA + (size_t)(t + 2) * kstep; const char* b2 = last ? nB : cB + (size_t)(t + 2) * kstep;
;             const char* a3 = a2 + kstep; const char* b3 = b2 + kstep;
;             PG8_LDB(B0, 0, 0); PG8_LDB(B1, 0, 1); PG8_SCHED; PG8_LDA(At, 0, 0); PG8_STAGE(PG8_SA(1, 1), a1 + hstepA, voffA);
;             PG8_WAIT_V(8); PG8_WAIT_L(0); PG8_BAR; PG8_MMA(0, 0, At, B0); PG8_MMA(0, 1, At, B1); PG8_BAR; PG8_SCHED;
;             PG8_LDA(At, 0, 1); PG8_STAGE(PG8_SB(0, 0), b2, voffB); PG8_STAGE(PG8_SB(0, 1), b2 + hstepB, voffB); PG8_STAGE(PG8_SA(0, 0), a2, voffA);
;             PG8_WAIT_V(8); PG8_WAIT_L(0); PG8_BAR; PG8_MMA(1, 0, At, B0); PG8_MMA(1, 1, At, B1); PG8_BAR; PG8_SCHED;
.LBB0_627:
	s_add_i32 s42, 0, 0x10000
	s_add_i32 s30, 0, 0x14000
	v_add_u32_e32 v8, s42, v166
	v_add_u32_e32 v9, s30, v166
	ds_read_b128 v[10:13], v8
	ds_read_b128 v[20:23], v8 offset:1024
	ds_read_b128 v[24:27], v8 offset:2048
	ds_read_b128 v[28:31], v8 offset:3072
	ds_read_b128 v[32:35], v9
	ds_read_b128 v[36:39], v9 offset:1024
	ds_read_b128 v[40:43], v9 offset:2048
	ds_read_b128 v[44:47], v9 offset:3072
	s_add_u32 s8, s16, 0x30080
	s_addc_u32 s9, s17, 0
	s_add_i32 s58, s22, 0xc000
	v_lshl_add_u64 v[14:15], s[8:9], 0, v[16:17]
	s_mov_b32 m0, s58
	s_add_i32 s2, s22, 0xe000
	ds_read_b128 v[0:3], v167
	ds_read_b128 v[4:7], v167 offset:1024
	ds_read_b128 v[48:51], v167 offset:2048
	ds_read_b128 v[52:55], v167 offset:3072
	ds_read_b128 v[56:59], v167 offset:4096
	ds_read_b128 v[60:63], v167 offset:5120
	ds_read_b128 v[64:67], v167 offset:6144
	s_waitcnt vmcnt(0)
	ds_read_b128 v[68:71], v167 offset:7168
	global_load_lds_dwordx4 v[14:15], off
	v_lshl_add_u64 v[14:15], s[8:9], 0, v[134:135]
	s_mov_b32 m0, s2
	s_nop 0
	global_load_lds_dwordx4 v[14:15], off
	s_waitcnt vmcnt(8)
	s_waitcnt lgkmcnt(0)
	s_barrier
	s_setprio 1
	v_mfma_f32_16x16x32_bf16 v[72:75], v[10:13], v[0:3], 0
	v_mfma_f32_16x16x32_bf16 v[76:79], v[24:27], v[0:3], 0
	v_mfma_f32_16x16x32_bf16 v[80:83], v[10:13], v[48:51], 0
	v_mfma_f32_16x16x32_bf16 v[84:87], v[24:27], v[48:51], 0
	v_mfma_f32_16x16x32_bf16 v[88:91], v[10:13], v[56:59], 0
	v_mfma_f32_16x16x32_bf16 v[92:95], v[24:27], v[56:59], 0
	v_mfma_f32_16x16x32_bf16 v[96:99], v[10:13], v[64:67], 0
	v_mfma_f32_16x16x32_bf16 v[100:103], v[24:27], v[64:67], 0
	v_mfma_f32_16x16x32_bf16 v[72:75], v[20:23], v[4:7], v[72:75]
	v_mfma_f32_16x16x32_bf16 v[76:79], v[28:31], v[4:7], v[76:79]
	v_mfma_f32_16x16x32_bf16 v[80:83], v[20:23], v[52:55], v[80:83]
	v_mfma_f32_16x16x32_bf16 v[84:87], v[28:31], v[52:55], v[84:87]
	v_mfma_f32_16x16x32_bf16 v[88:91], v[20:23], v[60:63], v[88:91]
	v_mfma_f32_16x16x32_bf16 v[92:95], v[28:31], v[60:63], v[92:95]
	v_mfma_f32_16x16x32_bf16 v[96:99], v[20:23], v[68:71], v[96:99]
	v_mfma_f32_16x16x32_bf16 v[100:103], v[28:31], v[68:71], v[100:103]
	s_setprio 0
	s_setprio 1
	v_mfma_f32_16x16x32_bf16 v[104:107], v[32:35], v[0:3], 0
	v_mfma_f32_16x16x32_bf16 v[0:3], v[40:43], v[0:3], 0
	v_mfma_f32_16x16x32_bf16 v[108:111], v[44:47], v[4:7], v[0:3]
	v_mfma_f32_16x16x32_bf16 v[0:3], v[32:35], v[48:51], 0
	v_mfma_f32_16x16x32_bf16 v[112:115], v[36:39], v[52:55], v[0:3]
	v_mfma_f32_16x16x32_bf16 v[0:3], v[40:43], v[48:51], 0
	v_mfma_f32_16x16x32_bf16 v[48:51], v[44:47], v[52:55], v[0:3]
	v_mfma_f32_16x16x32_bf16 v[0:3], v[32:35], v[56:59], 0
	v_mfma_f32_16x16x32_bf16 v[52:55], v[36:39], v[60:63], v[0:3]
	v_mfma_f32_16x16x32_bf16 v[0:3], v[40:43], v[56:59], 0
	v_mfma_f32_16x16x32_bf16 v[56:59], v[44:47], v[60:63], v[0:3]
	v_mfma_f32_16x16x32_bf16 v[0:3], v[32:35], v[64:67], 0
	v_mfma_f32_16x16x32_bf16 v[60:63], v[36:39], v[68:71], v[0:3]
	v_mfma_f32_16x16x32_bf16 v[0:3], v[40:43], v[64:67], 0
	v_mfma_f32_16x16x32_bf16 v[104:107], v[36:39], v[4:7], v[104:107]
	v_mfma_f32_16x16x32_bf16 v[64:67], v[44:47], v[68:71], v[0:3]
	s_setprio 0
	s_barrier
	s_nop 3
	v_lshl_add_u64 v[0:1], s[44:45], 0, v[132:133]
	s_mov_b64 s[64:65], 0x100
	s_add_i32 s42, s42, s21
	v_lshl_add_u64 v[2:3], v[0:1], 0, s[64:65]
	s_mov_b32 m0, s42
	s_add_i32 s8, s42, 0x2000
	ds_read_b128 v[68:71], v167 offset:16384
	ds_read_b128 v[116:119], v167 offset:17408
	ds_read_b128 v[120:123], v167 offset:18432
	s_waitcnt vmcnt(0)
	ds_read_b128 v[124:127], v167 offset:19456
	ds_read_b128 v[128:131], v167 offset:20480
	ds_read_b128 v[138:141], v167 offset:21504
	ds_read_b128 v[142:145], v167 offset:22528
	ds_read_b128 v[168:171], v167 offset:23552
	global_load_lds_dwordx4 v[2:3], off
	v_lshl_add_u64 v[2:3], s[44:45], 0, v[136:137]
	s_add_u32 s60, s44, 0x18100
	v_lshl_add_u64 v[4:5], v[2:3], 0, s[64:65]
	s_mov_b32 m0, s8
	s_addc_u32 s61, s45, 0
	s_add_i32 s9, s30, s21
	global_load_lds_dwordx4 v[4:5], off
	v_lshl_add_u64 v[4:5], s[60:61], 0, v[132:133]
	s_mov_b32 m0, s9
	s_add_i32 s30, s9, 0x2000
	global_load_lds_dwordx4 v[4:5], off
	v_lshl_add_u64 v[4:5], s[60:61], 0, v[136:137]
	s_mov_b32 m0, s30
	s_nop 0
	global_load_lds_dwordx4 v[4:5], off
	v_lshl_add_u64 v[4:5], s[16:17], 0, v[16:17]
	v_lshl_add_u64 v[6:7], v[4:5], 0, s[64:65]
	s_mov_b32 m0, s22
	s_nop 0
	global_load_lds_dwordx4 v[6:7], off
	v_lshl_add_u64 v[6:7], s[16:17], 0, v[134:135]
	v_lshl_add_u64 v[14:15], v[6:7], 0, s[64:65]
	s_mov_b32 m0, s23
	s_nop 0
	global_load_lds_dwordx4 v[14:15], off
	s_waitcnt vmcnt(8)
	s_waitcnt lgkmcnt(0)
	s_barrier
	s_setprio 1
	v_mfma_f32_16x16x32_bf16 v[172:175], v[10:13], v[68:71], 0
	v_mfma_f32_16x16x32_bf16 v[202:205], v[10:13], v[120:123], 0
	v_mfma_f32_16x16x32_bf16 v[210:213], v[10:13], v[128:131], 0
	v_mfma_f32_16x16x32_bf16 v[10:13], v[10:13], v[142:145], 0
	v_mfma_f32_16x16x32_bf16 v[172:175], v[20:23], v[116:119], v[172:175]
	v_mfma_f32_16x16x32_bf16 v[202:205], v[20:23], v[124:127], v[202:205]
	v_mfma_f32_16x16x32_bf16 v[210:213], v[20:23], v[138:141], v[210:213]
	v_mfma_f32_16x16x32_bf16 v[12:15], v[20:23], v[168:171], v[10:13]
	v_mfma_f32_16x16x32_bf16 v[20:23], v[24:27], v[142:145], 0
	v_mfma_f32_16x16x32_bf16 v[198:201], v[24:27], v[68:71], 0
	v_mfma_f32_16x16x32_bf16 v[206:209], v[24:27], v[120:123], 0
	v_mfma_f32_16x16x32_bf16 v[218:221], v[24:27], v[128:131], 0
	v_mfma_f32_16x16x32_bf16 v[20:23], v[28:31], v[168:171], v[20:23]
	v_mfma_f32_16x16x32_bf16 v[198:201], v[28:31], v[116:119], v[198:201]
	v_mfma_f32_16x16x32_bf16 v[206:209], v[28:31], v[124:127], v[206:209]
	v_mfma_f32_16x16x32_bf16 v[218:221], v[28:31], v[138:141], v[218:221]
	s_setprio 0
	s_setprio 1
	v_mfma_f32_16x16x32_bf16 v[24:27], v[32:35], v[68:71], 0
	v_mfma_f32_16x16x32_bf16 v[28:31], v[40:43], v[68:71], 0
	v_mfma_f32_16x16x32_bf16 v[24:27], v[36:39], v[116:119], v[24:27]
	v_mfma_f32_16x16x32_bf16 v[28:31], v[44:47], v[116:119], v[28:31]
	v_mfma_f32_16x16x32_bf16 v[68:71], v[32:35], v[120:123], 0
	v_mfma_f32_16x16x32_bf16 v[116:119], v[40:43], v[120:123], 0
	v_mfma_f32_16x16x32_bf16 v[120:123], v[32:35], v[128:131], 0
	v_mfma_f32_16x16x32_bf16 v[32:35], v[32:35], v[142:145], 0
	v_mfma_f32_16x16x32_bf16 v[68:71], v[36:39], v[124:127], v[68:71]
	v_mfma_f32_16x16x32_bf16 v[116:119], v[44:47], v[124:127], v[116:119]
	v_mfma_f32_16x16x32_bf16 v[120:123], v[36:39], v[138:141], v[120:123]
	v_mfma_f32_16x16x32_bf16 v[124:127], v[40:43], v[128:131], 0
	v_mfma_f32_16x16x32_bf16 v[32:35], v[36:39], v[168:171], v[32:35]
	v_mfma_f32_16x16x32_bf16 v[36:39], v[40:43], v[142:145], 0
	v_mfma_f32_16x16x32_bf16 v[124:127], v[44:47], v[138:141], v[124:127]
	v_mfma_f32_16x16x32_bf16 v[36:39], v[44:47], v[168:171], v[36:39]
	s_setprio 0
	s_barrier
; #define PG8_STAGE(bufoff, gbase, voff) do { _Pragma("unroll") for (int _i = 0; _i < 2; ++_i) \
;         __builtin_amdgcn_global_load_lds((const unsigned*)((const char*)(gbase) + (voff)[_i]), (LAS unsigned*)(lds + (bufoff) + ldsw + _i * 8192), 16, 0, 0); } while (0)
; #define PG8_LDA(dst, b, h) do { _Pragma("unroll") for (int m = 0; m < 4; ++m) _Pragma("unroll") for (int k = 0; k < 2; ++k) dst[m][k] = *(const LAS bf16x8*)(lds + PG8_SA(b, h) + aoff + m * 2048 + k * 1024); } while (0)
; #define PG8_LDB(dst, b, h) do { _Pragma("unroll") for (int n = 0; n < 2; ++n) _Pragma("unroll") for (int k = 0; k < 2; ++k) dst[n][k] = *(const LAS bf16x8*)(lds + PG8_SB(b, h) + boff + n * 2048 + k * 1024); } while (0)
; #define PG8_MMA(ai, bj, At, Bt) do { __builtin_amdgcn_s_setprio(1); _Pragma("unroll") for (int m = 0; m < 4; ++m) _Pragma("unroll") for (int n = 0; n < 2; ++n) _Pragma("unroll") for (int k = 0; k < 2; ++k) \
;         acc[ai][bj][m][n] = __builtin_amdgcn_mfma_f32_16x16x32_bf16(Bt[n][k], At[m][k], acc[ai][bj][m][n], 0, 0, 0); __builtin_amdgcn_s_setprio(0); } while (0)
; #define PG8_WAIT_V(n) asm volatile("s_waitcnt vmcnt(" #n ")" ::: "memory")
; #define PG8_WAIT_L(n) asm volatile("s_waitcnt lgkmcnt(" #n ")" ::: "memory")
; #define PG8_BAR __builtin_amdgcn_s_barrier()
; #define PG8_SCHED __builtin_amdgcn_sched_barrier(0)
; template <class Epi, class Sched, bool ALIGN_EPI = true, bool SP2 = true>
; __device__ __forceinline__ void gemm_phase(LAS unsigned char* lds, const Gemm g, const Sched& S, const Epi& E) {
;     ...
;             PG8_LDB(B0, 1, 0); PG8_LDB(B1, 1, 1); PG8_SCHED; PG8_LDA(At, 1, 0); PG8_STAGE(PG8_SA(0, 1), a2 + hstepA, voffA);
;             PG8_WAIT_V(8); PG8_WAIT_L(0); PG8_BAR; PG8_MMA(0, 0, At, B0); PG8_MMA(0, 1, At, B1); PG8_BAR; PG8_SCHED;
;             PG8_LDA(At, 1, 1); PG8_STAGE(PG8_SB(1, 0), b3, voffB); PG8_STAGE(PG8_SB(1, 1), b3 + hstepB, voffB); PG8_STAGE(PG8_SA(1, 0), a3, voffA);
;             PG8_WAIT_V(8); PG8_WAIT_L(0); PG8_BAR; PG8_MMA(1, 0, At, B0); PG8_MMA(1, 1, At, B1); PG8_BAR; PG8_SCHED;
	s_add_i32 s43, 0, 0x18000
	s_add_i32 s57, 0, 0x1c000
	v_add_u32_e32 v10, s43, v166
	v_add_u32_e32 v11, s57, v166
	ds_read_b128 v[40:43], v10
	ds_read_b128 v[44:47], v10 offset:1024
	ds_read_b128 v[128:131], v10 offset:2048
	ds_read_b128 v[138:141], v10 offset:3072
	ds_read_b128 v[142:145], v11
	ds_read_b128 v[168:171], v11 offset:1024
	ds_read_b128 v[222:225], v11 offset:2048
	ds_read_b128 v[226:229], v11 offset:3072
	s_add_u32 s60, s16, 0x30100
	s_addc_u32 s61, s17, 0
	s_mov_b32 m0, s24
	v_lshl_add_u64 v[154:155], s[60:61], 0, v[16:17]
	ds_read_b128 v[230:233], v167 offset:32768
	ds_read_b128 v[234:237], v167 offset:33792
	ds_read_b128 v[238:241], v167 offset:34816
	ds_read_b128 v[242:245], v167 offset:35840
	ds_read_b128 v[246:249], v167 offset:36864
	ds_read_b128 v[250:253], v167 offset:37888
	ds_read_b128 v[146:149], v167 offset:38912
	ds_read_b128 v[150:153], v167 offset:39936
	global_load_lds_dwordx4 v[154:155], off
	v_lshl_add_u64 v[154:155], s[60:61], 0, v[134:135]
	s_mov_b32 m0, s31
	s_nop 0
	global_load_lds_dwordx4 v[154:155], off
	s_waitcnt vmcnt(8)
	s_waitcnt lgkmcnt(0)
	s_barrier
	s_setprio 1
	v_mfma_f32_16x16x32_bf16 v[72:75], v[40:43], v[230:233], v[72:75]
	v_mfma_f32_16x16x32_bf16 v[76:79], v[128:131], v[230:233], v[76:79]
	v_mfma_f32_16x16x32_bf16 v[80:83], v[40:43], v[238:241], v[80:83]
	v_mfma_f32_16x16x32_bf16 v[84:87], v[128:131], v[238:241], v[84:87]
	v_mfma_f32_16x16x32_bf16 v[88:91], v[40:43], v[246:249], v[88:91]
	v_mfma_f32_16x16x32_bf16 v[92:95], v[128:131], v[246:249], v[92:95]
	v_mfma_f32_16x16x32_bf16 v[96:99], v[40:43], v[146:149], v[96:99]
	v_mfma_f32_16x16x32_bf16 v[100:103], v[128:131], v[146:149], v[100:103]
	v_mfma_f32_16x16x32_bf16 v[72:75], v[44:47], v[234:237], v[72:75]
	v_mfma_f32_16x16x32_bf16 v[76:79], v[138:141], v[234:237], v[76:79]
	v_mfma_f32_16x16x32_bf16 v[80:83], v[44:47], v[242:245], v[80:83]
	v_mfma_f32_16x16x32_bf16 v[84:87], v[138:141], v[242:245], v[84:87]
	v_mfma_f32_16x16x32_bf16 v[88:91], v[44:47], v[250:253], v[88:91]
	v_mfma_f32_16x16x32_bf16 v[92:95], v[138:141], v[250:253], v[92:95]
	v_mfma_f32_16x16x32_bf16 v[96:99], v[44:47], v[150:153], v[96:99]
	v_mfma_f32_16x16x32_bf16 v[100:103], v[138:141], v[150:153], v[100:103]
	s_setprio 0
	s_setprio 1
	v_mfma_f32_16x16x32_bf16 v[104:107], v[142:145], v[230:233], v[104:107]
	v_mfma_f32_16x16x32_bf16 v[108:111], v[222:225], v[230:233], v[108:111]
	v_mfma_f32_16x16x32_bf16 v[112:115], v[142:145], v[238:241], v[112:115]
	v_mfma_f32_16x16x32_bf16 v[48:51], v[222:225], v[238:241], v[48:51]
	v_mfma_f32_16x16x32_bf16 v[52:55], v[142:145], v[246:249], v[52:55]
	v_mfma_f32_16x16x32_bf16 v[56:59], v[222:225], v[246:249], v[56:59]
	v_mfma_f32_16x16x32_bf16 v[60:63], v[142:145], v[146:149], v[60:63]
	v_mfma_f32_16x16x32_bf16 v[64:67], v[222:225], v[146:149], v[64:67]
	v_mfma_f32_16x16x32_bf16 v[104:107], v[168:171], v[234:237], v[104:107]
	v_mfma_f32_16x16x32_bf16 v[108:111], v[226:229], v[234:237], v[108:111]
	v_mfma_f32_16x16x32_bf16 v[112:115], v[168:171], v[242:245], v[112:115]
	v_mfma_f32_16x16x32_bf16 v[48:51], v[226:229], v[242:245], v[48:51]
	v_mfma_f32_16x16x32_bf16 v[52:55], v[168:171], v[250:253], v[52:55]
	v_mfma_f32_16x16x32_bf16 v[56:59], v[226:229], v[250:253], v[56:59]
	v_mfma_f32_16x16x32_bf16 v[60:63], v[168:171], v[150:153], v[60:63]
	v_mfma_f32_16x16x32_bf16 v[64:67], v[226:229], v[150:153], v[64:67]
	s_setprio 0
	s_barrier
	s_add_i32 s61, s43, s21
	s_mov_b64 vcc, 0x180
	s_add_i32 s43, s61, 0x2000
	v_lshl_add_u64 v[154:155], v[0:1], 0, vcc
	s_mov_b32 m0, s61
	s_add_u32 s64, s44, 0x18180
	ds_read_b128 v[146:149], v167 offset:49152
	ds_read_b128 v[150:153], v167 offset:50176
	ds_read_b128 v[230:233], v167 offset:51200
	ds_read_b128 v[234:237], v167 offset:52224
	ds_read_b128 v[238:241], v167 offset:53248
	ds_read_b128 v[242:245], v167 offset:54272
	ds_read_b128 v[246:249], v167 offset:55296
	ds_read_b128 v[250:253], v167 offset:56320
	global_load_lds_dwordx4 v[154:155], off
	v_lshl_add_u64 v[154:155], v[2:3], 0, vcc
	s_mov_b32 m0, s43
	s_addc_u32 s65, s45, 0
	s_add_i32 s57, s57, s21
	global_load_lds_dwordx4 v[154:155], off
	v_lshl_add_u64 v[154:155], s[64:65], 0, v[132:133]
	s_mov_b32 m0, s57
	s_add_i32 s59, s57, 0x2000
	global_load_lds_dwordx4 v[154:155], off
	v_lshl_add_u64 v[154:155], s[64:65], 0, v[136:137]
	s_mov_b32 m0, s59
	s_nop 0
	global_load_lds_dwordx4 v[154:155], off
	v_lshl_add_u64 v[154:155], v[4:5], 0, vcc
	s_mov_b32 m0, s52
	s_nop 0
	global_load_lds_dwordx4 v[154:155], off
	v_lshl_add_u64 v[154:155], v[6:7], 0, vcc
	s_mov_b32 m0, s53
	s_nop 0
	global_load_lds_dwordx4 v[154:155], off
	s_waitcnt vmcnt(8)
	s_waitcnt lgkmcnt(0)
	s_barrier
; #define PG8_STAGE(bufoff, gbase, voff) do { _Pragma("unroll") for (int _i = 0; _i < 2; ++_i) \
;         __builtin_amdgcn_global_load_lds((const unsigned*)((const char*)(gbase) + (voff)[_i]), (LAS unsigned*)(lds + (bufoff) + ldsw + _i * 8192), 16, 0, 0); } while (0)
; #define PG8_LDA(dst, b, h) do { _Pragma("unroll") for (int m = 0; m < 4; ++m) _Pragma("unroll") for (int k = 0; k < 2; ++k) dst[m][k] = *(const LAS bf16x8*)(lds + PG8_SA(b, h) + aoff + m * 2048 + k * 1024); } while (0)
; #define PG8_LDB(dst, b, h) do { _Pragma("unroll") for (int n = 0; n < 2; ++n) _Pragma("unroll") for (int k = 0; k < 2; ++k) dst[n][k] = *(const LAS bf16x8*)(lds + PG8_SB(b, h) + boff + n * 2048 + k * 1024); } while (0)
; #define PG8_MMA(ai, bj, At, Bt) do { __builtin_amdgcn_s_setprio(1); _Pragma("unroll") for (int m = 0; m < 4; ++m) _Pragma("unroll") for (int n = 0; n < 2; ++n) _Pragma("unroll") for (int k = 0; k < 2; ++k) \
;         acc[ai][bj][m][n] = __builtin_amdgcn_mfma_f32_16x16x32_bf16(Bt[n][k], At[m][k], acc[ai][bj][m][n], 0, 0, 0); __builtin_amdgcn_s_setprio(0); } while (0)
; #define PG8_WAIT_V(n) asm volatile("s_waitcnt vmcnt(" #n ")" ::: "memory")
; template <class Epi, class Sched, bool ALIGN_EPI = true, bool SP2 = true>
; __device__ __forceinline__ void gemm_phase(LAS unsigned char* lds, const Gemm g, const Sched& S, const Epi& E) {
;     ...
;             PG8_LDB(B0, 0, 0); PG8_LDB(B1, 0, 1); PG8_SCHED; PG8_LDA(At, 0, 0); PG8_STAGE(PG8_SA(1, 1), a1 + hstepA, voffA);
;             PG8_WAIT_V(8); PG8_WAIT_L(0); PG8_BAR; PG8_MMA(0, 0, At, B0); PG8_MMA(0, 1, At, B1); PG8_BAR; PG8_SCHED;
;             PG8_LDA(At, 0, 1); PG8_STAGE(PG8_SB(0, 0), b2, voffB); PG8_STAGE(PG8_SB(0, 1), b2 + hstepB, voffB); PG8_STAGE(PG8_SA(0, 0), a2, voffA);
;             PG8_WAIT_V(8); PG8_WAIT_L(0); PG8_BAR; PG8_MMA(1, 0, At, B0); PG8_MMA(1, 1, At, B1); PG8_BAR; PG8_SCHED;
;             PG8_LDB(B0, 1, 0); PG8_LDB(B1, 1, 1); PG8_SCHED; PG8_LDA(At, 1, 0); PG8_STAGE(PG8_SA(0, 1), a2 + hstepA, voffA);
;             PG8_WAIT_V(8); PG8_WAIT_L(0); PG8_BAR; PG8_MMA(0, 0, At, B0); PG8_MMA(0, 1, At, B1); PG8_BAR; PG8_SCHED;
;             PG8_LDA(At, 1, 1); PG8_STAGE(PG8_SB(1, 0), b3, voffB); PG8_STAGE(PG8_SB(1, 1), b3 + hstepB, voffB); PG8_STAGE(PG8_SA(1, 0), a3, voffA);
;             PG8_WAIT_V(8); PG8_WAIT_L(0); PG8_BAR; PG8_MMA(1, 0, At, B0); PG8_MMA(1, 1, At, B1); PG8_BAR; PG8_SCHED;
	s_setprio 1
	v_mfma_f32_16x16x32_bf16 v[12:15], v[40:43], v[246:249], v[12:15]
	v_mfma_f32_16x16x32_bf16 v[20:23], v[128:131], v[246:249], v[20:23]
	v_mfma_f32_16x16x32_bf16 v[172:175], v[40:43], v[146:149], v[172:175]
	v_mfma_f32_16x16x32_bf16 v[198:201], v[128:131], v[146:149], v[198:201]
	v_mfma_f32_16x16x32_bf16 v[202:205], v[40:43], v[230:233], v[202:205]
	v_mfma_f32_16x16x32_bf16 v[206:209], v[128:131], v[230:233], v[206:209]
	v_mfma_f32_16x16x32_bf16 v[210:213], v[40:43], v[238:241], v[210:213]
	v_mfma_f32_16x16x32_bf16 v[218:221], v[128:131], v[238:241], v[218:221]
	v_mfma_f32_16x16x32_bf16 v[12:15], v[44:47], v[250:253], v[12:15]
	v_mfma_f32_16x16x32_bf16 v[20:23], v[138:141], v[250:253], v[20:23]
	v_mfma_f32_16x16x32_bf16 v[172:175], v[44:47], v[150:153], v[172:175]
	v_mfma_f32_16x16x32_bf16 v[198:201], v[138:141], v[150:153], v[198:201]
	v_mfma_f32_16x16x32_bf16 v[202:205], v[44:47], v[234:237], v[202:205]
	v_mfma_f32_16x16x32_bf16 v[206:209], v[138:141], v[234:237], v[206:209]
	v_mfma_f32_16x16x32_bf16 v[210:213], v[44:47], v[242:245], v[210:213]
	v_mfma_f32_16x16x32_bf16 v[218:221], v[138:141], v[242:245], v[218:221]
	s_setprio 0
	s_setprio 1
	v_mfma_f32_16x16x32_bf16 v[24:27], v[142:145], v[146:149], v[24:27]
	v_mfma_f32_16x16x32_bf16 v[28:31], v[222:225], v[146:149], v[28:31]
	v_mfma_f32_16x16x32_bf16 v[40:43], v[142:145], v[230:233], v[68:71]
	v_mfma_f32_16x16x32_bf16 v[44:47], v[222:225], v[230:233], v[116:119]
	v_mfma_f32_16x16x32_bf16 v[68:71], v[142:145], v[238:241], v[120:123]
	v_mfma_f32_16x16x32_bf16 v[116:119], v[222:225], v[238:241], v[124:127]
	v_mfma_f32_16x16x32_bf16 v[32:35], v[142:145], v[246:249], v[32:35]
	v_mfma_f32_16x16x32_bf16 v[36:39], v[222:225], v[246:249], v[36:39]
	v_mfma_f32_16x16x32_bf16 v[24:27], v[168:171], v[150:153], v[24:27]
	v_mfma_f32_16x16x32_bf16 v[28:31], v[226:229], v[150:153], v[28:31]
	v_mfma_f32_16x16x32_bf16 v[40:43], v[168:171], v[234:237], v[40:43]
	v_mfma_f32_16x16x32_bf16 v[44:47], v[226:229], v[234:237], v[44:47]
	v_mfma_f32_16x16x32_bf16 v[68:71], v[168:171], v[242:245], v[68:71]
	v_mfma_f32_16x16x32_bf16 v[116:119], v[226:229], v[242:245], v[116:119]
	v_mfma_f32_16x16x32_bf16 v[32:35], v[168:171], v[250:253], v[32:35]
	v_mfma_f32_16x16x32_bf16 v[36:39], v[226:229], v[250:253], v[36:39]
	s_setprio 0
	s_barrier
	ds_read_b128 v[120:123], v8
	ds_read_b128 v[124:127], v8 offset:1024
	ds_read_b128 v[128:131], v8 offset:2048
	ds_read_b128 v[138:141], v8 offset:3072
	ds_read_b128 v[142:145], v9
	ds_read_b128 v[146:149], v9 offset:1024
	ds_read_b128 v[150:153], v9 offset:2048
	ds_read_b128 v[168:171], v9 offset:3072
	s_add_u32 s64, s16, 0x30180
	s_addc_u32 s65, s17, 0
	s_mov_b32 m0, s58
	v_lshl_add_u64 v[154:155], s[64:65], 0, v[16:17]
	ds_read_b128 v[222:225], v167
	ds_read_b128 v[226:229], v167 offset:1024
	ds_read_b128 v[230:233], v167 offset:2048
	ds_read_b128 v[234:237], v167 offset:3072
	ds_read_b128 v[238:241], v167 offset:4096
	ds_read_b128 v[242:245], v167 offset:5120
	ds_read_b128 v[246:249], v167 offset:6144
	ds_read_b128 v[250:253], v167 offset:7168
	global_load_lds_dwordx4 v[154:155], off
	v_lshl_add_u64 v[154:155], s[64:65], 0, v[134:135]
	s_mov_b32 m0, s2
	s_nop 0
	global_load_lds_dwordx4 v[154:155], off
	s_waitcnt vmcnt(8)
	s_waitcnt lgkmcnt(0)
	s_barrier
	s_setprio 1
	v_mfma_f32_16x16x32_bf16 v[72:75], v[120:123], v[222:225], v[72:75]
	v_mfma_f32_16x16x32_bf16 v[76:79], v[128:131], v[222:225], v[76:79]
	v_mfma_f32_16x16x32_bf16 v[80:83], v[120:123], v[230:233], v[80:83]
	v_mfma_f32_16x16x32_bf16 v[84:87], v[128:131], v[230:233], v[84:87]
	v_mfma_f32_16x16x32_bf16 v[88:91], v[120:123], v[238:241], v[88:91]
	v_mfma_f32_16x16x32_bf16 v[92:95], v[128:131], v[238:241], v[92:95]
	v_mfma_f32_16x16x32_bf16 v[96:99], v[120:123], v[246:249], v[96:99]
	v_mfma_f32_16x16x32_bf16 v[100:103], v[128:131], v[246:249], v[100:103]
	v_mfma_f32_16x16x32_bf16 v[72:75], v[124:127], v[226:229], v[72:75]
	v_mfma_f32_16x16x32_bf16 v[76:79], v[138:141], v[226:229], v[76:79]
	v_mfma_f32_16x16x32_bf16 v[80:83], v[124:127], v[234:237], v[80:83]
	v_mfma_f32_16x16x32_bf16 v[84:87], v[138:141], v[234:237], v[84:87]
	v_mfma_f32_16x16x32_bf16 v[88:91], v[124:127], v[242:245], v[88:91]
	v_mfma_f32_16x16x32_bf16 v[92:95], v[138:141], v[242:245], v[92:95]
	v_mfma_f32_16x16x32_bf16 v[96:99], v[124:127], v[250:253], v[96:99]
	v_mfma_f32_16x16x32_bf16 v[100:103], v[138:141], v[250:253], v[100:103]
	s_setprio 0
	s_setprio 1
	v_mfma_f32_16x16x32_bf16 v[104:107], v[142:145], v[222:225], v[104:107]
	v_mfma_f32_16x16x32_bf16 v[108:111], v[150:153], v[222:225], v[108:111]
	v_mfma_f32_16x16x32_bf16 v[112:115], v[142:145], v[230:233], v[112:115]
	v_mfma_f32_16x16x32_bf16 v[48:51], v[150:153], v[230:233], v[48:51]
	v_mfma_f32_16x16x32_bf16 v[52:55], v[142:145], v[238:241], v[52:55]
	v_mfma_f32_16x16x32_bf16 v[56:59], v[150:153], v[238:241], v[56:59]
	v_mfma_f32_16x16x32_bf16 v[60:63], v[142:145], v[246:249], v[60:63]
	v_mfma_f32_16x16x32_bf16 v[64:67], v[150:153], v[246:249], v[64:67]
	v_mfma_f32_16x16x32_bf16 v[104:107], v[146:149], v[226:229], v[104:107]
	v_mfma_f32_16x16x32_bf16 v[108:111], v[168:171], v[226:229], v[108:111]
	v_mfma_f32_16x16x32_bf16 v[112:115], v[146:149], v[234:237], v[112:115]
	v_mfma_f32_16x16x32_bf16 v[48:51], v[168:171], v[234:237], v[48:51]
	v_mfma_f32_16x16x32_bf16 v[52:55], v[146:149], v[242:245], v[52:55]
	v_mfma_f32_16x16x32_bf16 v[56:59], v[168:171], v[242:245], v[56:59]
	v_mfma_f32_16x16x32_bf16 v[60:63], v[146:149], v[250:253], v[60:63]
	v_mfma_f32_16x16x32_bf16 v[64:67], v[168:171], v[250:253], v[64:67]
	s_setprio 0
	s_barrier
; #define PG8_STAGE(bufoff, gbase, voff) do { _Pragma("unroll") for (int _i = 0; _i < 2; ++_i) \
;         __builtin_amdgcn_global_load_lds((const unsigned*)((const char*)(gbase) + (voff)[_i]), (LAS unsigned*)(lds + (bufoff) + ldsw + _i * 8192), 16, 0, 0); } while (0)
; #define PG8_LDA(dst, b, h) do { _Pragma("unroll") for (int m = 0; m < 4; ++m) _Pragma("unroll") for (int k = 0; k < 2; ++k) dst[m][k] = *(const LAS bf16x8*)(lds + PG8_SA(b, h) + aoff + m * 2048 + k * 1024); } while (0)
; #define PG8_LDB(dst, b, h) do { _Pragma("unroll") for (int n = 0; n < 2; ++n) _Pragma("unroll") for (int k = 0; k < 2; ++k) dst[n][k] = *(const LAS bf16x8*)(lds + PG8_SB(b, h) + boff + n * 2048 + k * 1024); } while (0)
; #define PG8_MMA(ai, bj, At, Bt) do { __builtin_amdgcn_s_setprio(1); _Pragma("unroll") for (int m = 0; m < 4; ++m) _Pragma("unroll") for (int n = 0; n < 2; ++n) _Pragma("unroll") for (int k = 0; k < 2; ++k) \
;         acc[ai][bj][m][n] = __builtin_amdgcn_mfma_f32_16x16x32_bf16(Bt[n][k], At[m][k], acc[ai][bj][m][n], 0, 0, 0); __builtin_amdgcn_s_setprio(0); } while (0)
; #define PG8_WAIT_V(n) asm volatile("s_waitcnt vmcnt(" #n ")" ::: "memory")
; #define PG8_WAIT_L(n) asm volatile("s_waitcnt lgkmcnt(" #n ")" ::: "memory")
; #define PG8_BAR __builtin_amdgcn_s_barrier()
; #define PG8_SCHED __builtin_amdgcn_sched_barrier(0)
; template <class Epi, class Sched, bool ALIGN_EPI = true, bool SP2 = true>
; __device__ __forceinline__ void gemm_phase(LAS unsigned char* lds, const Gemm g, const Sched& S, const Epi& E) {
;     ...
;             PG8_WAIT_V(8); PG8_WAIT_L(0); PG8_BAR; PG8_MMA(0, 0, At, B0); PG8_MMA(0, 1, At, B1); PG8_BAR; PG8_SCHED;
;             PG8_LDA(At, 0, 1); PG8_STAGE(PG8_SB(0, 0), b2, voffB); PG8_STAGE(PG8_SB(0, 1), b2 + hstepB, voffB); PG8_STAGE(PG8_SA(0, 0), a2, voffA);
;             PG8_WAIT_V(8); PG8_WAIT_L(0); PG8_BAR; PG8_MMA(1, 0, At, B0); PG8_MMA(1, 1, At, B1); PG8_BAR; PG8_SCHED;
;             PG8_LDB(B0, 1, 0); PG8_LDB(B1, 1, 1); PG8_SCHED; PG8_LDA(At, 1, 0); PG8_STAGE(PG8_SA(0, 1), a2 + hstepA, voffA);
;             PG8_WAIT_V(8); PG8_WAIT_L(0); PG8_BAR; PG8_MMA(0, 0, At, B0); PG8_MMA(0, 1, At, B1); PG8_BAR; PG8_SCHED;
	s_mov_b64 vcc, 0x200
	s_mov_b32 m0, s42
	v_lshl_add_u64 v[154:155], v[0:1], 0, vcc
	s_add_u32 s64, s44, 0x18200
	ds_read_b128 v[222:225], v167 offset:16384
	ds_read_b128 v[226:229], v167 offset:17408
	ds_read_b128 v[230:233], v167 offset:18432
	ds_read_b128 v[234:237], v167 offset:19456
	ds_read_b128 v[238:241], v167 offset:20480
	ds_read_b128 v[242:245], v167 offset:21504
	ds_read_b128 v[246:249], v167 offset:22528
	ds_read_b128 v[250:253], v167 offset:23552
	global_load_lds_dwordx4 v[154:155], off
	v_lshl_add_u64 v[154:155], v[2:3], 0, vcc
	s_mov_b32 m0, s8
	s_addc_u32 s65, s45, 0
	global_load_lds_dwordx4 v[154:155], off
	v_lshl_add_u64 v[154:155], s[64:65], 0, v[132:133]
	s_mov_b32 m0, s9
	s_nop 0
	global_load_lds_dwordx4 v[154:155], off
	v_lshl_add_u64 v[154:155], s[64:65], 0, v[136:137]
	s_mov_b32 m0, s30
	s_nop 0
	global_load_lds_dwordx4 v[154:155], off
	v_lshl_add_u64 v[154:155], v[4:5], 0, vcc
	s_mov_b32 m0, s22
	s_nop 0
	global_load_lds_dwordx4 v[154:155], off
	v_lshl_add_u64 v[154:155], v[6:7], 0, vcc
	s_mov_b32 m0, s23
	s_nop 0
	global_load_lds_dwordx4 v[154:155], off
	s_waitcnt vmcnt(8)
	s_waitcnt lgkmcnt(0)
	s_barrier
	s_setprio 1
	v_mfma_f32_16x16x32_bf16 v[12:15], v[120:123], v[246:249], v[12:15]
	v_mfma_f32_16x16x32_bf16 v[20:23], v[128:131], v[246:249], v[20:23]
	v_mfma_f32_16x16x32_bf16 v[172:175], v[120:123], v[222:225], v[172:175]
	v_mfma_f32_16x16x32_bf16 v[198:201], v[128:131], v[222:225], v[198:201]
	v_mfma_f32_16x16x32_bf16 v[202:205], v[120:123], v[230:233], v[202:205]
	v_mfma_f32_16x16x32_bf16 v[206:209], v[128:131], v[230:233], v[206:209]
	v_mfma_f32_16x16x32_bf16 v[210:213], v[120:123], v[238:241], v[210:213]
	v_mfma_f32_16x16x32_bf16 v[218:221], v[128:131], v[238:241], v[218:221]
	v_mfma_f32_16x16x32_bf16 v[12:15], v[124:127], v[250:253], v[12:15]
	v_mfma_f32_16x16x32_bf16 v[20:23], v[138:141], v[250:253], v[20:23]
	v_mfma_f32_16x16x32_bf16 v[172:175], v[124:127], v[226:229], v[172:175]
	v_mfma_f32_16x16x32_bf16 v[198:201], v[138:141], v[226:229], v[198:201]
	v_mfma_f32_16x16x32_bf16 v[202:205], v[124:127], v[234:237], v[202:205]
	v_mfma_f32_16x16x32_bf16 v[206:209], v[138:141], v[234:237], v[206:209]
	v_mfma_f32_16x16x32_bf16 v[210:213], v[124:127], v[242:245], v[210:213]
	v_mfma_f32_16x16x32_bf16 v[218:221], v[138:141], v[242:245], v[218:221]
	s_setprio 0
	s_setprio 1
	v_mfma_f32_16x16x32_bf16 v[24:27], v[142:145], v[222:225], v[24:27]
	v_mfma_f32_16x16x32_bf16 v[28:31], v[150:153], v[222:225], v[28:31]
	v_mfma_f32_16x16x32_bf16 v[40:43], v[142:145], v[230:233], v[40:43]
	v_mfma_f32_16x16x32_bf16 v[44:47], v[150:153], v[230:233], v[44:47]
	v_mfma_f32_16x16x32_bf16 v[68:71], v[142:145], v[238:241], v[68:71]
	v_mfma_f32_16x16x32_bf16 v[116:119], v[150:153], v[238:241], v[116:119]
	v_mfma_f32_16x16x32_bf16 v[32:35], v[142:145], v[246:249], v[32:35]
	v_mfma_f32_16x16x32_bf16 v[36:39], v[150:153], v[246:249], v[36:39]
	v_mfma_f32_16x16x32_bf16 v[24:27], v[146:149], v[226:229], v[24:27]
	v_mfma_f32_16x16x32_bf16 v[28:31], v[168:171], v[226:229], v[28:31]
	v_mfma_f32_16x16x32_bf16 v[40:43], v[146:149], v[234:237], v[40:43]
	v_mfma_f32_16x16x32_bf16 v[44:47], v[168:171], v[234:237], v[44:47]
	v_mfma_f32_16x16x32_bf16 v[68:71], v[146:149], v[242:245], v[68:71]
	v_mfma_f32_16x16x32_bf16 v[116:119], v[168:171], v[242:245], v[116:119]
	v_mfma_f32_16x16x32_bf16 v[32:35], v[146:149], v[250:253], v[32:35]
	v_mfma_f32_16x16x32_bf16 v[36:39], v[168:171], v[250:253], v[36:39]
	s_setprio 0
	s_barrier
	ds_read_b128 v[120:123], v10
	ds_read_b128 v[124:127], v10 offset:1024
	ds_read_b128 v[128:131], v10 offset:2048
	ds_read_b128 v[138:141], v10 offset:3072
	ds_read_b128 v[142:145], v11
	ds_read_b128 v[146:149], v11 offset:1024
	ds_read_b128 v[150:153], v11 offset:2048
	ds_read_b128 v[168:171], v11 offset:3072
	s_add_u32 s64, s16, 0x30200
	s_addc_u32 s65, s17, 0
	s_mov_b32 m0, s24
	v_lshl_add_u64 v[154:155], s[64:65], 0, v[16:17]
	ds_read_b128 v[222:225], v167 offset:32768
	ds_read_b128 v[226:229], v167 offset:33792
	ds_read_b128 v[230:233], v167 offset:34816
	ds_read_b128 v[234:237], v167 offset:35840
	ds_read_b128 v[238:241], v167 offset:36864
	ds_read_b128 v[242:245], v167 offset:37888
	ds_read_b128 v[246:249], v167 offset:38912
	ds_read_b128 v[250:253], v167 offset:39936
	global_load_lds_dwordx4 v[154:155], off
	v_lshl_add_u64 v[154:155], s[64:65], 0, v[134:135]
	s_mov_b32 m0, s31
	s_nop 0
	global_load_lds_dwordx4 v[154:155], off
	s_waitcnt vmcnt(8)
	s_waitcnt lgkmcnt(0)
	s_barrier
	s_setprio 1
	v_mfma_f32_16x16x32_bf16 v[72:75], v[120:123], v[222:225], v[72:75]
	v_mfma_f32_16x16x32_bf16 v[76:79], v[128:131], v[222:225], v[76:79]
	v_mfma_f32_16x16x32_bf16 v[80:83], v[120:123], v[230:233], v[80:83]
	v_mfma_f32_16x16x32_bf16 v[84:87], v[128:131], v[230:233], v[84:87]
	v_mfma_f32_16x16x32_bf16 v[88:91], v[120:123], v[238:241], v[88:91]
	v_mfma_f32_16x16x32_bf16 v[92:95], v[128:131], v[238:241], v[92:95]
	v_mfma_f32_16x16x32_bf16 v[96:99], v[120:123], v[246:249], v[96:99]
	v_mfma_f32_16x16x32_bf16 v[100:103], v[128:131], v[246:249], v[100:103]
	v_mfma_f32_16x16x32_bf16 v[72:75], v[124:127], v[226:229], v[72:75]
	v_mfma_f32_16x16x32_bf16 v[76:79], v[138:141], v[226:229], v[76:79]
	v_mfma_f32_16x16x32_bf16 v[80:83], v[124:127], v[234:237], v[80:83]
	v_mfma_f32_16x16x32_bf16 v[84:87], v[138:141], v[234:237], v[84:87]
	v_mfma_f32_16x16x32_bf16 v[88:91], v[124:127], v[242:245], v[88:91]
	v_mfma_f32_16x16x32_bf16 v[92:95], v[138:141], v[242:245], v[92:95]
	v_mfma_f32_16x16x32_bf16 v[96:99], v[124:127], v[250:253], v[96:99]
	v_mfma_f32_16x16x32_bf16 v[100:103], v[138:141], v[250:253], v[100:103]
	s_setprio 0
	s_setprio 1
	v_mfma_f32_16x16x32_bf16 v[104:107], v[142:145], v[222:225], v[104:107]
	v_mfma_f32_16x16x32_bf16 v[108:111], v[150:153], v[222:225], v[108:111]
	v_mfma_f32_16x16x32_bf16 v[112:115], v[142:145], v[230:233], v[112:115]
	v_mfma_f32_16x16x32_bf16 v[48:51], v[150:153], v[230:233], v[48:51]
	v_mfma_f32_16x16x32_bf16 v[52:55], v[142:145], v[238:241], v[52:55]
	v_mfma_f32_16x16x32_bf16 v[56:59], v[150:153], v[238:241], v[56:59]
	v_mfma_f32_16x16x32_bf16 v[60:63], v[142:145], v[246:249], v[60:63]
	v_mfma_f32_16x16x32_bf16 v[64:67], v[150:153], v[246:249], v[64:67]
	v_mfma_f32_16x16x32_bf16 v[104:107], v[146:149], v[226:229], v[104:107]
	v_mfma_f32_16x16x32_bf16 v[108:111], v[168:171], v[226:229], v[108:111]
	v_mfma_f32_16x16x32_bf16 v[112:115], v[146:149], v[234:237], v[112:115]
	v_mfma_f32_16x16x32_bf16 v[48:51], v[168:171], v[234:237], v[48:51]
	v_mfma_f32_16x16x32_bf16 v[52:55], v[146:149], v[242:245], v[52:55]
	v_mfma_f32_16x16x32_bf16 v[56:59], v[168:171], v[242:245], v[56:59]
	v_mfma_f32_16x16x32_bf16 v[60:63], v[146:149], v[250:253], v[60:63]
	v_mfma_f32_16x16x32_bf16 v[64:67], v[168:171], v[250:253], v[64:67]
	s_setprio 0
	s_barrier
; #define PG8_STAGE(bufoff, gbase, voff) do { _Pragma("unroll") for (int _i = 0; _i < 2; ++_i) \
;         __builtin_amdgcn_global_load_lds((const unsigned*)((const char*)(gbase) + (voff)[_i]), (LAS unsigned*)(lds + (bufoff) + ldsw + _i * 8192), 16, 0, 0); } while (0)
; #define PG8_LDA(dst, b, h) do { _Pragma("unroll") for (int m = 0; m < 4; ++m) _Pragma("unroll") for (int k = 0; k < 2; ++k) dst[m][k] = *(const LAS bf16x8*)(lds + PG8_SA(b, h) + aoff + m * 2048 + k * 1024); } while (0)
; #define PG8_LDB(dst, b, h) do { _Pragma("unroll") for (int n = 0; n < 2; ++n) _Pragma("unroll") for (int k = 0; k < 2; ++k) dst[n][k] = *(const LAS bf16x8*)(lds + PG8_SB(b, h) + boff + n * 2048 + k * 1024); } while (0)
; #define PG8_MMA(ai, bj, At, Bt) do { __builtin_amdgcn_s_setprio(1); _Pragma("unroll") for (int m = 0; m < 4; ++m) _Pragma("unroll") for (int n = 0; n < 2; ++n) _Pragma("unroll") for (int k = 0; k < 2; ++k) \
;         acc[ai][bj][m][n] = __builtin_amdgcn_mfma_f32_16x16x32_bf16(Bt[n][k], At[m][k], acc[ai][bj][m][n], 0, 0, 0); __builtin_amdgcn_s_setprio(0); } while (0)
; #define PG8_WAIT_V(n) asm volatile("s_waitcnt vmcnt(" #n ")" ::: "memory")
; template <class Epi, class Sched, bool ALIGN_EPI = true, bool SP2 = true>
; __device__ __forceinline__ void gemm_phase(LAS unsigned char* lds, const Gemm g, const Sched& S, const Epi& E) {
;     ...
;             PG8_LDB(B0, 0, 0); PG8_LDB(B1, 0, 1); PG8_SCHED; PG8_LDA(At, 0, 0); PG8_STAGE(PG8_SA(1, 1), a1 + hstepA, voffA);
;             PG8_WAIT_V(8); PG8_WAIT_L(0); PG8_BAR; PG8_MMA(0, 0, At, B0); PG8_MMA(0, 1, At, B1); PG8_BAR; PG8_SCHED;
;             PG8_LDA(At, 0, 1); PG8_STAGE(PG8_SB(0, 0), b2, voffB); PG8_STAGE(PG8_SB(0, 1), b2 + hstepB, voffB); PG8_STAGE(PG8_SA(0, 0), a2, voffA);
;             PG8_WAIT_V(8); PG8_WAIT_L(0); PG8_BAR; PG8_MMA(1, 0, At, B0); PG8_MMA(1, 1, At, B1); PG8_BAR; PG8_SCHED;
;             PG8_LDB(B0, 1, 0); PG8_LDB(B1, 1, 1); PG8_SCHED; PG8_LDA(At, 1, 0); PG8_STAGE(PG8_SA(0, 1), a2 + hstepA, voffA);
;             PG8_WAIT_V(8); PG8_WAIT_L(0); PG8_BAR; PG8_MMA(0, 0, At, B0); PG8_MMA(0, 1, At, B1); PG8_BAR; PG8_SCHED;
;             PG8_LDA(At, 1, 1); PG8_STAGE(PG8_SB(1, 0), b3, voffB); PG8_STAGE(PG8_SB(1, 1), b3 + hstepB, voffB); PG8_STAGE(PG8_SA(1, 0), a3, voffA);
;             PG8_WAIT_V(8); PG8_WAIT_L(0); PG8_BAR; PG8_MMA(1, 0, At, B0); PG8_MMA(1, 1, At, B1); PG8_BAR; PG8_SCHED;
	s_mov_b64 s[64:65], 0x280
	s_mov_b32 m0, s61
	v_lshl_add_u64 v[0:1], v[0:1], 0, s[64:65]
	s_add_u32 s44, s44, 0x18280
	ds_read_b128 v[222:225], v167 offset:49152
	ds_read_b128 v[226:229], v167 offset:50176
	ds_read_b128 v[230:233], v167 offset:51200
	ds_read_b128 v[234:237], v167 offset:52224
	ds_read_b128 v[238:241], v167 offset:53248
	ds_read_b128 v[242:245], v167 offset:54272
	ds_read_b128 v[246:249], v167 offset:55296
	ds_read_b128 v[250:253], v167 offset:56320
	global_load_lds_dwordx4 v[0:1], off
	v_lshl_add_u64 v[0:1], v[2:3], 0, s[64:65]
	s_mov_b32 m0, s43
	s_addc_u32 s45, s45, 0
	global_load_lds_dwordx4 v[0:1], off
	v_lshl_add_u64 v[0:1], s[44:45], 0, v[132:133]
	s_mov_b32 m0, s57
	s_nop 0
	global_load_lds_dwordx4 v[0:1], off
	v_lshl_add_u64 v[0:1], s[44:45], 0, v[136:137]
	s_mov_b32 m0, s59
	s_nop 0
	global_load_lds_dwordx4 v[0:1], off
	v_lshl_add_u64 v[0:1], v[4:5], 0, s[64:65]
	s_mov_b32 m0, s52
	s_nop 0
	global_load_lds_dwordx4 v[0:1], off
	v_lshl_add_u64 v[0:1], v[6:7], 0, s[64:65]
	s_mov_b32 m0, s53
	s_nop 0
	global_load_lds_dwordx4 v[0:1], off
	s_waitcnt vmcnt(8)
	s_waitcnt lgkmcnt(0)
	s_barrier
	s_setprio 1
	v_mfma_f32_16x16x32_bf16 v[0:3], v[120:123], v[222:225], v[172:175]
	v_mfma_f32_16x16x32_bf16 v[4:7], v[128:131], v[222:225], v[198:201]
	v_mfma_f32_16x16x32_bf16 v[12:15], v[120:123], v[246:249], v[12:15]
	v_mfma_f32_16x16x32_bf16 v[20:23], v[128:131], v[246:249], v[20:23]
	v_mfma_f32_16x16x32_bf16 v[0:3], v[124:127], v[226:229], v[0:3]
	v_mfma_f32_16x16x32_bf16 v[4:7], v[138:141], v[226:229], v[4:7]
	v_mfma_f32_16x16x32_bf16 v[172:175], v[120:123], v[230:233], v[202:205]
	v_mfma_f32_16x16x32_bf16 v[198:201], v[128:131], v[230:233], v[206:209]
	v_mfma_f32_16x16x32_bf16 v[202:205], v[120:123], v[238:241], v[210:213]
	v_mfma_f32_16x16x32_bf16 v[206:209], v[128:131], v[238:241], v[218:221]
	v_mfma_f32_16x16x32_bf16 v[12:15], v[124:127], v[250:253], v[12:15]
	v_mfma_f32_16x16x32_bf16 v[20:23], v[138:141], v[250:253], v[20:23]
	v_mfma_f32_16x16x32_bf16 v[172:175], v[124:127], v[234:237], v[172:175]
	v_mfma_f32_16x16x32_bf16 v[198:201], v[138:141], v[234:237], v[198:201]
	v_mfma_f32_16x16x32_bf16 v[202:205], v[124:127], v[242:245], v[202:205]
	v_mfma_f32_16x16x32_bf16 v[206:209], v[138:141], v[242:245], v[206:209]
	s_setprio 0
	s_setprio 1
	v_mfma_f32_16x16x32_bf16 v[24:27], v[142:145], v[222:225], v[24:27]
	v_mfma_f32_16x16x32_bf16 v[28:31], v[150:153], v[222:225], v[28:31]
	v_mfma_f32_16x16x32_bf16 v[40:43], v[142:145], v[230:233], v[40:43]
	v_mfma_f32_16x16x32_bf16 v[44:47], v[150:153], v[230:233], v[44:47]
	v_mfma_f32_16x16x32_bf16 v[68:71], v[142:145], v[238:241], v[68:71]
	v_mfma_f32_16x16x32_bf16 v[116:119], v[150:153], v[238:241], v[116:119]
	v_mfma_f32_16x16x32_bf16 v[32:35], v[142:145], v[246:249], v[32:35]
	v_mfma_f32_16x16x32_bf16 v[36:39], v[150:153], v[246:249], v[36:39]
	v_mfma_f32_16x16x32_bf16 v[24:27], v[146:149], v[226:229], v[24:27]
	v_mfma_f32_16x16x32_bf16 v[28:31], v[168:171], v[226:229], v[28:31]
	v_mfma_f32_16x16x32_bf16 v[40:43], v[146:149], v[234:237], v[40:43]
	v_mfma_f32_16x16x32_bf16 v[44:47], v[168:171], v[234:237], v[44:47]
	v_mfma_f32_16x16x32_bf16 v[68:71], v[146:149], v[242:245], v[68:71]
	v_mfma_f32_16x16x32_bf16 v[116:119], v[168:171], v[242:245], v[116:119]
	v_mfma_f32_16x16x32_bf16 v[32:35], v[146:149], v[250:253], v[32:35]
	v_mfma_f32_16x16x32_bf16 v[36:39], v[168:171], v[250:253], v[36:39]
	s_setprio 0
	s_barrier
	ds_read_b128 v[120:123], v8
	ds_read_b128 v[124:127], v8 offset:1024
	ds_read_b128 v[128:131], v8 offset:2048
	ds_read_b128 v[138:141], v8 offset:3072
	ds_read_b128 v[142:145], v9
	ds_read_b128 v[146:149], v9 offset:1024
	ds_read_b128 v[150:153], v9 offset:2048
	ds_read_b128 v[168:171], v9 offset:3072
	s_add_u32 s16, s16, 0x30280
	s_addc_u32 s17, s17, 0
	s_mov_b32 m0, s58
	v_lshl_add_u64 v[8:9], s[16:17], 0, v[16:17]
	ds_read_b128 v[210:213], v167
	ds_read_b128 v[218:221], v167 offset:1024
	ds_read_b128 v[222:225], v167 offset:2048
	ds_read_b128 v[226:229], v167 offset:3072
	ds_read_b128 v[230:233], v167 offset:4096
	ds_read_b128 v[234:237], v167 offset:5120
	ds_read_b128 v[238:241], v167 offset:6144
	ds_read_b128 v[242:245], v167 offset:7168
	global_load_lds_dwordx4 v[8:9], off
	v_lshl_add_u64 v[8:9], s[16:17], 0, v[134:135]
	s_mov_b32 m0, s2
	s_nop 0
	global_load_lds_dwordx4 v[8:9], off
	s_waitcnt vmcnt(8)
	s_waitcnt lgkmcnt(0)
	s_barrier
	s_setprio 1
	v_mfma_f32_16x16x32_bf16 v[96:99], v[120:123], v[238:241], v[96:99]
	v_mfma_f32_16x16x32_bf16 v[72:75], v[120:123], v[210:213], v[72:75]
	v_mfma_f32_16x16x32_bf16 v[76:79], v[128:131], v[210:213], v[76:79]
	v_mfma_f32_16x16x32_bf16 v[80:83], v[120:123], v[222:225], v[80:83]
	v_mfma_f32_16x16x32_bf16 v[84:87], v[128:131], v[222:225], v[84:87]
	v_mfma_f32_16x16x32_bf16 v[88:91], v[120:123], v[230:233], v[88:91]
	v_mfma_f32_16x16x32_bf16 v[92:95], v[128:131], v[230:233], v[92:95]
	v_mfma_f32_16x16x32_bf16 v[246:249], v[124:127], v[242:245], v[96:99]
	v_mfma_f32_16x16x32_bf16 v[96:99], v[128:131], v[238:241], v[100:103]
	v_mfma_f32_16x16x32_bf16 v[72:75], v[124:127], v[218:221], v[72:75]
	v_mfma_f32_16x16x32_bf16 v[76:79], v[138:141], v[218:221], v[76:79]
	v_mfma_f32_16x16x32_bf16 v[80:83], v[124:127], v[226:229], v[80:83]
	v_mfma_f32_16x16x32_bf16 v[84:87], v[138:141], v[226:229], v[84:87]
	v_mfma_f32_16x16x32_bf16 v[88:91], v[124:127], v[234:237], v[88:91]
	v_mfma_f32_16x16x32_bf16 v[92:95], v[138:141], v[234:237], v[92:95]
	v_mfma_f32_16x16x32_bf16 v[100:103], v[138:141], v[242:245], v[96:99]
	s_setprio 0
	s_setprio 1
	v_mfma_f32_16x16x32_bf16 v[96:99], v[142:145], v[210:213], v[104:107]
	v_mfma_f32_16x16x32_bf16 v[104:107], v[146:149], v[218:221], v[96:99]
	v_mfma_f32_16x16x32_bf16 v[96:99], v[150:153], v[210:213], v[108:111]
	v_mfma_f32_16x16x32_bf16 v[48:51], v[150:153], v[222:225], v[48:51]
	v_mfma_f32_16x16x32_bf16 v[52:55], v[142:145], v[230:233], v[52:55]
	v_mfma_f32_16x16x32_bf16 v[56:59], v[150:153], v[230:233], v[56:59]
	v_mfma_f32_16x16x32_bf16 v[60:63], v[142:145], v[238:241], v[60:63]
	v_mfma_f32_16x16x32_bf16 v[64:67], v[150:153], v[238:241], v[64:67]
	v_mfma_f32_16x16x32_bf16 v[210:213], v[168:171], v[218:221], v[96:99]
	v_mfma_f32_16x16x32_bf16 v[96:99], v[142:145], v[222:225], v[112:115]
	v_mfma_f32_16x16x32_bf16 v[48:51], v[168:171], v[226:229], v[48:51]
	v_mfma_f32_16x16x32_bf16 v[52:55], v[146:149], v[234:237], v[52:55]
	v_mfma_f32_16x16x32_bf16 v[56:59], v[168:171], v[234:237], v[56:59]
	v_mfma_f32_16x16x32_bf16 v[60:63], v[146:149], v[242:245], v[60:63]
	v_mfma_f32_16x16x32_bf16 v[64:67], v[168:171], v[242:245], v[64:67]
	v_mfma_f32_16x16x32_bf16 v[218:221], v[146:149], v[226:229], v[96:99]
	s_setprio 0
	s_barrier
; #define PG8_STAGE(bufoff, gbase, voff) do { _Pragma("unroll") for (int _i = 0; _i < 2; ++_i) \
;         __builtin_amdgcn_global_load_lds((const unsigned*)((const char*)(gbase) + (voff)[_i]), (LAS unsigned*)(lds + (bufoff) + ldsw + _i * 8192), 16, 0, 0); } while (0)
; #define PG8_LDA(dst, b, h) do { _Pragma("unroll") for (int m = 0; m < 4; ++m) _Pragma("unroll") for (int k = 0; k < 2; ++k) dst[m][k] = *(const LAS bf16x8*)(lds + PG8_SA(b, h) + aoff + m * 2048 + k * 1024); } while (0)
; #define PG8_LDB(dst, b, h) do { _Pragma("unroll") for (int n = 0; n < 2; ++n) _Pragma("unroll") for (int k = 0; k < 2; ++k) dst[n][k] = *(const LAS bf16x8*)(lds + PG8_SB(b, h) + boff + n * 2048 + k * 1024); } while (0)
; #define PG8_MMA(ai, bj, At, Bt) do { __builtin_amdgcn_s_setprio(1); _Pragma("unroll") for (int m = 0; m < 4; ++m) _Pragma("unroll") for (int n = 0; n < 2; ++n) _Pragma("unroll") for (int k = 0; k < 2; ++k) \
;         acc[ai][bj][m][n] = __builtin_amdgcn_mfma_f32_16x16x32_bf16(Bt[n][k], At[m][k], acc[ai][bj][m][n], 0, 0, 0); __builtin_amdgcn_s_setprio(0); } while (0)
; #define PG8_WAIT_V(n) asm volatile("s_waitcnt vmcnt(" #n ")" ::: "memory")
; #define PG8_WAIT_L(n) asm volatile("s_waitcnt lgkmcnt(" #n ")" ::: "memory")
; #define PG8_BAR __builtin_amdgcn_s_barrier()
; #define PG8_SCHED __builtin_amdgcn_sched_barrier(0)
; template <class Epi, class Sched, bool ALIGN_EPI = true, bool SP2 = true>
; __device__ __forceinline__ void gemm_phase(LAS unsigned char* lds, const Gemm g, const Sched& S, const Epi& E) {
;     ...
;             PG8_WAIT_V(8); PG8_WAIT_L(0); PG8_BAR; PG8_MMA(0, 0, At, B0); PG8_MMA(0, 1, At, B1); PG8_BAR; PG8_SCHED;
;             PG8_LDA(At, 0, 1); PG8_STAGE(PG8_SB(0, 0), b2, voffB); PG8_STAGE(PG8_SB(0, 1), b2 + hstepB, voffB); PG8_STAGE(PG8_SA(0, 0), a2, voffA);
;             PG8_WAIT_V(8); PG8_WAIT_L(0); PG8_BAR; PG8_MMA(1, 0, At, B0); PG8_MMA(1, 1, At, B1); PG8_BAR; PG8_SCHED;
;             PG8_LDB(B0, 1, 0); PG8_LDB(B1, 1, 1); PG8_SCHED; PG8_LDA(At, 1, 0); PG8_STAGE(PG8_SA(0, 1), a2 + hstepA, voffA);
;             PG8_WAIT_V(8); PG8_WAIT_L(0); PG8_BAR; PG8_MMA(0, 0, At, B0); PG8_MMA(0, 1, At, B1); PG8_BAR; PG8_SCHED;
	s_mov_b32 m0, s42
	v_lshl_add_u64 v[176:177], s[34:35], 0, v[132:133]
	s_add_u32 s16, s34, 0x18000
	ds_read_b128 v[96:99], v167 offset:16384
	ds_read_b128 v[108:111], v167 offset:17408
	ds_read_b128 v[112:115], v167 offset:18432
	ds_read_b128 v[222:225], v167 offset:19456
	ds_read_b128 v[226:229], v167 offset:20480
	ds_read_b128 v[230:233], v167 offset:21504
	ds_read_b128 v[234:237], v167 offset:22528
	ds_read_b128 v[238:241], v167 offset:23552
	global_load_lds_dwordx4 v[176:177], off
	v_lshl_add_u64 v[214:215], s[34:35], 0, v[136:137]
	s_mov_b32 m0, s8
	s_addc_u32 s17, s35, 0
	global_load_lds_dwordx4 v[214:215], off
	v_lshl_add_u64 v[8:9], s[16:17], 0, v[132:133]
	s_mov_b32 m0, s9
	v_lshl_add_u64 v[182:183], s[46:47], 0, v[16:17]
	global_load_lds_dwordx4 v[8:9], off
	v_lshl_add_u64 v[8:9], s[16:17], 0, v[136:137]
	s_mov_b32 m0, s30
	v_lshl_add_u64 v[178:179], s[46:47], 0, v[134:135]
	global_load_lds_dwordx4 v[8:9], off
	s_mov_b32 m0, s22
	s_nop 0
	global_load_lds_dwordx4 v[182:183], off
	s_mov_b32 m0, s23
	s_nop 0
	global_load_lds_dwordx4 v[178:179], off
	s_waitcnt vmcnt(8)
	s_waitcnt lgkmcnt(0)
	s_barrier
	s_setprio 1
	v_mfma_f32_16x16x32_bf16 v[0:3], v[120:123], v[96:99], v[0:3]
	v_mfma_f32_16x16x32_bf16 v[4:7], v[128:131], v[96:99], v[4:7]
	v_mfma_f32_16x16x32_bf16 v[12:15], v[120:123], v[234:237], v[12:15]
	v_mfma_f32_16x16x32_bf16 v[20:23], v[128:131], v[234:237], v[20:23]
	v_mfma_f32_16x16x32_bf16 v[0:3], v[124:127], v[108:111], v[0:3]
	v_mfma_f32_16x16x32_bf16 v[4:7], v[138:141], v[108:111], v[4:7]
	v_mfma_f32_16x16x32_bf16 v[172:175], v[120:123], v[112:115], v[172:175]
	v_mfma_f32_16x16x32_bf16 v[198:201], v[128:131], v[112:115], v[198:201]
	v_mfma_f32_16x16x32_bf16 v[202:205], v[120:123], v[226:229], v[202:205]
	v_mfma_f32_16x16x32_bf16 v[206:209], v[128:131], v[226:229], v[206:209]
	v_mfma_f32_16x16x32_bf16 v[12:15], v[124:127], v[238:241], v[12:15]
	v_mfma_f32_16x16x32_bf16 v[20:23], v[138:141], v[238:241], v[20:23]
	v_mfma_f32_16x16x32_bf16 v[172:175], v[124:127], v[222:225], v[172:175]
	v_mfma_f32_16x16x32_bf16 v[198:201], v[138:141], v[222:225], v[198:201]
	v_mfma_f32_16x16x32_bf16 v[202:205], v[124:127], v[230:233], v[202:205]
	v_mfma_f32_16x16x32_bf16 v[206:209], v[138:141], v[230:233], v[206:209]
	s_setprio 0
	s_setprio 1
	v_mfma_f32_16x16x32_bf16 v[28:31], v[150:153], v[96:99], v[28:31]
	v_mfma_f32_16x16x32_bf16 v[138:141], v[168:171], v[108:111], v[28:31]
	v_mfma_f32_16x16x32_bf16 v[28:31], v[142:145], v[112:115], v[40:43]
	v_mfma_f32_16x16x32_bf16 v[40:43], v[146:149], v[222:225], v[28:31]
	v_mfma_f32_16x16x32_bf16 v[28:31], v[150:153], v[112:115], v[44:47]
	v_mfma_f32_16x16x32_bf16 v[222:225], v[168:171], v[222:225], v[28:31]
	v_mfma_f32_16x16x32_bf16 v[28:31], v[142:145], v[226:229], v[68:71]
	v_mfma_f32_16x16x32_bf16 v[242:245], v[146:149], v[230:233], v[28:31]
	v_mfma_f32_16x16x32_bf16 v[28:31], v[150:153], v[226:229], v[116:119]
	v_mfma_f32_16x16x32_bf16 v[24:27], v[142:145], v[96:99], v[24:27]
	v_mfma_f32_16x16x32_bf16 v[226:229], v[168:171], v[230:233], v[28:31]
	v_mfma_f32_16x16x32_bf16 v[28:31], v[142:145], v[234:237], v[32:35]
	v_mfma_f32_16x16x32_bf16 v[24:27], v[146:149], v[108:111], v[24:27]
	v_mfma_f32_16x16x32_bf16 v[142:145], v[146:149], v[238:241], v[28:31]
	v_mfma_f32_16x16x32_bf16 v[28:31], v[150:153], v[234:237], v[36:39]
	v_mfma_f32_16x16x32_bf16 v[146:149], v[168:171], v[238:241], v[28:31]
	s_setprio 0
	s_barrier
	ds_read_b128 v[36:39], v10
	ds_read_b128 v[150:153], v10 offset:1024
	ds_read_b128 v[168:171], v10 offset:2048
	ds_read_b128 v[230:233], v10 offset:3072
	ds_read_b128 v[234:237], v11
	ds_read_b128 v[238:241], v11 offset:1024
	ds_read_b128 v[250:253], v11 offset:2048
	ds_read_b128 v[154:157], v11 offset:3072
	s_add_u32 s8, s46, 0x30000
	s_addc_u32 s9, s47, 0
	s_mov_b32 m0, s24
	v_lshl_add_u64 v[96:97], s[8:9], 0, v[16:17]
	ds_read_b128 v[8:11], v167 offset:32768
	ds_read_b128 v[28:31], v167 offset:33792
	ds_read_b128 v[32:35], v167 offset:34816
	ds_read_b128 v[44:47], v167 offset:35840
	ds_read_b128 v[68:71], v167 offset:36864
	ds_read_b128 v[186:189], v167 offset:37888
	ds_read_b128 v[190:193], v167 offset:38912
	ds_read_b128 v[158:161], v167 offset:39936
	global_load_lds_dwordx4 v[96:97], off
	v_lshl_add_u64 v[96:97], s[8:9], 0, v[134:135]
	s_mov_b32 m0, s31
	s_nop 0
	global_load_lds_dwordx4 v[96:97], off
	s_waitcnt vmcnt(8)
	s_waitcnt lgkmcnt(0)
	s_barrier
; #define PG8_STAGE(bufoff, gbase, voff) do { _Pragma("unroll") for (int _i = 0; _i < 2; ++_i) \
;         __builtin_amdgcn_global_load_lds((const unsigned*)((const char*)(gbase) + (voff)[_i]), (LAS unsigned*)(lds + (bufoff) + ldsw + _i * 8192), 16, 0, 0); } while (0)
; #define PG8_LDA(dst, b, h) do { _Pragma("unroll") for (int m = 0; m < 4; ++m) _Pragma("unroll") for (int k = 0; k < 2; ++k) dst[m][k] = *(const LAS bf16x8*)(lds + PG8_SA(b, h) + aoff + m * 2048 + k * 1024); } while (0)
; #define PG8_MMA(ai, bj, At, Bt) do { __builtin_amdgcn_s_setprio(1); _Pragma("unroll") for (int m = 0; m < 4; ++m) _Pragma("unroll") for (int n = 0; n < 2; ++n) _Pragma("unroll") for (int k = 0; k < 2; ++k) \
;         acc[ai][bj][m][n] = __builtin_amdgcn_mfma_f32_16x16x32_bf16(Bt[n][k], At[m][k], acc[ai][bj][m][n], 0, 0, 0); __builtin_amdgcn_s_setprio(0); } while (0)
; #define PG8_WAIT_V(n) asm volatile("s_waitcnt vmcnt(" #n ")" ::: "memory")
; #define PG8_WAIT_L(n) asm volatile("s_waitcnt lgkmcnt(" #n ")" ::: "memory")
; #define PG8_BAR __builtin_amdgcn_s_barrier()
; #define PG8_SCHED __builtin_amdgcn_sched_barrier(0)
; template <class Epi, class Sched, bool ALIGN_EPI = true, bool SP2 = true>
; __device__ __forceinline__ void gemm_phase(LAS unsigned char* lds, const Gemm g, const Sched& S, const Epi& E) {
;     ...
;             PG8_WAIT_V(8); PG8_WAIT_L(0); PG8_BAR; PG8_MMA(0, 0, At, B0); PG8_MMA(0, 1, At, B1); PG8_BAR; PG8_SCHED;
;             PG8_LDA(At, 1, 1); PG8_STAGE(PG8_SB(1, 0), b3, voffB); PG8_STAGE(PG8_SB(1, 1), b3 + hstepB, voffB); PG8_STAGE(PG8_SA(1, 0), a3, voffA);
;             PG8_WAIT_V(8); PG8_WAIT_L(0); PG8_BAR; PG8_MMA(1, 0, At, B0); PG8_MMA(1, 1, At, B1); PG8_BAR; PG8_SCHED;
;         }
;         if constexpr (ALIGN_EPI) { if (wr == 0) PG8_BAR; }
	s_setprio 1
	v_mfma_f32_16x16x32_bf16 v[72:75], v[36:39], v[8:11], v[72:75]
	v_mfma_f32_16x16x32_bf16 v[124:127], v[150:153], v[28:31], v[72:75]
	v_mfma_f32_16x16x32_bf16 v[72:75], v[168:171], v[8:11], v[76:79]
	v_mfma_f32_16x16x32_bf16 v[128:131], v[230:233], v[28:31], v[72:75]
	v_mfma_f32_16x16x32_bf16 v[72:75], v[36:39], v[32:35], v[80:83]
	v_mfma_f32_16x16x32_bf16 v[112:115], v[150:153], v[44:47], v[72:75]
	v_mfma_f32_16x16x32_bf16 v[72:75], v[168:171], v[32:35], v[84:87]
	v_mfma_f32_16x16x32_bf16 v[108:111], v[230:233], v[44:47], v[72:75]
	v_mfma_f32_16x16x32_bf16 v[72:75], v[36:39], v[68:71], v[88:91]
	v_mfma_f32_16x16x32_bf16 v[96:99], v[150:153], v[186:189], v[72:75]
	v_mfma_f32_16x16x32_bf16 v[72:75], v[168:171], v[68:71], v[92:95]
	v_mfma_f32_16x16x32_bf16 v[92:95], v[230:233], v[186:189], v[72:75]
	v_mfma_f32_16x16x32_bf16 v[72:75], v[36:39], v[190:193], v[246:249]
	v_mfma_f32_16x16x32_bf16 v[80:83], v[150:153], v[158:161], v[72:75]
	v_mfma_f32_16x16x32_bf16 v[72:75], v[168:171], v[190:193], v[100:103]
	v_mfma_f32_16x16x32_bf16 v[76:79], v[230:233], v[158:161], v[72:75]
	s_setprio 0
	s_setprio 1
	v_mfma_f32_16x16x32_bf16 v[72:75], v[234:237], v[8:11], v[104:107]
	v_mfma_f32_16x16x32_bf16 v[8:11], v[250:253], v[8:11], v[210:213]
	v_mfma_f32_16x16x32_bf16 v[116:119], v[154:157], v[28:31], v[8:11]
	v_mfma_f32_16x16x32_bf16 v[8:11], v[234:237], v[32:35], v[218:221]
	v_mfma_f32_16x16x32_bf16 v[104:107], v[238:241], v[44:47], v[8:11]
	v_mfma_f32_16x16x32_bf16 v[8:11], v[250:253], v[32:35], v[48:51]
	v_mfma_f32_16x16x32_bf16 v[100:103], v[154:157], v[44:47], v[8:11]
	v_mfma_f32_16x16x32_bf16 v[8:11], v[234:237], v[68:71], v[52:55]
	v_mfma_f32_16x16x32_bf16 v[88:91], v[238:241], v[186:189], v[8:11]
	v_mfma_f32_16x16x32_bf16 v[8:11], v[250:253], v[68:71], v[56:59]
	v_mfma_f32_16x16x32_bf16 v[84:87], v[154:157], v[186:189], v[8:11]
	v_mfma_f32_16x16x32_bf16 v[8:11], v[234:237], v[190:193], v[60:63]
	v_mfma_f32_16x16x32_bf16 v[120:123], v[238:241], v[28:31], v[72:75]
	v_mfma_f32_16x16x32_bf16 v[72:75], v[238:241], v[158:161], v[8:11]
	v_mfma_f32_16x16x32_bf16 v[8:11], v[250:253], v[190:193], v[64:67]
	v_mfma_f32_16x16x32_bf16 v[68:71], v[154:157], v[158:161], v[8:11]
	s_setprio 0
	s_barrier
	s_mov_b32 m0, s61
	s_nop 3
	v_lshl_add_u64 v[8:9], v[176:177], 0, s[14:15]
	s_add_u32 s8, s34, 0x18080
	ds_read_b128 v[52:55], v167 offset:49152
	ds_read_b128 v[158:161], v167 offset:50176
	ds_read_b128 v[186:189], v167 offset:51200
	ds_read_b128 v[190:193], v167 offset:52224
	ds_read_b128 v[210:213], v167 offset:53248
	ds_read_b128 v[218:221], v167 offset:54272
	ds_read_b128 v[246:249], v167 offset:55296
	ds_read_b128 v[162:165], v167 offset:56320
	global_load_lds_dwordx4 v[8:9], off
	v_lshl_add_u64 v[8:9], v[214:215], 0, s[14:15]
	s_mov_b32 m0, s43
	s_addc_u32 s9, s35, 0
	global_load_lds_dwordx4 v[8:9], off
	v_lshl_add_u64 v[8:9], s[8:9], 0, v[132:133]
	s_mov_b32 m0, s57
	s_nop 0
	global_load_lds_dwordx4 v[8:9], off
	v_lshl_add_u64 v[8:9], s[8:9], 0, v[136:137]
	s_mov_b32 m0, s59
	s_nop 0
	global_load_lds_dwordx4 v[8:9], off
	v_lshl_add_u64 v[8:9], v[182:183], 0, s[14:15]
	s_mov_b32 m0, s52
	s_nop 0
	global_load_lds_dwordx4 v[8:9], off
	v_lshl_add_u64 v[8:9], v[178:179], 0, s[14:15]
	s_mov_b32 m0, s53
	s_nop 0
	global_load_lds_dwordx4 v[8:9], off
	s_waitcnt vmcnt(8)
	s_waitcnt lgkmcnt(0)
	s_barrier
	s_setprio 1
	v_mfma_f32_16x16x32_bf16 v[0:3], v[36:39], v[52:55], v[0:3]
	v_mfma_f32_16x16x32_bf16 v[64:67], v[150:153], v[158:161], v[0:3]
	v_mfma_f32_16x16x32_bf16 v[0:3], v[168:171], v[52:55], v[4:7]
	v_mfma_f32_16x16x32_bf16 v[60:63], v[230:233], v[158:161], v[0:3]
	v_mfma_f32_16x16x32_bf16 v[0:3], v[36:39], v[186:189], v[172:175]
	v_mfma_f32_16x16x32_bf16 v[48:51], v[150:153], v[190:193], v[0:3]
	v_mfma_f32_16x16x32_bf16 v[0:3], v[168:171], v[186:189], v[198:201]
	v_mfma_f32_16x16x32_bf16 v[44:47], v[230:233], v[190:193], v[0:3]
	v_mfma_f32_16x16x32_bf16 v[0:3], v[36:39], v[210:213], v[202:205]
	v_mfma_f32_16x16x32_bf16 v[32:35], v[150:153], v[218:221], v[0:3]
	v_mfma_f32_16x16x32_bf16 v[0:3], v[168:171], v[210:213], v[206:209]
	v_mfma_f32_16x16x32_bf16 v[28:31], v[230:233], v[218:221], v[0:3]
	v_mfma_f32_16x16x32_bf16 v[0:3], v[36:39], v[246:249], v[12:15]
	v_mfma_f32_16x16x32_bf16 v[12:15], v[150:153], v[162:165], v[0:3]
	v_mfma_f32_16x16x32_bf16 v[0:3], v[168:171], v[246:249], v[20:23]
	v_mfma_f32_16x16x32_bf16 v[8:11], v[230:233], v[162:165], v[0:3]
	s_setprio 0
	s_setprio 1
	v_mfma_f32_16x16x32_bf16 v[0:3], v[234:237], v[52:55], v[24:27]
	v_mfma_f32_16x16x32_bf16 v[56:59], v[238:241], v[158:161], v[0:3]
	v_mfma_f32_16x16x32_bf16 v[0:3], v[250:253], v[52:55], v[138:141]
	v_mfma_f32_16x16x32_bf16 v[52:55], v[154:157], v[158:161], v[0:3]
	v_mfma_f32_16x16x32_bf16 v[0:3], v[234:237], v[186:189], v[40:43]
	v_mfma_f32_16x16x32_bf16 v[40:43], v[238:241], v[190:193], v[0:3]
	v_mfma_f32_16x16x32_bf16 v[0:3], v[250:253], v[186:189], v[222:225]
	v_mfma_f32_16x16x32_bf16 v[36:39], v[154:157], v[190:193], v[0:3]
	v_mfma_f32_16x16x32_bf16 v[0:3], v[234:237], v[210:213], v[242:245]
	v_mfma_f32_16x16x32_bf16 v[24:27], v[238:241], v[218:221], v[0:3]
	v_mfma_f32_16x16x32_bf16 v[0:3], v[250:253], v[210:213], v[226:229]
	v_mfma_f32_16x16x32_bf16 v[20:23], v[154:157], v[218:221], v[0:3]
	v_mfma_f32_16x16x32_bf16 v[0:3], v[234:237], v[246:249], v[142:145]
	v_mfma_f32_16x16x32_bf16 v[4:7], v[238:241], v[162:165], v[0:3]
	v_mfma_f32_16x16x32_bf16 v[0:3], v[250:253], v[246:249], v[146:149]
	v_mfma_f32_16x16x32_bf16 v[0:3], v[154:157], v[162:165], v[0:3]
	s_setprio 0
	s_barrier
	s_andn2_b64 vcc, exec, s[62:63]
	s_cbranch_vccnz .LBB0_629
	s_barrier

; #define PG8_STAGE(bufoff, gbase, voff) do { _Pragma("unroll") for (int _i = 0; _i < 2; ++_i) \
;         __builtin_amdgcn_global_load_lds((const unsigned*)((const char*)(gbase) + (voff)[_i]), (LAS unsigned*)(lds + (bufoff) + ldsw + _i * 8192), 16, 0, 0); } while (0)
; #define PG8_LDA(dst, b, h) do { _Pragma("unroll") for (int m = 0; m < 4; ++m) _Pragma("unroll") for (int k = 0; k < 2; ++k) dst[m][k] = *(const LAS bf16x8*)(lds + PG8_SA(b, h) + aoff + m * 2048 + k * 1024); } while (0)
; #define PG8_LDB(dst, b, h) do { _Pragma("unroll") for (int n = 0; n < 2; ++n) _Pragma("unroll") for (int k = 0; k < 2; ++k) dst[n][k] = *(const LAS bf16x8*)(lds + PG8_SB(b, h) + boff + n * 2048 + k * 1024); } while (0)
; #define PG8_MMA(ai, bj, At, Bt) do { __builtin_amdgcn_s_setprio(1); _Pragma("unroll") for (int m = 0; m < 4; ++m) _Pragma("unroll") for (int n = 0; n < 2; ++n) _Pragma("unroll") for (int k = 0; k < 2; ++k) \
;         acc[ai][bj][m][n] = __builtin_amdgcn_mfma_f32_16x16x32_bf16(Bt[n][k], At[m][k], acc[ai][bj][m][n], 0, 0, 0); __builtin_amdgcn_s_setprio(0); } while (0)
; #define PG8_WAIT_V(n) asm volatile("s_waitcnt vmcnt(" #n ")" ::: "memory")
; #define PG8_WAIT_L(n) asm volatile("s_waitcnt lgkmcnt(" #n ")" ::: "memory")
; #define PG8_BAR __builtin_amdgcn_s_barrier()
; template <class Epi, class Sched, bool ALIGN_EPI = true, bool SP2 = true>
; __device__ __forceinline__ void gemm_phase(LAS unsigned char* lds, const Gemm g, const Sched& S, const Epi& E) {
;     ...
;         for (int t = 0; t < nt; t += 2) {
;             const bool last = (t == nt - 2);
;             const char* a1 = cA + (size_t)(t + 1) * kstep;
;             const char* a2 = last ? nA : cA + (size_t)(t + 2) * kstep; const char* b2 = last ? nB : cB + (size_t)(t + 2) * kstep;
;             const char* a3 = a2 + kstep; const char* b3 = b2 + kstep;
;             PG8_LDB(B0, 0, 0); PG8_LDB(B1, 0, 1); PG8_SCHED; PG8_LDA(At, 0, 0); PG8_STAGE(PG8_SA(1, 1), a1 + hstepA, voffA);
;             PG8_WAIT_V(8); PG8_WAIT_L(0); PG8_BAR; PG8_MMA(0, 0, At, B0); PG8_MMA(0, 1, At, B1); PG8_BAR; PG8_SCHED;
;             PG8_LDA(At, 0, 1); PG8_STAGE(PG8_SB(0, 0), b2, voffB); PG8_STAGE(PG8_SB(0, 1), b2 + hstepB, voffB); PG8_STAGE(PG8_SA(0, 0), a2, voffA);
;             PG8_WAIT_V(8); PG8_WAIT_L(0); PG8_BAR; PG8_MMA(1, 0, At, B0); PG8_MMA(1, 1, At, B1); PG8_BAR; PG8_SCHED;
.LBB0_676:
	s_add_u32 s22, s50, s9
	s_addc_u32 s23, s51, 0
	s_add_u32 s30, s22, 0x100
	s_addc_u32 s38, s23, 0
	s_and_b64 s[20:21], s[18:19], exec
	s_cselect_b32 s55, s47, s38
	s_cselect_b32 s54, s46, s30
	s_add_u32 s9, s16, s9
	s_addc_u32 s20, s17, 0
	s_add_u32 s9, s9, 0x100
	s_addc_u32 s20, s20, 0
	s_add_i32 s38, 0, 0x10000
	s_and_b64 s[18:19], s[18:19], exec
	s_cselect_b32 s63, s2, s20
	s_cselect_b32 s62, s8, s9
	s_add_i32 s19, 0, 0x14000
	s_add_u32 s22, s22, 0x30080
	s_addc_u32 s23, s23, 0
	s_add_i32 s67, s38, s52
	s_add_i32 m0, s39, 0xc000
	s_add_i32 s28, s39, 0xe000
	s_add_i32 s59, s67, 0x2000
	s_add_u32 vcc_lo, s62, 0x10000
	v_add_u32_e32 v150, s38, v144
	v_add_u32_e32 v166, s19, v144
	s_addc_u32 vcc_hi, s63, 0
	s_add_i32 s66, s19, s52
	ds_read_b128 v[136:139], v150
	ds_read_b128 v[140:143], v150 offset:1024
	ds_read_b128 v[146:149], v150 offset:2048
	ds_read_b128 v[150:153], v150 offset:3072
	ds_read_b128 v[154:157], v166
	ds_read_b128 v[158:161], v166 offset:1024
	ds_read_b128 v[162:165], v166 offset:2048
	ds_read_b128 v[166:169], v166 offset:3072
	s_add_i32 s61, s66, 0x2000
	s_add_i32 s58, 0, 0x18000
	s_add_i32 s45, 0, 0x1c000
	s_add_u32 s20, s54, 0x30000
	s_addc_u32 s21, s55, 0
	s_add_i32 s30, s58, s52
	s_add_i32 s9, s30, 0x2000
	s_add_u32 s18, s62, 0x10080
	s_addc_u32 s19, s63, 0
	s_add_i32 s60, s45, s52
	s_add_i32 s38, s60, 0x2000
	v_lshl_add_u64 v[178:179], s[22:23], 0, v[134:135]
	ds_read_b128 v[170:173], v145
	ds_read_b128 v[174:177], v145 offset:1024
	ds_read_b128 v[186:189], v145 offset:2048
	ds_read_b128 v[190:193], v145 offset:3072
	ds_read_b128 v[198:201], v145 offset:4096
	ds_read_b128 v[202:205], v145 offset:5120
	ds_read_b128 v[206:209], v145 offset:6144
	ds_read_b128 v[210:213], v145 offset:7168
	global_load_lds_dwordx4 v[178:179], off
	v_lshl_add_u64 v[178:179], s[22:23], 0, v[132:133]
	s_mov_b32 m0, s28
	s_nop 0
	global_load_lds_dwordx4 v[178:179], off
	s_waitcnt vmcnt(8)
	s_waitcnt lgkmcnt(0)
	s_barrier
	s_setprio 1
	v_mfma_f32_16x16x32_bf16 v[128:131], v[136:139], v[170:173], v[128:131]
	v_mfma_f32_16x16x32_bf16 v[124:127], v[146:149], v[170:173], v[124:127]
	v_mfma_f32_16x16x32_bf16 v[112:115], v[136:139], v[186:189], v[112:115]
	v_mfma_f32_16x16x32_bf16 v[108:111], v[146:149], v[186:189], v[108:111]
	v_mfma_f32_16x16x32_bf16 v[96:99], v[136:139], v[198:201], v[96:99]
	v_mfma_f32_16x16x32_bf16 v[92:95], v[146:149], v[198:201], v[92:95]
	v_mfma_f32_16x16x32_bf16 v[80:83], v[136:139], v[206:209], v[80:83]
	v_mfma_f32_16x16x32_bf16 v[76:79], v[146:149], v[206:209], v[76:79]
	v_mfma_f32_16x16x32_bf16 v[128:131], v[140:143], v[174:177], v[128:131]
	v_mfma_f32_16x16x32_bf16 v[124:127], v[150:153], v[174:177], v[124:127]
	v_mfma_f32_16x16x32_bf16 v[112:115], v[140:143], v[190:193], v[112:115]
	v_mfma_f32_16x16x32_bf16 v[108:111], v[150:153], v[190:193], v[108:111]
	v_mfma_f32_16x16x32_bf16 v[96:99], v[140:143], v[202:205], v[96:99]
	v_mfma_f32_16x16x32_bf16 v[92:95], v[150:153], v[202:205], v[92:95]
	v_mfma_f32_16x16x32_bf16 v[80:83], v[140:143], v[210:213], v[80:83]
	v_mfma_f32_16x16x32_bf16 v[76:79], v[150:153], v[210:213], v[76:79]
	s_setprio 0
	s_setprio 1
	v_mfma_f32_16x16x32_bf16 v[120:123], v[154:157], v[170:173], v[120:123]
	v_mfma_f32_16x16x32_bf16 v[116:119], v[162:165], v[170:173], v[116:119]
	v_mfma_f32_16x16x32_bf16 v[104:107], v[154:157], v[186:189], v[104:107]
	v_mfma_f32_16x16x32_bf16 v[100:103], v[162:165], v[186:189], v[100:103]
	v_mfma_f32_16x16x32_bf16 v[88:91], v[154:157], v[198:201], v[88:91]
	v_mfma_f32_16x16x32_bf16 v[84:87], v[162:165], v[198:201], v[84:87]
	v_mfma_f32_16x16x32_bf16 v[72:75], v[154:157], v[206:209], v[72:75]
	v_mfma_f32_16x16x32_bf16 v[68:71], v[162:165], v[206:209], v[68:71]
	v_mfma_f32_16x16x32_bf16 v[120:123], v[158:161], v[174:177], v[120:123]
	v_mfma_f32_16x16x32_bf16 v[116:119], v[166:169], v[174:177], v[116:119]
	v_mfma_f32_16x16x32_bf16 v[104:107], v[158:161], v[190:193], v[104:107]
	v_mfma_f32_16x16x32_bf16 v[100:103], v[166:169], v[190:193], v[100:103]
	v_mfma_f32_16x16x32_bf16 v[88:91], v[158:161], v[202:205], v[88:91]
	v_mfma_f32_16x16x32_bf16 v[84:87], v[166:169], v[202:205], v[84:87]
	v_mfma_f32_16x16x32_bf16 v[72:75], v[158:161], v[210:213], v[72:75]
	v_mfma_f32_16x16x32_bf16 v[68:71], v[166:169], v[210:213], v[68:71]
	s_setprio 0
	s_barrier
	s_mov_b32 m0, s67
	v_lshl_add_u64 v[178:179], s[62:63], 0, v[18:19]
	ds_read_b128 v[170:173], v145 offset:16384
	ds_read_b128 v[174:177], v145 offset:17408
	ds_read_b128 v[186:189], v145 offset:18432
	ds_read_b128 v[190:193], v145 offset:19456
	ds_read_b128 v[198:201], v145 offset:20480
	ds_read_b128 v[202:205], v145 offset:21504
	ds_read_b128 v[206:209], v145 offset:22528
	ds_read_b128 v[210:213], v145 offset:23552
	global_load_lds_dwordx4 v[178:179], off
	v_lshl_add_u64 v[182:183], s[62:63], 0, v[16:17]
	s_mov_b32 m0, s59
	v_lshl_add_u64 v[214:215], vcc, 0, v[18:19]
	global_load_lds_dwordx4 v[182:183], off
	s_mov_b32 m0, s66
	v_lshl_add_u64 v[218:219], s[54:55], 0, v[132:133]
	global_load_lds_dwordx4 v[214:215], off
	v_lshl_add_u64 v[214:215], vcc, 0, v[16:17]
	s_mov_b32 m0, s61
	s_nop 0
	global_load_lds_dwordx4 v[214:215], off
	v_lshl_add_u64 v[214:215], s[54:55], 0, v[134:135]
	s_mov_b32 m0, s39
	s_nop 0
	global_load_lds_dwordx4 v[214:215], off
	s_mov_b32 m0, s56
	s_nop 0
	global_load_lds_dwordx4 v[218:219], off
	s_waitcnt vmcnt(8)
	s_waitcnt lgkmcnt(0)
	s_barrier
; #define PG8_STAGE(bufoff, gbase, voff) do { _Pragma("unroll") for (int _i = 0; _i < 2; ++_i) \
;         __builtin_amdgcn_global_load_lds((const unsigned*)((const char*)(gbase) + (voff)[_i]), (LAS unsigned*)(lds + (bufoff) + ldsw + _i * 8192), 16, 0, 0); } while (0)
; #define PG8_LDA(dst, b, h) do { _Pragma("unroll") for (int m = 0; m < 4; ++m) _Pragma("unroll") for (int k = 0; k < 2; ++k) dst[m][k] = *(const LAS bf16x8*)(lds + PG8_SA(b, h) + aoff + m * 2048 + k * 1024); } while (0)
; #define PG8_LDB(dst, b, h) do { _Pragma("unroll") for (int n = 0; n < 2; ++n) _Pragma("unroll") for (int k = 0; k < 2; ++k) dst[n][k] = *(const LAS bf16x8*)(lds + PG8_SB(b, h) + boff + n * 2048 + k * 1024); } while (0)
; #define PG8_MMA(ai, bj, At, Bt) do { __builtin_amdgcn_s_setprio(1); _Pragma("unroll") for (int m = 0; m < 4; ++m) _Pragma("unroll") for (int n = 0; n < 2; ++n) _Pragma("unroll") for (int k = 0; k < 2; ++k) \
;         acc[ai][bj][m][n] = __builtin_amdgcn_mfma_f32_16x16x32_bf16(Bt[n][k], At[m][k], acc[ai][bj][m][n], 0, 0, 0); __builtin_amdgcn_s_setprio(0); } while (0)
; #define PG8_WAIT_V(n) asm volatile("s_waitcnt vmcnt(" #n ")" ::: "memory")
; #define PG8_WAIT_L(n) asm volatile("s_waitcnt lgkmcnt(" #n ")" ::: "memory")
; #define PG8_BAR __builtin_amdgcn_s_barrier()
; #define PG8_SCHED __builtin_amdgcn_sched_barrier(0)
; template <class Epi, class Sched, bool ALIGN_EPI = true, bool SP2 = true>
; __device__ __forceinline__ void gemm_phase(LAS unsigned char* lds, const Gemm g, const Sched& S, const Epi& E) {
;     ...
;             PG8_LDA(At, 0, 1); PG8_STAGE(PG8_SB(0, 0), b2, voffB); PG8_STAGE(PG8_SB(0, 1), b2 + hstepB, voffB); PG8_STAGE(PG8_SA(0, 0), a2, voffA);
;             PG8_WAIT_V(8); PG8_WAIT_L(0); PG8_BAR; PG8_MMA(1, 0, At, B0); PG8_MMA(1, 1, At, B1); PG8_BAR; PG8_SCHED;
;             PG8_LDB(B0, 1, 0); PG8_LDB(B1, 1, 1); PG8_SCHED; PG8_LDA(At, 1, 0); PG8_STAGE(PG8_SA(0, 1), a2 + hstepA, voffA);
;             PG8_WAIT_V(8); PG8_WAIT_L(0); PG8_BAR; PG8_MMA(0, 0, At, B0); PG8_MMA(0, 1, At, B1); PG8_BAR; PG8_SCHED;
	s_setprio 1
	v_mfma_f32_16x16x32_bf16 v[64:67], v[136:139], v[170:173], v[64:67]
	v_mfma_f32_16x16x32_bf16 v[60:63], v[146:149], v[170:173], v[60:63]
	v_mfma_f32_16x16x32_bf16 v[48:51], v[136:139], v[186:189], v[48:51]
	v_mfma_f32_16x16x32_bf16 v[44:47], v[146:149], v[186:189], v[44:47]
	v_mfma_f32_16x16x32_bf16 v[32:35], v[136:139], v[198:201], v[32:35]
	v_mfma_f32_16x16x32_bf16 v[28:31], v[146:149], v[198:201], v[28:31]
	v_mfma_f32_16x16x32_bf16 v[12:15], v[136:139], v[206:209], v[12:15]
	v_mfma_f32_16x16x32_bf16 v[8:11], v[146:149], v[206:209], v[8:11]
	v_mfma_f32_16x16x32_bf16 v[64:67], v[140:143], v[174:177], v[64:67]
	v_mfma_f32_16x16x32_bf16 v[60:63], v[150:153], v[174:177], v[60:63]
	v_mfma_f32_16x16x32_bf16 v[48:51], v[140:143], v[190:193], v[48:51]
	v_mfma_f32_16x16x32_bf16 v[44:47], v[150:153], v[190:193], v[44:47]
	v_mfma_f32_16x16x32_bf16 v[32:35], v[140:143], v[202:205], v[32:35]
	v_mfma_f32_16x16x32_bf16 v[28:31], v[150:153], v[202:205], v[28:31]
	v_mfma_f32_16x16x32_bf16 v[12:15], v[140:143], v[210:213], v[12:15]
	v_mfma_f32_16x16x32_bf16 v[8:11], v[150:153], v[210:213], v[8:11]
	s_setprio 0
	s_setprio 1
	v_mfma_f32_16x16x32_bf16 v[56:59], v[154:157], v[170:173], v[56:59]
	v_mfma_f32_16x16x32_bf16 v[52:55], v[162:165], v[170:173], v[52:55]
	v_mfma_f32_16x16x32_bf16 v[40:43], v[154:157], v[186:189], v[40:43]
	v_mfma_f32_16x16x32_bf16 v[36:39], v[162:165], v[186:189], v[36:39]
	v_mfma_f32_16x16x32_bf16 v[24:27], v[154:157], v[198:201], v[24:27]
	v_mfma_f32_16x16x32_bf16 v[20:23], v[162:165], v[198:201], v[20:23]
	v_mfma_f32_16x16x32_bf16 v[4:7], v[154:157], v[206:209], v[4:7]
	v_mfma_f32_16x16x32_bf16 v[0:3], v[162:165], v[206:209], v[0:3]
	v_mfma_f32_16x16x32_bf16 v[56:59], v[158:161], v[174:177], v[56:59]
	v_mfma_f32_16x16x32_bf16 v[52:55], v[166:169], v[174:177], v[52:55]
	v_mfma_f32_16x16x32_bf16 v[40:43], v[158:161], v[190:193], v[40:43]
	v_mfma_f32_16x16x32_bf16 v[36:39], v[166:169], v[190:193], v[36:39]
	v_mfma_f32_16x16x32_bf16 v[24:27], v[158:161], v[202:205], v[24:27]
	v_mfma_f32_16x16x32_bf16 v[20:23], v[166:169], v[202:205], v[20:23]
	v_mfma_f32_16x16x32_bf16 v[4:7], v[158:161], v[210:213], v[4:7]
	v_mfma_f32_16x16x32_bf16 v[0:3], v[166:169], v[210:213], v[0:3]
	s_setprio 0
	s_barrier
	v_add_u32_e32 v150, s58, v144
	v_add_u32_e32 v166, s45, v144
	ds_read_b128 v[136:139], v150
	ds_read_b128 v[140:143], v150 offset:1024
	ds_read_b128 v[146:149], v150 offset:2048
	ds_read_b128 v[150:153], v150 offset:3072
	ds_read_b128 v[154:157], v166
	ds_read_b128 v[158:161], v166 offset:1024
	ds_read_b128 v[162:165], v166 offset:2048
	ds_read_b128 v[166:169], v166 offset:3072
	s_mov_b32 m0, s57
	v_lshl_add_u64 v[220:221], s[20:21], 0, v[134:135]
	ds_read_b128 v[170:173], v145 offset:32768
	ds_read_b128 v[174:177], v145 offset:33792
	ds_read_b128 v[186:189], v145 offset:34816
	ds_read_b128 v[190:193], v145 offset:35840
	ds_read_b128 v[198:201], v145 offset:36864
	ds_read_b128 v[202:205], v145 offset:37888
	ds_read_b128 v[206:209], v145 offset:38912
	ds_read_b128 v[210:213], v145 offset:39936
	global_load_lds_dwordx4 v[220:221], off
	v_lshl_add_u64 v[220:221], s[20:21], 0, v[132:133]
	s_mov_b32 m0, s25
	s_nop 0
	global_load_lds_dwordx4 v[220:221], off
	s_waitcnt vmcnt(8)
	s_waitcnt lgkmcnt(0)
	s_barrier
	s_setprio 1
	v_mfma_f32_16x16x32_bf16 v[128:131], v[136:139], v[170:173], v[128:131]
	v_mfma_f32_16x16x32_bf16 v[124:127], v[146:149], v[170:173], v[124:127]
	v_mfma_f32_16x16x32_bf16 v[112:115], v[136:139], v[186:189], v[112:115]
	v_mfma_f32_16x16x32_bf16 v[108:111], v[146:149], v[186:189], v[108:111]
	v_mfma_f32_16x16x32_bf16 v[96:99], v[136:139], v[198:201], v[96:99]
	v_mfma_f32_16x16x32_bf16 v[92:95], v[146:149], v[198:201], v[92:95]
	v_mfma_f32_16x16x32_bf16 v[80:83], v[136:139], v[206:209], v[80:83]
	v_mfma_f32_16x16x32_bf16 v[76:79], v[146:149], v[206:209], v[76:79]
	v_mfma_f32_16x16x32_bf16 v[128:131], v[140:143], v[174:177], v[128:131]
	v_mfma_f32_16x16x32_bf16 v[124:127], v[150:153], v[174:177], v[124:127]
	v_mfma_f32_16x16x32_bf16 v[112:115], v[140:143], v[190:193], v[112:115]
	v_mfma_f32_16x16x32_bf16 v[108:111], v[150:153], v[190:193], v[108:111]
	v_mfma_f32_16x16x32_bf16 v[96:99], v[140:143], v[202:205], v[96:99]
	v_mfma_f32_16x16x32_bf16 v[92:95], v[150:153], v[202:205], v[92:95]
	v_mfma_f32_16x16x32_bf16 v[80:83], v[140:143], v[210:213], v[80:83]
	v_mfma_f32_16x16x32_bf16 v[76:79], v[150:153], v[210:213], v[76:79]
	s_setprio 0
	s_setprio 1
	v_mfma_f32_16x16x32_bf16 v[120:123], v[154:157], v[170:173], v[120:123]
	v_mfma_f32_16x16x32_bf16 v[116:119], v[162:165], v[170:173], v[116:119]
	v_mfma_f32_16x16x32_bf16 v[104:107], v[154:157], v[186:189], v[104:107]
	v_mfma_f32_16x16x32_bf16 v[100:103], v[162:165], v[186:189], v[100:103]
	v_mfma_f32_16x16x32_bf16 v[88:91], v[154:157], v[198:201], v[88:91]
	v_mfma_f32_16x16x32_bf16 v[84:87], v[162:165], v[198:201], v[84:87]
	v_mfma_f32_16x16x32_bf16 v[72:75], v[154:157], v[206:209], v[72:75]
	v_mfma_f32_16x16x32_bf16 v[68:71], v[162:165], v[206:209], v[68:71]
	v_mfma_f32_16x16x32_bf16 v[120:123], v[158:161], v[174:177], v[120:123]
	v_mfma_f32_16x16x32_bf16 v[116:119], v[166:169], v[174:177], v[116:119]
	v_mfma_f32_16x16x32_bf16 v[104:107], v[158:161], v[190:193], v[104:107]
	v_mfma_f32_16x16x32_bf16 v[100:103], v[166:169], v[190:193], v[100:103]
	v_mfma_f32_16x16x32_bf16 v[88:91], v[158:161], v[202:205], v[88:91]
	v_mfma_f32_16x16x32_bf16 v[84:87], v[166:169], v[202:205], v[84:87]
	v_mfma_f32_16x16x32_bf16 v[72:75], v[158:161], v[210:213], v[72:75]
	v_mfma_f32_16x16x32_bf16 v[68:71], v[166:169], v[210:213], v[68:71]
	s_setprio 0
	s_barrier
; #define PG8_STAGE(bufoff, gbase, voff) do { _Pragma("unroll") for (int _i = 0; _i < 2; ++_i) \
;         __builtin_amdgcn_global_load_lds((const unsigned*)((const char*)(gbase) + (voff)[_i]), (LAS unsigned*)(lds + (bufoff) + ldsw + _i * 8192), 16, 0, 0); } while (0)
; #define PG8_LDA(dst, b, h) do { _Pragma("unroll") for (int m = 0; m < 4; ++m) _Pragma("unroll") for (int k = 0; k < 2; ++k) dst[m][k] = *(const LAS bf16x8*)(lds + PG8_SA(b, h) + aoff + m * 2048 + k * 1024); } while (0)
; #define PG8_MMA(ai, bj, At, Bt) do { __builtin_amdgcn_s_setprio(1); _Pragma("unroll") for (int m = 0; m < 4; ++m) _Pragma("unroll") for (int n = 0; n < 2; ++n) _Pragma("unroll") for (int k = 0; k < 2; ++k) \
;         acc[ai][bj][m][n] = __builtin_amdgcn_mfma_f32_16x16x32_bf16(Bt[n][k], At[m][k], acc[ai][bj][m][n], 0, 0, 0); __builtin_amdgcn_s_setprio(0); } while (0)
; #define PG8_WAIT_V(n) asm volatile("s_waitcnt vmcnt(" #n ")" ::: "memory")
; #define PG8_WAIT_L(n) asm volatile("s_waitcnt lgkmcnt(" #n ")" ::: "memory")
; #define PG8_BAR __builtin_amdgcn_s_barrier()
; #define PG8_SCHED __builtin_amdgcn_sched_barrier(0)
; template <class Epi, class Sched, bool ALIGN_EPI = true, bool SP2 = true>
; __device__ __forceinline__ void gemm_phase(LAS unsigned char* lds, const Gemm g, const Sched& S, const Epi& E) {
;     ...
;             PG8_LDA(At, 1, 1); PG8_STAGE(PG8_SB(1, 0), b3, voffB); PG8_STAGE(PG8_SB(1, 1), b3 + hstepB, voffB); PG8_STAGE(PG8_SA(1, 0), a3, voffA);
;             PG8_WAIT_V(8); PG8_WAIT_L(0); PG8_BAR; PG8_MMA(1, 0, At, B0); PG8_MMA(1, 1, At, B1); PG8_BAR; PG8_SCHED;
;         }
;         if constexpr (ALIGN_EPI) { if (wr == 0) PG8_BAR; }
	s_mov_b32 m0, s30
	v_lshl_add_u64 v[178:179], v[178:179], 0, s[14:15]
	ds_read_b128 v[170:173], v145 offset:49152
	ds_read_b128 v[174:177], v145 offset:50176
	ds_read_b128 v[186:189], v145 offset:51200
	ds_read_b128 v[190:193], v145 offset:52224
	ds_read_b128 v[198:201], v145 offset:53248
	ds_read_b128 v[202:205], v145 offset:54272
	ds_read_b128 v[206:209], v145 offset:55296
	ds_read_b128 v[210:213], v145 offset:56320
	global_load_lds_dwordx4 v[178:179], off
	v_lshl_add_u64 v[178:179], v[182:183], 0, s[14:15]
	s_mov_b32 m0, s9
	s_nop 0
	global_load_lds_dwordx4 v[178:179], off
	v_lshl_add_u64 v[178:179], s[18:19], 0, v[18:19]
	s_mov_b32 m0, s60
	s_nop 0
	global_load_lds_dwordx4 v[178:179], off
	v_lshl_add_u64 v[178:179], s[18:19], 0, v[16:17]
	s_mov_b32 m0, s38
	s_nop 0
	global_load_lds_dwordx4 v[178:179], off
	v_lshl_add_u64 v[178:179], v[214:215], 0, s[14:15]
	s_mov_b32 m0, s31
	s_nop 0
	global_load_lds_dwordx4 v[178:179], off
	v_lshl_add_u64 v[178:179], v[218:219], 0, s[14:15]
	s_mov_b32 m0, s6
	s_nop 0
	global_load_lds_dwordx4 v[178:179], off
	s_waitcnt vmcnt(8)
	s_waitcnt lgkmcnt(0)
	s_barrier
	s_setprio 1
	v_mfma_f32_16x16x32_bf16 v[64:67], v[136:139], v[170:173], v[64:67]
	v_mfma_f32_16x16x32_bf16 v[60:63], v[146:149], v[170:173], v[60:63]
	v_mfma_f32_16x16x32_bf16 v[48:51], v[136:139], v[186:189], v[48:51]
	v_mfma_f32_16x16x32_bf16 v[44:47], v[146:149], v[186:189], v[44:47]
	v_mfma_f32_16x16x32_bf16 v[32:35], v[136:139], v[198:201], v[32:35]
	v_mfma_f32_16x16x32_bf16 v[28:31], v[146:149], v[198:201], v[28:31]
	v_mfma_f32_16x16x32_bf16 v[12:15], v[136:139], v[206:209], v[12:15]
	v_mfma_f32_16x16x32_bf16 v[8:11], v[146:149], v[206:209], v[8:11]
	v_mfma_f32_16x16x32_bf16 v[64:67], v[140:143], v[174:177], v[64:67]
	v_mfma_f32_16x16x32_bf16 v[60:63], v[150:153], v[174:177], v[60:63]
	v_mfma_f32_16x16x32_bf16 v[48:51], v[140:143], v[190:193], v[48:51]
	v_mfma_f32_16x16x32_bf16 v[44:47], v[150:153], v[190:193], v[44:47]
	v_mfma_f32_16x16x32_bf16 v[32:35], v[140:143], v[202:205], v[32:35]
	v_mfma_f32_16x16x32_bf16 v[28:31], v[150:153], v[202:205], v[28:31]
	v_mfma_f32_16x16x32_bf16 v[12:15], v[140:143], v[210:213], v[12:15]
	v_mfma_f32_16x16x32_bf16 v[8:11], v[150:153], v[210:213], v[8:11]
	s_setprio 0
	s_setprio 1
	v_mfma_f32_16x16x32_bf16 v[56:59], v[154:157], v[170:173], v[56:59]
	v_mfma_f32_16x16x32_bf16 v[52:55], v[162:165], v[170:173], v[52:55]
	v_mfma_f32_16x16x32_bf16 v[40:43], v[154:157], v[186:189], v[40:43]
	v_mfma_f32_16x16x32_bf16 v[36:39], v[162:165], v[186:189], v[36:39]
	v_mfma_f32_16x16x32_bf16 v[24:27], v[154:157], v[198:201], v[24:27]
	v_mfma_f32_16x16x32_bf16 v[20:23], v[162:165], v[198:201], v[20:23]
	v_mfma_f32_16x16x32_bf16 v[4:7], v[154:157], v[206:209], v[4:7]
	v_mfma_f32_16x16x32_bf16 v[0:3], v[162:165], v[206:209], v[0:3]
	v_mfma_f32_16x16x32_bf16 v[56:59], v[158:161], v[174:177], v[56:59]
	v_mfma_f32_16x16x32_bf16 v[52:55], v[166:169], v[174:177], v[52:55]
	v_mfma_f32_16x16x32_bf16 v[40:43], v[158:161], v[190:193], v[40:43]
	v_mfma_f32_16x16x32_bf16 v[36:39], v[166:169], v[190:193], v[36:39]
	v_mfma_f32_16x16x32_bf16 v[24:27], v[158:161], v[202:205], v[24:27]
	v_mfma_f32_16x16x32_bf16 v[20:23], v[166:169], v[202:205], v[20:23]
	v_mfma_f32_16x16x32_bf16 v[4:7], v[158:161], v[210:213], v[4:7]
	v_mfma_f32_16x16x32_bf16 v[0:3], v[166:169], v[210:213], v[0:3]
	s_setprio 0
	s_barrier
	s_movk_i32 s9, 0x100
	s_andn2_b64 vcc, exec, s[42:43]
	s_mov_b64 s[18:19], -1
	s_mov_b64 s[42:43], 0
	s_cbranch_vccz .LBB0_676
	s_and_b64 vcc, exec, s[34:35]
	s_cbranch_vccz .LBB0_679
	s_barrier

; #define PG8_STAGE(bufoff, gbase, voff) do { _Pragma("unroll") for (int _i = 0; _i < 2; ++_i) \
;         __builtin_amdgcn_global_load_lds((const unsigned*)((const char*)(gbase) + (voff)[_i]), (LAS unsigned*)(lds + (bufoff) + ldsw + _i * 8192), 16, 0, 0); } while (0)
; #define PG8_LDA(dst, b, h) do { _Pragma("unroll") for (int m = 0; m < 4; ++m) _Pragma("unroll") for (int k = 0; k < 2; ++k) dst[m][k] = *(const LAS bf16x8*)(lds + PG8_SA(b, h) + aoff + m * 2048 + k * 1024); } while (0)
; #define PG8_LDB(dst, b, h) do { _Pragma("unroll") for (int n = 0; n < 2; ++n) _Pragma("unroll") for (int k = 0; k < 2; ++k) dst[n][k] = *(const LAS bf16x8*)(lds + PG8_SB(b, h) + boff + n * 2048 + k * 1024); } while (0)
; #define PG8_MMA(ai, bj, At, Bt) do { __builtin_amdgcn_s_setprio(1); _Pragma("unroll") for (int m = 0; m < 4; ++m) _Pragma("unroll") for (int n = 0; n < 2; ++n) _Pragma("unroll") for (int k = 0; k < 2; ++k) \
;         acc[ai][bj][m][n] = __builtin_amdgcn_mfma_f32_16x16x32_bf16(Bt[n][k], At[m][k], acc[ai][bj][m][n], 0, 0, 0); __builtin_amdgcn_s_setprio(0); } while (0)
; #define PG8_WAIT_V(n) asm volatile("s_waitcnt vmcnt(" #n ")" ::: "memory")
; #define PG8_WAIT_L(n) asm volatile("s_waitcnt lgkmcnt(" #n ")" ::: "memory")
; #define PG8_BAR __builtin_amdgcn_s_barrier()
; template <class Epi, class Sched, bool ALIGN_EPI = true, bool SP2 = true>
; __device__ __forceinline__ void gemm_phase(LAS unsigned char* lds, const Gemm g, const Sched& S, const Epi& E) {
;     ...
;         for (int t = 0; t < nt; t += 2) {
;             const bool last = (t == nt - 2);
;             const char* a1 = cA + (size_t)(t + 1) * kstep;
;             const char* a2 = last ? nA : cA + (size_t)(t + 2) * kstep; const char* b2 = last ? nB : cB + (size_t)(t + 2) * kstep;
;             const char* a3 = a2 + kstep; const char* b3 = b2 + kstep;
;             PG8_LDB(B0, 0, 0); PG8_LDB(B1, 0, 1); PG8_SCHED; PG8_LDA(At, 0, 0); PG8_STAGE(PG8_SA(1, 1), a1 + hstepA, voffA);
;             PG8_WAIT_V(8); PG8_WAIT_L(0); PG8_BAR; PG8_MMA(0, 0, At, B0); PG8_MMA(0, 1, At, B1); PG8_BAR; PG8_SCHED;
;             PG8_LDA(At, 0, 1); PG8_STAGE(PG8_SB(0, 0), b2, voffB); PG8_STAGE(PG8_SB(0, 1), b2 + hstepB, voffB); PG8_STAGE(PG8_SA(0, 0), a2, voffA);
;             PG8_WAIT_V(8); PG8_WAIT_L(0); PG8_BAR; PG8_MMA(1, 0, At, B0); PG8_MMA(1, 1, At, B1); PG8_BAR; PG8_SCHED;
.LBB0_884:
	s_add_u32 s18, s54, 0xfffc0080
	s_addc_u32 s19, s55, -1
	s_add_i32 s58, 0, 0x10000
	s_cmp_eq_u32 s49, 12
	s_cselect_b32 s21, s22, s19
	s_cselect_b32 s20, s23, s18
	v_add_u32_e32 v140, s58, v142
	s_cselect_b32 s19, s2, s45
	s_cselect_b32 s18, s43, s30
	s_add_i32 s61, 0, 0x14000
	ds_read_b128 v[144:147], v140
	ds_read_b128 v[148:151], v140 offset:1024
	ds_read_b128 v[152:155], v140 offset:2048
	ds_read_b128 v[156:159], v140 offset:3072
	v_add_u32_e32 v140, s61, v142
	ds_read_b128 v[160:163], v140
	ds_read_b128 v[164:167], v140 offset:1024
	ds_read_b128 v[168:171], v140 offset:2048
	ds_read_b128 v[172:175], v140 offset:3072
	v_lshl_add_u64 v[140:141], s[54:55], 0, v[136:137]
	s_add_i32 m0, s53, 0xc000
	ds_read_b128 v[186:189], v143
	ds_read_b128 v[190:193], v143 offset:1024
	ds_read_b128 v[198:201], v143 offset:2048
	ds_read_b128 v[202:205], v143 offset:3072
	ds_read_b128 v[206:209], v143 offset:4096
	ds_read_b128 v[210:213], v143 offset:5120
	ds_read_b128 v[218:221], v143 offset:6144
	ds_read_b128 v[222:225], v143 offset:7168
	global_load_lds_dwordx4 v[140:141], off
	v_lshl_add_u64 v[140:141], s[54:55], 0, v[138:139]
	s_add_i32 m0, s53, 0xe000
	s_nop 0
	global_load_lds_dwordx4 v[140:141], off
	s_waitcnt vmcnt(8)
	s_waitcnt lgkmcnt(0)
	s_barrier
	s_setprio 1
	v_mfma_f32_16x16x32_bf16 v[128:131], v[144:147], v[186:189], v[128:131]
	v_mfma_f32_16x16x32_bf16 v[124:127], v[152:155], v[186:189], v[124:127]
	v_mfma_f32_16x16x32_bf16 v[120:123], v[144:147], v[198:201], v[120:123]
	v_mfma_f32_16x16x32_bf16 v[112:115], v[152:155], v[198:201], v[112:115]
	v_mfma_f32_16x16x32_bf16 v[104:107], v[144:147], v[206:209], v[104:107]
	v_mfma_f32_16x16x32_bf16 v[96:99], v[152:155], v[206:209], v[96:99]
	v_mfma_f32_16x16x32_bf16 v[88:91], v[144:147], v[218:221], v[88:91]
	v_mfma_f32_16x16x32_bf16 v[80:83], v[152:155], v[218:221], v[80:83]
	v_mfma_f32_16x16x32_bf16 v[128:131], v[148:151], v[190:193], v[128:131]
	v_mfma_f32_16x16x32_bf16 v[124:127], v[156:159], v[190:193], v[124:127]
	v_mfma_f32_16x16x32_bf16 v[120:123], v[148:151], v[202:205], v[120:123]
	v_mfma_f32_16x16x32_bf16 v[112:115], v[156:159], v[202:205], v[112:115]
	v_mfma_f32_16x16x32_bf16 v[104:107], v[148:151], v[210:213], v[104:107]
	v_mfma_f32_16x16x32_bf16 v[96:99], v[156:159], v[210:213], v[96:99]
	v_mfma_f32_16x16x32_bf16 v[88:91], v[148:151], v[222:225], v[88:91]
	v_mfma_f32_16x16x32_bf16 v[80:83], v[156:159], v[222:225], v[80:83]
	s_setprio 0
	s_setprio 1
	v_mfma_f32_16x16x32_bf16 v[116:119], v[160:163], v[186:189], v[116:119]
	v_mfma_f32_16x16x32_bf16 v[108:111], v[168:171], v[186:189], v[108:111]
	v_mfma_f32_16x16x32_bf16 v[100:103], v[160:163], v[198:201], v[100:103]
	v_mfma_f32_16x16x32_bf16 v[92:95], v[168:171], v[198:201], v[92:95]
	v_mfma_f32_16x16x32_bf16 v[84:87], v[160:163], v[206:209], v[84:87]
	v_mfma_f32_16x16x32_bf16 v[76:79], v[168:171], v[206:209], v[76:79]
	v_mfma_f32_16x16x32_bf16 v[72:75], v[160:163], v[218:221], v[72:75]
	v_mfma_f32_16x16x32_bf16 v[68:71], v[168:171], v[218:221], v[68:71]
	v_mfma_f32_16x16x32_bf16 v[116:119], v[164:167], v[190:193], v[116:119]
	v_mfma_f32_16x16x32_bf16 v[108:111], v[172:175], v[190:193], v[108:111]
	v_mfma_f32_16x16x32_bf16 v[100:103], v[164:167], v[202:205], v[100:103]
	v_mfma_f32_16x16x32_bf16 v[92:95], v[172:175], v[202:205], v[92:95]
	v_mfma_f32_16x16x32_bf16 v[84:87], v[164:167], v[210:213], v[84:87]
	v_mfma_f32_16x16x32_bf16 v[76:79], v[172:175], v[210:213], v[76:79]
	v_mfma_f32_16x16x32_bf16 v[72:75], v[164:167], v[222:225], v[72:75]
	v_mfma_f32_16x16x32_bf16 v[68:71], v[172:175], v[222:225], v[68:71]
	s_setprio 0
	s_barrier
	s_add_i32 s58, s58, s39
	v_lshl_add_u64 v[140:141], s[18:19], 0, v[18:19]
	s_mov_b32 m0, s58
	ds_read_b128 v[186:189], v143 offset:16384
	ds_read_b128 v[190:193], v143 offset:17408
	ds_read_b128 v[198:201], v143 offset:18432
	ds_read_b128 v[202:205], v143 offset:19456
	ds_read_b128 v[206:209], v143 offset:20480
	ds_read_b128 v[210:213], v143 offset:21504
	ds_read_b128 v[218:221], v143 offset:22528
	ds_read_b128 v[222:225], v143 offset:23552
	global_load_lds_dwordx4 v[140:141], off
	s_add_i32 m0, s58, 0x2000
	s_add_u32 s58, s18, 0x40000
	v_lshl_add_u64 v[176:177], s[18:19], 0, v[16:17]
	s_addc_u32 s59, s19, 0
	s_add_i32 s61, s61, s39
	global_load_lds_dwordx4 v[176:177], off
	v_lshl_add_u64 v[178:179], s[58:59], 0, v[18:19]
	s_mov_b32 m0, s61
	v_lshl_add_u64 v[182:183], s[20:21], 0, v[132:133]
	global_load_lds_dwordx4 v[178:179], off
	v_lshl_add_u64 v[178:179], s[58:59], 0, v[16:17]
	s_add_i32 m0, s61, 0x2000
	s_nop 0
	global_load_lds_dwordx4 v[178:179], off
	v_lshl_add_u64 v[178:179], s[20:21], 0, v[134:135]
	s_mov_b32 m0, s53
	s_nop 0
	global_load_lds_dwordx4 v[178:179], off
	s_mov_b32 m0, s56
	s_nop 0
	global_load_lds_dwordx4 v[182:183], off
	s_waitcnt vmcnt(8)
	s_waitcnt lgkmcnt(0)
	s_barrier
; #define PG8_STAGE(bufoff, gbase, voff) do { _Pragma("unroll") for (int _i = 0; _i < 2; ++_i) \
;         __builtin_amdgcn_global_load_lds((const unsigned*)((const char*)(gbase) + (voff)[_i]), (LAS unsigned*)(lds + (bufoff) + ldsw + _i * 8192), 16, 0, 0); } while (0)
; #define PG8_LDA(dst, b, h) do { _Pragma("unroll") for (int m = 0; m < 4; ++m) _Pragma("unroll") for (int k = 0; k < 2; ++k) dst[m][k] = *(const LAS bf16x8*)(lds + PG8_SA(b, h) + aoff + m * 2048 + k * 1024); } while (0)
; #define PG8_LDB(dst, b, h) do { _Pragma("unroll") for (int n = 0; n < 2; ++n) _Pragma("unroll") for (int k = 0; k < 2; ++k) dst[n][k] = *(const LAS bf16x8*)(lds + PG8_SB(b, h) + boff + n * 2048 + k * 1024); } while (0)
; #define PG8_MMA(ai, bj, At, Bt) do { __builtin_amdgcn_s_setprio(1); _Pragma("unroll") for (int m = 0; m < 4; ++m) _Pragma("unroll") for (int n = 0; n < 2; ++n) _Pragma("unroll") for (int k = 0; k < 2; ++k) \
;         acc[ai][bj][m][n] = __builtin_amdgcn_mfma_f32_16x16x32_bf16(Bt[n][k], At[m][k], acc[ai][bj][m][n], 0, 0, 0); __builtin_amdgcn_s_setprio(0); } while (0)
; #define PG8_WAIT_V(n) asm volatile("s_waitcnt vmcnt(" #n ")" ::: "memory")
; #define PG8_WAIT_L(n) asm volatile("s_waitcnt lgkmcnt(" #n ")" ::: "memory")
; #define PG8_BAR __builtin_amdgcn_s_barrier()
; #define PG8_SCHED __builtin_amdgcn_sched_barrier(0)
; template <class Epi, class Sched, bool ALIGN_EPI = true, bool SP2 = true>
; __device__ __forceinline__ void gemm_phase(LAS unsigned char* lds, const Gemm g, const Sched& S, const Epi& E) {
;     ...
;             PG8_LDA(At, 0, 1); PG8_STAGE(PG8_SB(0, 0), b2, voffB); PG8_STAGE(PG8_SB(0, 1), b2 + hstepB, voffB); PG8_STAGE(PG8_SA(0, 0), a2, voffA);
;             PG8_WAIT_V(8); PG8_WAIT_L(0); PG8_BAR; PG8_MMA(1, 0, At, B0); PG8_MMA(1, 1, At, B1); PG8_BAR; PG8_SCHED;
;             PG8_LDB(B0, 1, 0); PG8_LDB(B1, 1, 1); PG8_SCHED; PG8_LDA(At, 1, 0); PG8_STAGE(PG8_SA(0, 1), a2 + hstepA, voffA);
;             PG8_WAIT_V(8); PG8_WAIT_L(0); PG8_BAR; PG8_MMA(0, 0, At, B0); PG8_MMA(0, 1, At, B1); PG8_BAR; PG8_SCHED;
	s_setprio 1
	v_mfma_f32_16x16x32_bf16 v[64:67], v[144:147], v[186:189], v[64:67]
	v_mfma_f32_16x16x32_bf16 v[60:63], v[152:155], v[186:189], v[60:63]
	v_mfma_f32_16x16x32_bf16 v[56:59], v[144:147], v[198:201], v[56:59]
	v_mfma_f32_16x16x32_bf16 v[48:51], v[152:155], v[198:201], v[48:51]
	v_mfma_f32_16x16x32_bf16 v[40:43], v[144:147], v[206:209], v[40:43]
	v_mfma_f32_16x16x32_bf16 v[32:35], v[152:155], v[206:209], v[32:35]
	v_mfma_f32_16x16x32_bf16 v[24:27], v[144:147], v[218:221], v[24:27]
	v_mfma_f32_16x16x32_bf16 v[12:15], v[152:155], v[218:221], v[12:15]
	v_mfma_f32_16x16x32_bf16 v[64:67], v[148:151], v[190:193], v[64:67]
	v_mfma_f32_16x16x32_bf16 v[60:63], v[156:159], v[190:193], v[60:63]
	v_mfma_f32_16x16x32_bf16 v[56:59], v[148:151], v[202:205], v[56:59]
	v_mfma_f32_16x16x32_bf16 v[48:51], v[156:159], v[202:205], v[48:51]
	v_mfma_f32_16x16x32_bf16 v[40:43], v[148:151], v[210:213], v[40:43]
	v_mfma_f32_16x16x32_bf16 v[32:35], v[156:159], v[210:213], v[32:35]
	v_mfma_f32_16x16x32_bf16 v[24:27], v[148:151], v[222:225], v[24:27]
	v_mfma_f32_16x16x32_bf16 v[12:15], v[156:159], v[222:225], v[12:15]
	s_setprio 0
	s_setprio 1
	v_mfma_f32_16x16x32_bf16 v[52:55], v[160:163], v[186:189], v[52:55]
	v_mfma_f32_16x16x32_bf16 v[44:47], v[168:171], v[186:189], v[44:47]
	v_mfma_f32_16x16x32_bf16 v[36:39], v[160:163], v[198:201], v[36:39]
	v_mfma_f32_16x16x32_bf16 v[28:31], v[168:171], v[198:201], v[28:31]
	v_mfma_f32_16x16x32_bf16 v[20:23], v[160:163], v[206:209], v[20:23]
	v_mfma_f32_16x16x32_bf16 v[8:11], v[168:171], v[206:209], v[8:11]
	v_mfma_f32_16x16x32_bf16 v[4:7], v[160:163], v[218:221], v[4:7]
	v_mfma_f32_16x16x32_bf16 v[0:3], v[168:171], v[218:221], v[0:3]
	v_mfma_f32_16x16x32_bf16 v[52:55], v[164:167], v[190:193], v[52:55]
	v_mfma_f32_16x16x32_bf16 v[44:47], v[172:175], v[190:193], v[44:47]
	v_mfma_f32_16x16x32_bf16 v[36:39], v[164:167], v[202:205], v[36:39]
	v_mfma_f32_16x16x32_bf16 v[28:31], v[172:175], v[202:205], v[28:31]
	v_mfma_f32_16x16x32_bf16 v[20:23], v[164:167], v[210:213], v[20:23]
	v_mfma_f32_16x16x32_bf16 v[8:11], v[172:175], v[210:213], v[8:11]
	v_mfma_f32_16x16x32_bf16 v[4:7], v[164:167], v[222:225], v[4:7]
	v_mfma_f32_16x16x32_bf16 v[0:3], v[172:175], v[222:225], v[0:3]
	s_setprio 0
	s_barrier
	s_add_i32 s58, 0, 0x18000
	s_add_i32 s59, 0, 0x1c000
	v_add_u32_e32 v156, s58, v142
	v_add_u32_e32 v172, s59, v142
	ds_read_b128 v[144:147], v156
	ds_read_b128 v[148:151], v156 offset:1024
	ds_read_b128 v[152:155], v156 offset:2048
	ds_read_b128 v[156:159], v156 offset:3072
	ds_read_b128 v[160:163], v172
	ds_read_b128 v[164:167], v172 offset:1024
	ds_read_b128 v[168:171], v172 offset:2048
	ds_read_b128 v[172:175], v172 offset:3072
	s_add_u32 s20, s20, 0x40000
	s_addc_u32 s21, s21, 0
	s_mov_b32 m0, s57
	v_lshl_add_u64 v[214:215], s[20:21], 0, v[134:135]
	ds_read_b128 v[186:189], v143 offset:32768
	ds_read_b128 v[190:193], v143 offset:33792
	ds_read_b128 v[198:201], v143 offset:34816
	ds_read_b128 v[202:205], v143 offset:35840
	ds_read_b128 v[206:209], v143 offset:36864
	ds_read_b128 v[210:213], v143 offset:37888
	ds_read_b128 v[218:221], v143 offset:38912
	ds_read_b128 v[222:225], v143 offset:39936
	global_load_lds_dwordx4 v[214:215], off
	v_lshl_add_u64 v[214:215], s[20:21], 0, v[132:133]
	s_mov_b32 m0, s60
	s_nop 0
	global_load_lds_dwordx4 v[214:215], off
	s_waitcnt vmcnt(8)
	s_waitcnt lgkmcnt(0)
	s_barrier
	s_setprio 1
	v_mfma_f32_16x16x32_bf16 v[128:131], v[144:147], v[186:189], v[128:131]
	v_mfma_f32_16x16x32_bf16 v[124:127], v[152:155], v[186:189], v[124:127]
	v_mfma_f32_16x16x32_bf16 v[120:123], v[144:147], v[198:201], v[120:123]
	v_mfma_f32_16x16x32_bf16 v[112:115], v[152:155], v[198:201], v[112:115]
	v_mfma_f32_16x16x32_bf16 v[104:107], v[144:147], v[206:209], v[104:107]
	v_mfma_f32_16x16x32_bf16 v[96:99], v[152:155], v[206:209], v[96:99]
	v_mfma_f32_16x16x32_bf16 v[88:91], v[144:147], v[218:221], v[88:91]
	v_mfma_f32_16x16x32_bf16 v[80:83], v[152:155], v[218:221], v[80:83]
	v_mfma_f32_16x16x32_bf16 v[128:131], v[148:151], v[190:193], v[128:131]
	v_mfma_f32_16x16x32_bf16 v[124:127], v[156:159], v[190:193], v[124:127]
	v_mfma_f32_16x16x32_bf16 v[120:123], v[148:151], v[202:205], v[120:123]
	v_mfma_f32_16x16x32_bf16 v[112:115], v[156:159], v[202:205], v[112:115]
	v_mfma_f32_16x16x32_bf16 v[104:107], v[148:151], v[210:213], v[104:107]
	v_mfma_f32_16x16x32_bf16 v[96:99], v[156:159], v[210:213], v[96:99]
	v_mfma_f32_16x16x32_bf16 v[88:91], v[148:151], v[222:225], v[88:91]
	v_mfma_f32_16x16x32_bf16 v[80:83], v[156:159], v[222:225], v[80:83]
	s_setprio 0
	s_setprio 1
	v_mfma_f32_16x16x32_bf16 v[116:119], v[160:163], v[186:189], v[116:119]
	v_mfma_f32_16x16x32_bf16 v[108:111], v[168:171], v[186:189], v[108:111]
	v_mfma_f32_16x16x32_bf16 v[100:103], v[160:163], v[198:201], v[100:103]
	v_mfma_f32_16x16x32_bf16 v[92:95], v[168:171], v[198:201], v[92:95]
	v_mfma_f32_16x16x32_bf16 v[84:87], v[160:163], v[206:209], v[84:87]
	v_mfma_f32_16x16x32_bf16 v[76:79], v[168:171], v[206:209], v[76:79]
	v_mfma_f32_16x16x32_bf16 v[72:75], v[160:163], v[218:221], v[72:75]
	v_mfma_f32_16x16x32_bf16 v[68:71], v[168:171], v[218:221], v[68:71]
	v_mfma_f32_16x16x32_bf16 v[116:119], v[164:167], v[190:193], v[116:119]
	v_mfma_f32_16x16x32_bf16 v[108:111], v[172:175], v[190:193], v[108:111]
	v_mfma_f32_16x16x32_bf16 v[100:103], v[164:167], v[202:205], v[100:103]
	v_mfma_f32_16x16x32_bf16 v[92:95], v[172:175], v[202:205], v[92:95]
	v_mfma_f32_16x16x32_bf16 v[84:87], v[164:167], v[210:213], v[84:87]
	v_mfma_f32_16x16x32_bf16 v[76:79], v[172:175], v[210:213], v[76:79]
	v_mfma_f32_16x16x32_bf16 v[72:75], v[164:167], v[222:225], v[72:75]
	v_mfma_f32_16x16x32_bf16 v[68:71], v[172:175], v[222:225], v[68:71]
	s_setprio 0
	s_barrier
; #define PG8_STAGE(bufoff, gbase, voff) do { _Pragma("unroll") for (int _i = 0; _i < 2; ++_i) \
;         __builtin_amdgcn_global_load_lds((const unsigned*)((const char*)(gbase) + (voff)[_i]), (LAS unsigned*)(lds + (bufoff) + ldsw + _i * 8192), 16, 0, 0); } while (0)
; #define PG8_LDA(dst, b, h) do { _Pragma("unroll") for (int m = 0; m < 4; ++m) _Pragma("unroll") for (int k = 0; k < 2; ++k) dst[m][k] = *(const LAS bf16x8*)(lds + PG8_SA(b, h) + aoff + m * 2048 + k * 1024); } while (0)
; #define PG8_MMA(ai, bj, At, Bt) do { __builtin_amdgcn_s_setprio(1); _Pragma("unroll") for (int m = 0; m < 4; ++m) _Pragma("unroll") for (int n = 0; n < 2; ++n) _Pragma("unroll") for (int k = 0; k < 2; ++k) \
;         acc[ai][bj][m][n] = __builtin_amdgcn_mfma_f32_16x16x32_bf16(Bt[n][k], At[m][k], acc[ai][bj][m][n], 0, 0, 0); __builtin_amdgcn_s_setprio(0); } while (0)
; #define PG8_WAIT_V(n) asm volatile("s_waitcnt vmcnt(" #n ")" ::: "memory")
; #define PG8_WAIT_L(n) asm volatile("s_waitcnt lgkmcnt(" #n ")" ::: "memory")
; #define PG8_BAR __builtin_amdgcn_s_barrier()
; #define PG8_SCHED __builtin_amdgcn_sched_barrier(0)
; template <class Epi, class Sched, bool ALIGN_EPI = true, bool SP2 = true>
; __device__ __forceinline__ void gemm_phase(LAS unsigned char* lds, const Gemm g, const Sched& S, const Epi& E) {
;     ...
;             PG8_LDA(At, 1, 1); PG8_STAGE(PG8_SB(1, 0), b3, voffB); PG8_STAGE(PG8_SB(1, 1), b3 + hstepB, voffB); PG8_STAGE(PG8_SA(1, 0), a3, voffA);
;             PG8_WAIT_V(8); PG8_WAIT_L(0); PG8_BAR; PG8_MMA(1, 0, At, B0); PG8_MMA(1, 1, At, B1); PG8_BAR; PG8_SCHED;
;         }
;         if constexpr (ALIGN_EPI) { if (wr == 0) PG8_BAR; }
	s_add_i32 s20, s58, s39
	v_lshl_add_u64 v[140:141], v[140:141], 0, s[14:15]
	s_mov_b32 m0, s20
	ds_read_b128 v[186:189], v143 offset:49152
	ds_read_b128 v[190:193], v143 offset:50176
	ds_read_b128 v[198:201], v143 offset:51200
	ds_read_b128 v[202:205], v143 offset:52224
	ds_read_b128 v[206:209], v143 offset:53248
	ds_read_b128 v[210:213], v143 offset:54272
	ds_read_b128 v[218:221], v143 offset:55296
	ds_read_b128 v[222:225], v143 offset:56320
	global_load_lds_dwordx4 v[140:141], off
	s_add_i32 m0, s20, 0x2000
	s_add_u32 s18, s18, 0x40080
	v_lshl_add_u64 v[140:141], v[176:177], 0, s[14:15]
	s_addc_u32 s19, s19, 0
	s_add_i32 s20, s59, s39
	global_load_lds_dwordx4 v[140:141], off
	v_lshl_add_u64 v[140:141], s[18:19], 0, v[18:19]
	s_mov_b32 m0, s20
	s_nop 0
	global_load_lds_dwordx4 v[140:141], off
	v_lshl_add_u64 v[140:141], s[18:19], 0, v[16:17]
	s_add_i32 m0, s20, 0x2000
	s_nop 0
	global_load_lds_dwordx4 v[140:141], off
	v_lshl_add_u64 v[140:141], v[178:179], 0, s[14:15]
	s_mov_b32 m0, s8
	s_nop 0
	global_load_lds_dwordx4 v[140:141], off
	v_lshl_add_u64 v[140:141], v[182:183], 0, s[14:15]
	s_mov_b32 m0, s9
	s_nop 0
	global_load_lds_dwordx4 v[140:141], off
	s_waitcnt vmcnt(8)
	s_waitcnt lgkmcnt(0)
	s_barrier
	s_setprio 1
	v_mfma_f32_16x16x32_bf16 v[64:67], v[144:147], v[186:189], v[64:67]
	v_mfma_f32_16x16x32_bf16 v[60:63], v[152:155], v[186:189], v[60:63]
	v_mfma_f32_16x16x32_bf16 v[56:59], v[144:147], v[198:201], v[56:59]
	v_mfma_f32_16x16x32_bf16 v[48:51], v[152:155], v[198:201], v[48:51]
	v_mfma_f32_16x16x32_bf16 v[40:43], v[144:147], v[206:209], v[40:43]
	v_mfma_f32_16x16x32_bf16 v[32:35], v[152:155], v[206:209], v[32:35]
	v_mfma_f32_16x16x32_bf16 v[24:27], v[144:147], v[218:221], v[24:27]
	v_mfma_f32_16x16x32_bf16 v[12:15], v[152:155], v[218:221], v[12:15]
	v_mfma_f32_16x16x32_bf16 v[64:67], v[148:151], v[190:193], v[64:67]
	v_mfma_f32_16x16x32_bf16 v[60:63], v[156:159], v[190:193], v[60:63]
	v_mfma_f32_16x16x32_bf16 v[56:59], v[148:151], v[202:205], v[56:59]
	v_mfma_f32_16x16x32_bf16 v[48:51], v[156:159], v[202:205], v[48:51]
	v_mfma_f32_16x16x32_bf16 v[40:43], v[148:151], v[210:213], v[40:43]
	v_mfma_f32_16x16x32_bf16 v[32:35], v[156:159], v[210:213], v[32:35]
	v_mfma_f32_16x16x32_bf16 v[24:27], v[148:151], v[222:225], v[24:27]
	v_mfma_f32_16x16x32_bf16 v[12:15], v[156:159], v[222:225], v[12:15]
	s_setprio 0
	s_setprio 1
	v_mfma_f32_16x16x32_bf16 v[52:55], v[160:163], v[186:189], v[52:55]
	v_mfma_f32_16x16x32_bf16 v[44:47], v[168:171], v[186:189], v[44:47]
	v_mfma_f32_16x16x32_bf16 v[36:39], v[160:163], v[198:201], v[36:39]
	v_mfma_f32_16x16x32_bf16 v[28:31], v[168:171], v[198:201], v[28:31]
	v_mfma_f32_16x16x32_bf16 v[20:23], v[160:163], v[206:209], v[20:23]
	v_mfma_f32_16x16x32_bf16 v[8:11], v[168:171], v[206:209], v[8:11]
	v_mfma_f32_16x16x32_bf16 v[4:7], v[160:163], v[218:221], v[4:7]
	v_mfma_f32_16x16x32_bf16 v[0:3], v[168:171], v[218:221], v[0:3]
	v_mfma_f32_16x16x32_bf16 v[52:55], v[164:167], v[190:193], v[52:55]
	v_mfma_f32_16x16x32_bf16 v[44:47], v[172:175], v[190:193], v[44:47]
	v_mfma_f32_16x16x32_bf16 v[36:39], v[164:167], v[202:205], v[36:39]
	v_mfma_f32_16x16x32_bf16 v[28:31], v[172:175], v[202:205], v[28:31]
	v_mfma_f32_16x16x32_bf16 v[20:23], v[164:167], v[210:213], v[20:23]
	v_mfma_f32_16x16x32_bf16 v[8:11], v[172:175], v[210:213], v[8:11]
	v_mfma_f32_16x16x32_bf16 v[4:7], v[164:167], v[222:225], v[4:7]
	v_mfma_f32_16x16x32_bf16 v[0:3], v[172:175], v[222:225], v[0:3]
	s_setprio 0
	s_barrier
	s_add_i32 s49, s49, 2
	s_add_u32 s54, s54, 0x100
	s_addc_u32 s55, s55, 0
	s_add_u32 s30, s30, 0x100
	s_addc_u32 s45, s45, 0
	s_cmp_gt_u32 s49, 13
	s_cbranch_scc0 .LBB0_884
	s_and_b64 vcc, exec, s[36:37]
	s_cbranch_vccz .LBB0_887
	s_barrier

; #define PG8_STAGE(bufoff, gbase, voff) do { _Pragma("unroll") for (int _i = 0; _i < 2; ++_i) \
;         __builtin_amdgcn_global_load_lds((const unsigned*)((const char*)(gbase) + (voff)[_i]), (LAS unsigned*)(lds + (bufoff) + ldsw + _i * 8192), 16, 0, 0); } while (0)
; #define PG8_LDA(dst, b, h) do { _Pragma("unroll") for (int m = 0; m < 4; ++m) _Pragma("unroll") for (int k = 0; k < 2; ++k) dst[m][k] = *(const LAS bf16x8*)(lds + PG8_SA(b, h) + aoff + m * 2048 + k * 1024); } while (0)
; #define PG8_LDB(dst, b, h) do { _Pragma("unroll") for (int n = 0; n < 2; ++n) _Pragma("unroll") for (int k = 0; k < 2; ++k) dst[n][k] = *(const LAS bf16x8*)(lds + PG8_SB(b, h) + boff + n * 2048 + k * 1024); } while (0)
; #define PG8_MMA(ai, bj, At, Bt) do { __builtin_amdgcn_s_setprio(1); _Pragma("unroll") for (int m = 0; m < 4; ++m) _Pragma("unroll") for (int n = 0; n < 2; ++n) _Pragma("unroll") for (int k = 0; k < 2; ++k) \
;         acc[ai][bj][m][n] = __builtin_amdgcn_mfma_f32_16x16x32_bf16(Bt[n][k], At[m][k], acc[ai][bj][m][n], 0, 0, 0); __builtin_amdgcn_s_setprio(0); } while (0)
; #define PG8_WAIT_V(n) asm volatile("s_waitcnt vmcnt(" #n ")" ::: "memory")
; #define PG8_WAIT_L(n) asm volatile("s_waitcnt lgkmcnt(" #n ")" ::: "memory")
; #define PG8_BAR __builtin_amdgcn_s_barrier()
; template <class Epi, class Sched, bool ALIGN_EPI = true, bool SP2 = true>
; __device__ __forceinline__ void gemm_phase(LAS unsigned char* lds, const Gemm g, const Sched& S, const Epi& E) {
;     ...
;         for (int t = 0; t < nt; t += 2) {
;             const bool last = (t == nt - 2);
;             const char* a1 = cA + (size_t)(t + 1) * kstep;
;             const char* a2 = last ? nA : cA + (size_t)(t + 2) * kstep; const char* b2 = last ? nB : cB + (size_t)(t + 2) * kstep;
;             const char* a3 = a2 + kstep; const char* b3 = b2 + kstep;
;             PG8_LDB(B0, 0, 0); PG8_LDB(B1, 0, 1); PG8_SCHED; PG8_LDA(At, 0, 0); PG8_STAGE(PG8_SA(1, 1), a1 + hstepA, voffA);
;             PG8_WAIT_V(8); PG8_WAIT_L(0); PG8_BAR; PG8_MMA(0, 0, At, B0); PG8_MMA(0, 1, At, B1); PG8_BAR; PG8_SCHED;
;             PG8_LDA(At, 0, 1); PG8_STAGE(PG8_SB(0, 0), b2, voffB); PG8_STAGE(PG8_SB(0, 1), b2 + hstepB, voffB); PG8_STAGE(PG8_SA(0, 0), a2, voffA);
;             PG8_WAIT_V(8); PG8_WAIT_L(0); PG8_BAR; PG8_MMA(1, 0, At, B0); PG8_MMA(1, 1, At, B1); PG8_BAR; PG8_SCHED;
.LBB0_1063:
	s_add_u32 s18, vcc_lo, 0xfffc0080
	s_addc_u32 s19, vcc_hi, -1
	s_add_i32 s34, 0, 0x10000
	s_cmp_eq_u32 s58, 12
	s_cselect_b32 s23, s51, s19
	s_cselect_b32 s22, s2, s18
	s_cselect_b32 s19, s47, s55
	s_cselect_b32 s18, s30, s54
	s_add_i32 s59, 0, 0x14000
	v_add_u32_e32 v154, s34, v144
	v_add_u32_e32 v170, s59, v144
	ds_read_b128 v[140:143], v154
	ds_read_b128 v[146:149], v154 offset:1024
	ds_read_b128 v[150:153], v154 offset:2048
	ds_read_b128 v[154:157], v154 offset:3072
	ds_read_b128 v[158:161], v170
	ds_read_b128 v[162:165], v170 offset:1024
	ds_read_b128 v[166:169], v170 offset:2048
	ds_read_b128 v[170:173], v170 offset:3072
	v_lshl_add_u64 v[178:179], vcc, 0, v[136:137]
	s_add_i32 m0, s65, 0xc000
	ds_read_b128 v[174:177], v145
	ds_read_b128 v[186:189], v145 offset:1024
	ds_read_b128 v[190:193], v145 offset:2048
	ds_read_b128 v[198:201], v145 offset:3072
	ds_read_b128 v[202:205], v145 offset:4096
	ds_read_b128 v[206:209], v145 offset:5120
	ds_read_b128 v[210:213], v145 offset:6144
	ds_read_b128 v[218:221], v145 offset:7168
	global_load_lds_dwordx4 v[178:179], off
	v_lshl_add_u64 v[178:179], vcc, 0, v[138:139]
	s_add_i32 m0, s65, 0xe000
	s_nop 0
	global_load_lds_dwordx4 v[178:179], off
	s_waitcnt vmcnt(8)
	s_waitcnt lgkmcnt(0)
	s_barrier
	s_setprio 1
	v_mfma_f32_16x16x32_bf16 v[128:131], v[140:143], v[174:177], v[128:131]
	v_mfma_f32_16x16x32_bf16 v[124:127], v[150:153], v[174:177], v[124:127]
	v_mfma_f32_16x16x32_bf16 v[120:123], v[140:143], v[190:193], v[120:123]
	v_mfma_f32_16x16x32_bf16 v[112:115], v[150:153], v[190:193], v[112:115]
	v_mfma_f32_16x16x32_bf16 v[104:107], v[140:143], v[202:205], v[104:107]
	v_mfma_f32_16x16x32_bf16 v[96:99], v[150:153], v[202:205], v[96:99]
	v_mfma_f32_16x16x32_bf16 v[88:91], v[140:143], v[210:213], v[88:91]
	v_mfma_f32_16x16x32_bf16 v[80:83], v[150:153], v[210:213], v[80:83]
	v_mfma_f32_16x16x32_bf16 v[128:131], v[146:149], v[186:189], v[128:131]
	v_mfma_f32_16x16x32_bf16 v[124:127], v[154:157], v[186:189], v[124:127]
	v_mfma_f32_16x16x32_bf16 v[120:123], v[146:149], v[198:201], v[120:123]
	v_mfma_f32_16x16x32_bf16 v[112:115], v[154:157], v[198:201], v[112:115]
	v_mfma_f32_16x16x32_bf16 v[104:107], v[146:149], v[206:209], v[104:107]
	v_mfma_f32_16x16x32_bf16 v[96:99], v[154:157], v[206:209], v[96:99]
	v_mfma_f32_16x16x32_bf16 v[88:91], v[146:149], v[218:221], v[88:91]
	v_mfma_f32_16x16x32_bf16 v[80:83], v[154:157], v[218:221], v[80:83]
	s_setprio 0
	s_setprio 1
	v_mfma_f32_16x16x32_bf16 v[116:119], v[158:161], v[174:177], v[116:119]
	v_mfma_f32_16x16x32_bf16 v[108:111], v[166:169], v[174:177], v[108:111]
	v_mfma_f32_16x16x32_bf16 v[100:103], v[158:161], v[190:193], v[100:103]
	v_mfma_f32_16x16x32_bf16 v[92:95], v[166:169], v[190:193], v[92:95]
	v_mfma_f32_16x16x32_bf16 v[84:87], v[158:161], v[202:205], v[84:87]
	v_mfma_f32_16x16x32_bf16 v[76:79], v[166:169], v[202:205], v[76:79]
	v_mfma_f32_16x16x32_bf16 v[72:75], v[158:161], v[210:213], v[72:75]
	v_mfma_f32_16x16x32_bf16 v[68:71], v[166:169], v[210:213], v[68:71]
	v_mfma_f32_16x16x32_bf16 v[116:119], v[162:165], v[186:189], v[116:119]
	v_mfma_f32_16x16x32_bf16 v[108:111], v[170:173], v[186:189], v[108:111]
	v_mfma_f32_16x16x32_bf16 v[100:103], v[162:165], v[198:201], v[100:103]
	v_mfma_f32_16x16x32_bf16 v[92:95], v[170:173], v[198:201], v[92:95]
	v_mfma_f32_16x16x32_bf16 v[84:87], v[162:165], v[206:209], v[84:87]
	v_mfma_f32_16x16x32_bf16 v[76:79], v[170:173], v[206:209], v[76:79]
	v_mfma_f32_16x16x32_bf16 v[72:75], v[162:165], v[218:221], v[72:75]
	v_mfma_f32_16x16x32_bf16 v[68:71], v[170:173], v[218:221], v[68:71]
	s_setprio 0
	s_barrier
	s_add_i32 s34, s34, s56
	v_lshl_add_u64 v[178:179], s[18:19], 0, v[18:19]
	s_mov_b32 m0, s34
	ds_read_b128 v[174:177], v145 offset:16384
	ds_read_b128 v[186:189], v145 offset:17408
	ds_read_b128 v[190:193], v145 offset:18432
	ds_read_b128 v[198:201], v145 offset:19456
	ds_read_b128 v[202:205], v145 offset:20480
	ds_read_b128 v[206:209], v145 offset:21504
	ds_read_b128 v[210:213], v145 offset:22528
	ds_read_b128 v[218:221], v145 offset:23552
	global_load_lds_dwordx4 v[178:179], off
	s_add_i32 m0, s34, 0x2000
	s_add_u32 s34, s18, 0x40000
	v_lshl_add_u64 v[182:183], s[18:19], 0, v[16:17]
	s_addc_u32 s35, s19, 0
	s_add_i32 s59, s59, s56
	global_load_lds_dwordx4 v[182:183], off
	v_lshl_add_u64 v[214:215], s[34:35], 0, v[18:19]
	s_mov_b32 m0, s59
	v_lshl_add_u64 v[222:223], s[22:23], 0, v[132:133]
	global_load_lds_dwordx4 v[214:215], off
	v_lshl_add_u64 v[214:215], s[34:35], 0, v[16:17]
	s_add_i32 m0, s59, 0x2000
	s_nop 0
	global_load_lds_dwordx4 v[214:215], off
	v_lshl_add_u64 v[214:215], s[22:23], 0, v[134:135]
	s_mov_b32 m0, s65
	s_nop 0
	global_load_lds_dwordx4 v[214:215], off
	s_mov_b32 m0, s0
	s_nop 0
	global_load_lds_dwordx4 v[222:223], off
	s_waitcnt vmcnt(8)
	s_waitcnt lgkmcnt(0)
	s_barrier
; #define PG8_STAGE(bufoff, gbase, voff) do { _Pragma("unroll") for (int _i = 0; _i < 2; ++_i) \
;         __builtin_amdgcn_global_load_lds((const unsigned*)((const char*)(gbase) + (voff)[_i]), (LAS unsigned*)(lds + (bufoff) + ldsw + _i * 8192), 16, 0, 0); } while (0)
; #define PG8_LDA(dst, b, h) do { _Pragma("unroll") for (int m = 0; m < 4; ++m) _Pragma("unroll") for (int k = 0; k < 2; ++k) dst[m][k] = *(const LAS bf16x8*)(lds + PG8_SA(b, h) + aoff + m * 2048 + k * 1024); } while (0)
; #define PG8_LDB(dst, b, h) do { _Pragma("unroll") for (int n = 0; n < 2; ++n) _Pragma("unroll") for (int k = 0; k < 2; ++k) dst[n][k] = *(const LAS bf16x8*)(lds + PG8_SB(b, h) + boff + n * 2048 + k * 1024); } while (0)
; #define PG8_MMA(ai, bj, At, Bt) do { __builtin_amdgcn_s_setprio(1); _Pragma("unroll") for (int m = 0; m < 4; ++m) _Pragma("unroll") for (int n = 0; n < 2; ++n) _Pragma("unroll") for (int k = 0; k < 2; ++k) \
;         acc[ai][bj][m][n] = __builtin_amdgcn_mfma_f32_16x16x32_bf16(Bt[n][k], At[m][k], acc[ai][bj][m][n], 0, 0, 0); __builtin_amdgcn_s_setprio(0); } while (0)
; #define PG8_WAIT_V(n) asm volatile("s_waitcnt vmcnt(" #n ")" ::: "memory")
; #define PG8_WAIT_L(n) asm volatile("s_waitcnt lgkmcnt(" #n ")" ::: "memory")
; #define PG8_BAR __builtin_amdgcn_s_barrier()
; #define PG8_SCHED __builtin_amdgcn_sched_barrier(0)
; template <class Epi, class Sched, bool ALIGN_EPI = true, bool SP2 = true>
; __device__ __forceinline__ void gemm_phase(LAS unsigned char* lds, const Gemm g, const Sched& S, const Epi& E) {
;     ...
;             PG8_LDA(At, 0, 1); PG8_STAGE(PG8_SB(0, 0), b2, voffB); PG8_STAGE(PG8_SB(0, 1), b2 + hstepB, voffB); PG8_STAGE(PG8_SA(0, 0), a2, voffA);
;             PG8_WAIT_V(8); PG8_WAIT_L(0); PG8_BAR; PG8_MMA(1, 0, At, B0); PG8_MMA(1, 1, At, B1); PG8_BAR; PG8_SCHED;
;             PG8_LDB(B0, 1, 0); PG8_LDB(B1, 1, 1); PG8_SCHED; PG8_LDA(At, 1, 0); PG8_STAGE(PG8_SA(0, 1), a2 + hstepA, voffA);
;             PG8_WAIT_V(8); PG8_WAIT_L(0); PG8_BAR; PG8_MMA(0, 0, At, B0); PG8_MMA(0, 1, At, B1); PG8_BAR; PG8_SCHED;
	s_setprio 1
	v_mfma_f32_16x16x32_bf16 v[64:67], v[140:143], v[174:177], v[64:67]
	v_mfma_f32_16x16x32_bf16 v[60:63], v[150:153], v[174:177], v[60:63]
	v_mfma_f32_16x16x32_bf16 v[56:59], v[140:143], v[190:193], v[56:59]
	v_mfma_f32_16x16x32_bf16 v[48:51], v[150:153], v[190:193], v[48:51]
	v_mfma_f32_16x16x32_bf16 v[40:43], v[140:143], v[202:205], v[40:43]
	v_mfma_f32_16x16x32_bf16 v[32:35], v[150:153], v[202:205], v[32:35]
	v_mfma_f32_16x16x32_bf16 v[24:27], v[140:143], v[210:213], v[24:27]
	v_mfma_f32_16x16x32_bf16 v[12:15], v[150:153], v[210:213], v[12:15]
	v_mfma_f32_16x16x32_bf16 v[64:67], v[146:149], v[186:189], v[64:67]
	v_mfma_f32_16x16x32_bf16 v[60:63], v[154:157], v[186:189], v[60:63]
	v_mfma_f32_16x16x32_bf16 v[56:59], v[146:149], v[198:201], v[56:59]
	v_mfma_f32_16x16x32_bf16 v[48:51], v[154:157], v[198:201], v[48:51]
	v_mfma_f32_16x16x32_bf16 v[40:43], v[146:149], v[206:209], v[40:43]
	v_mfma_f32_16x16x32_bf16 v[32:35], v[154:157], v[206:209], v[32:35]
	v_mfma_f32_16x16x32_bf16 v[24:27], v[146:149], v[218:221], v[24:27]
	v_mfma_f32_16x16x32_bf16 v[12:15], v[154:157], v[218:221], v[12:15]
	s_setprio 0
	s_setprio 1
	v_mfma_f32_16x16x32_bf16 v[52:55], v[158:161], v[174:177], v[52:55]
	v_mfma_f32_16x16x32_bf16 v[44:47], v[166:169], v[174:177], v[44:47]
	v_mfma_f32_16x16x32_bf16 v[36:39], v[158:161], v[190:193], v[36:39]
	v_mfma_f32_16x16x32_bf16 v[28:31], v[166:169], v[190:193], v[28:31]
	v_mfma_f32_16x16x32_bf16 v[20:23], v[158:161], v[202:205], v[20:23]
	v_mfma_f32_16x16x32_bf16 v[8:11], v[166:169], v[202:205], v[8:11]
	v_mfma_f32_16x16x32_bf16 v[4:7], v[158:161], v[210:213], v[4:7]
	v_mfma_f32_16x16x32_bf16 v[0:3], v[166:169], v[210:213], v[0:3]
	v_mfma_f32_16x16x32_bf16 v[52:55], v[162:165], v[186:189], v[52:55]
	v_mfma_f32_16x16x32_bf16 v[44:47], v[170:173], v[186:189], v[44:47]
	v_mfma_f32_16x16x32_bf16 v[36:39], v[162:165], v[198:201], v[36:39]
	v_mfma_f32_16x16x32_bf16 v[28:31], v[170:173], v[198:201], v[28:31]
	v_mfma_f32_16x16x32_bf16 v[20:23], v[162:165], v[206:209], v[20:23]
	v_mfma_f32_16x16x32_bf16 v[8:11], v[170:173], v[206:209], v[8:11]
	v_mfma_f32_16x16x32_bf16 v[4:7], v[162:165], v[218:221], v[4:7]
	v_mfma_f32_16x16x32_bf16 v[0:3], v[170:173], v[218:221], v[0:3]
	s_setprio 0
	s_barrier
	s_add_i32 s34, 0, 0x18000
	s_add_i32 s35, 0, 0x1c000
	v_add_u32_e32 v154, s34, v144
	v_add_u32_e32 v170, s35, v144
	ds_read_b128 v[140:143], v154
	ds_read_b128 v[146:149], v154 offset:1024
	ds_read_b128 v[150:153], v154 offset:2048
	ds_read_b128 v[154:157], v154 offset:3072
	ds_read_b128 v[158:161], v170
	ds_read_b128 v[162:165], v170 offset:1024
	ds_read_b128 v[166:169], v170 offset:2048
	ds_read_b128 v[170:173], v170 offset:3072
	s_add_u32 s22, s22, 0x40000
	s_addc_u32 s23, s23, 0
	s_mov_b32 m0, s1
	v_lshl_add_u64 v[224:225], s[22:23], 0, v[134:135]
	ds_read_b128 v[174:177], v145 offset:32768
	ds_read_b128 v[186:189], v145 offset:33792
	ds_read_b128 v[190:193], v145 offset:34816
	ds_read_b128 v[198:201], v145 offset:35840
	ds_read_b128 v[202:205], v145 offset:36864
	ds_read_b128 v[206:209], v145 offset:37888
	ds_read_b128 v[210:213], v145 offset:38912
	ds_read_b128 v[218:221], v145 offset:39936
	global_load_lds_dwordx4 v[224:225], off
	v_lshl_add_u64 v[224:225], s[22:23], 0, v[132:133]
	s_mov_b32 m0, s8
	s_nop 0
	global_load_lds_dwordx4 v[224:225], off
	s_waitcnt vmcnt(8)
	s_waitcnt lgkmcnt(0)
	s_barrier
	s_setprio 1
	v_mfma_f32_16x16x32_bf16 v[128:131], v[140:143], v[174:177], v[128:131]
	v_mfma_f32_16x16x32_bf16 v[124:127], v[150:153], v[174:177], v[124:127]
	v_mfma_f32_16x16x32_bf16 v[120:123], v[140:143], v[190:193], v[120:123]
	v_mfma_f32_16x16x32_bf16 v[112:115], v[150:153], v[190:193], v[112:115]
	v_mfma_f32_16x16x32_bf16 v[104:107], v[140:143], v[202:205], v[104:107]
	v_mfma_f32_16x16x32_bf16 v[96:99], v[150:153], v[202:205], v[96:99]
	v_mfma_f32_16x16x32_bf16 v[88:91], v[140:143], v[210:213], v[88:91]
	v_mfma_f32_16x16x32_bf16 v[80:83], v[150:153], v[210:213], v[80:83]
	v_mfma_f32_16x16x32_bf16 v[128:131], v[146:149], v[186:189], v[128:131]
	v_mfma_f32_16x16x32_bf16 v[124:127], v[154:157], v[186:189], v[124:127]
	v_mfma_f32_16x16x32_bf16 v[120:123], v[146:149], v[198:201], v[120:123]
	v_mfma_f32_16x16x32_bf16 v[112:115], v[154:157], v[198:201], v[112:115]
	v_mfma_f32_16x16x32_bf16 v[104:107], v[146:149], v[206:209], v[104:107]
	v_mfma_f32_16x16x32_bf16 v[96:99], v[154:157], v[206:209], v[96:99]
	v_mfma_f32_16x16x32_bf16 v[88:91], v[146:149], v[218:221], v[88:91]
	v_mfma_f32_16x16x32_bf16 v[80:83], v[154:157], v[218:221], v[80:83]
	s_setprio 0
	s_setprio 1
	v_mfma_f32_16x16x32_bf16 v[116:119], v[158:161], v[174:177], v[116:119]
	v_mfma_f32_16x16x32_bf16 v[108:111], v[166:169], v[174:177], v[108:111]
	v_mfma_f32_16x16x32_bf16 v[100:103], v[158:161], v[190:193], v[100:103]
	v_mfma_f32_16x16x32_bf16 v[92:95], v[166:169], v[190:193], v[92:95]
	v_mfma_f32_16x16x32_bf16 v[84:87], v[158:161], v[202:205], v[84:87]
	v_mfma_f32_16x16x32_bf16 v[76:79], v[166:169], v[202:205], v[76:79]
	v_mfma_f32_16x16x32_bf16 v[72:75], v[158:161], v[210:213], v[72:75]
	v_mfma_f32_16x16x32_bf16 v[68:71], v[166:169], v[210:213], v[68:71]
	v_mfma_f32_16x16x32_bf16 v[116:119], v[162:165], v[186:189], v[116:119]
	v_mfma_f32_16x16x32_bf16 v[108:111], v[170:173], v[186:189], v[108:111]
	v_mfma_f32_16x16x32_bf16 v[100:103], v[162:165], v[198:201], v[100:103]
	v_mfma_f32_16x16x32_bf16 v[92:95], v[170:173], v[198:201], v[92:95]
	v_mfma_f32_16x16x32_bf16 v[84:87], v[162:165], v[206:209], v[84:87]
	v_mfma_f32_16x16x32_bf16 v[76:79], v[170:173], v[206:209], v[76:79]
	v_mfma_f32_16x16x32_bf16 v[72:75], v[162:165], v[218:221], v[72:75]
	v_mfma_f32_16x16x32_bf16 v[68:71], v[170:173], v[218:221], v[68:71]
	s_setprio 0
	s_barrier
; #define PG8_STAGE(bufoff, gbase, voff) do { _Pragma("unroll") for (int _i = 0; _i < 2; ++_i) \
;         __builtin_amdgcn_global_load_lds((const unsigned*)((const char*)(gbase) + (voff)[_i]), (LAS unsigned*)(lds + (bufoff) + ldsw + _i * 8192), 16, 0, 0); } while (0)
; #define PG8_LDA(dst, b, h) do { _Pragma("unroll") for (int m = 0; m < 4; ++m) _Pragma("unroll") for (int k = 0; k < 2; ++k) dst[m][k] = *(const LAS bf16x8*)(lds + PG8_SA(b, h) + aoff + m * 2048 + k * 1024); } while (0)
; #define PG8_MMA(ai, bj, At, Bt) do { __builtin_amdgcn_s_setprio(1); _Pragma("unroll") for (int m = 0; m < 4; ++m) _Pragma("unroll") for (int n = 0; n < 2; ++n) _Pragma("unroll") for (int k = 0; k < 2; ++k) \
;         acc[ai][bj][m][n] = __builtin_amdgcn_mfma_f32_16x16x32_bf16(Bt[n][k], At[m][k], acc[ai][bj][m][n], 0, 0, 0); __builtin_amdgcn_s_setprio(0); } while (0)
; #define PG8_WAIT_V(n) asm volatile("s_waitcnt vmcnt(" #n ")" ::: "memory")
; #define PG8_WAIT_L(n) asm volatile("s_waitcnt lgkmcnt(" #n ")" ::: "memory")
; #define PG8_BAR __builtin_amdgcn_s_barrier()
; #define PG8_SCHED __builtin_amdgcn_sched_barrier(0)
; template <class Epi, class Sched, bool ALIGN_EPI = true, bool SP2 = true>
; __device__ __forceinline__ void gemm_phase(LAS unsigned char* lds, const Gemm g, const Sched& S, const Epi& E) {
;     ...
;             PG8_LDA(At, 1, 1); PG8_STAGE(PG8_SB(1, 0), b3, voffB); PG8_STAGE(PG8_SB(1, 1), b3 + hstepB, voffB); PG8_STAGE(PG8_SA(1, 0), a3, voffA);
;             PG8_WAIT_V(8); PG8_WAIT_L(0); PG8_BAR; PG8_MMA(1, 0, At, B0); PG8_MMA(1, 1, At, B1); PG8_BAR; PG8_SCHED;
;         }
;         if constexpr (ALIGN_EPI) { if (wr == 0) PG8_BAR; }
	s_add_i32 s22, s34, s56
	v_lshl_add_u64 v[178:179], v[178:179], 0, s[14:15]
	s_mov_b32 m0, s22
	ds_read_b128 v[174:177], v145 offset:49152
	ds_read_b128 v[186:189], v145 offset:50176
	ds_read_b128 v[190:193], v145 offset:51200
	ds_read_b128 v[198:201], v145 offset:52224
	ds_read_b128 v[202:205], v145 offset:53248
	ds_read_b128 v[206:209], v145 offset:54272
	ds_read_b128 v[210:213], v145 offset:55296
	ds_read_b128 v[218:221], v145 offset:56320
	global_load_lds_dwordx4 v[178:179], off
	s_add_i32 m0, s22, 0x2000
	s_add_u32 s18, s18, 0x40080
	v_lshl_add_u64 v[178:179], v[182:183], 0, s[14:15]
	s_addc_u32 s19, s19, 0
	s_add_i32 s22, s35, s56
	global_load_lds_dwordx4 v[178:179], off
	v_lshl_add_u64 v[178:179], s[18:19], 0, v[18:19]
	s_mov_b32 m0, s22
	s_nop 0
	global_load_lds_dwordx4 v[178:179], off
	v_lshl_add_u64 v[178:179], s[18:19], 0, v[16:17]
	s_add_i32 m0, s22, 0x2000
	s_nop 0
	global_load_lds_dwordx4 v[178:179], off
	v_lshl_add_u64 v[178:179], v[214:215], 0, s[14:15]
	s_mov_b32 m0, s49
	s_nop 0
	global_load_lds_dwordx4 v[178:179], off
	v_lshl_add_u64 v[178:179], v[222:223], 0, s[14:15]
	s_mov_b32 m0, s66
	s_nop 0
	global_load_lds_dwordx4 v[178:179], off
	s_waitcnt vmcnt(8)
	s_waitcnt lgkmcnt(0)
	s_barrier
	s_setprio 1
	v_mfma_f32_16x16x32_bf16 v[64:67], v[140:143], v[174:177], v[64:67]
	v_mfma_f32_16x16x32_bf16 v[60:63], v[150:153], v[174:177], v[60:63]
	v_mfma_f32_16x16x32_bf16 v[56:59], v[140:143], v[190:193], v[56:59]
	v_mfma_f32_16x16x32_bf16 v[48:51], v[150:153], v[190:193], v[48:51]
	v_mfma_f32_16x16x32_bf16 v[40:43], v[140:143], v[202:205], v[40:43]
	v_mfma_f32_16x16x32_bf16 v[32:35], v[150:153], v[202:205], v[32:35]
	v_mfma_f32_16x16x32_bf16 v[24:27], v[140:143], v[210:213], v[24:27]
	v_mfma_f32_16x16x32_bf16 v[12:15], v[150:153], v[210:213], v[12:15]
	v_mfma_f32_16x16x32_bf16 v[64:67], v[146:149], v[186:189], v[64:67]
	v_mfma_f32_16x16x32_bf16 v[60:63], v[154:157], v[186:189], v[60:63]
	v_mfma_f32_16x16x32_bf16 v[56:59], v[146:149], v[198:201], v[56:59]
	v_mfma_f32_16x16x32_bf16 v[48:51], v[154:157], v[198:201], v[48:51]
	v_mfma_f32_16x16x32_bf16 v[40:43], v[146:149], v[206:209], v[40:43]
	v_mfma_f32_16x16x32_bf16 v[32:35], v[154:157], v[206:209], v[32:35]
	v_mfma_f32_16x16x32_bf16 v[24:27], v[146:149], v[218:221], v[24:27]
	v_mfma_f32_16x16x32_bf16 v[12:15], v[154:157], v[218:221], v[12:15]
	s_setprio 0
	s_setprio 1
	v_mfma_f32_16x16x32_bf16 v[52:55], v[158:161], v[174:177], v[52:55]
	v_mfma_f32_16x16x32_bf16 v[44:47], v[166:169], v[174:177], v[44:47]
	v_mfma_f32_16x16x32_bf16 v[36:39], v[158:161], v[190:193], v[36:39]
	v_mfma_f32_16x16x32_bf16 v[28:31], v[166:169], v[190:193], v[28:31]
	v_mfma_f32_16x16x32_bf16 v[20:23], v[158:161], v[202:205], v[20:23]
	v_mfma_f32_16x16x32_bf16 v[8:11], v[166:169], v[202:205], v[8:11]
	v_mfma_f32_16x16x32_bf16 v[4:7], v[158:161], v[210:213], v[4:7]
	v_mfma_f32_16x16x32_bf16 v[0:3], v[166:169], v[210:213], v[0:3]
	v_mfma_f32_16x16x32_bf16 v[52:55], v[162:165], v[186:189], v[52:55]
	v_mfma_f32_16x16x32_bf16 v[44:47], v[170:173], v[186:189], v[44:47]
	v_mfma_f32_16x16x32_bf16 v[36:39], v[162:165], v[198:201], v[36:39]
	v_mfma_f32_16x16x32_bf16 v[28:31], v[170:173], v[198:201], v[28:31]
	v_mfma_f32_16x16x32_bf16 v[20:23], v[162:165], v[206:209], v[20:23]
	v_mfma_f32_16x16x32_bf16 v[8:11], v[170:173], v[206:209], v[8:11]
	v_mfma_f32_16x16x32_bf16 v[4:7], v[162:165], v[218:221], v[4:7]
	v_mfma_f32_16x16x32_bf16 v[0:3], v[170:173], v[218:221], v[0:3]
	s_setprio 0
	s_barrier
	s_add_i32 s58, s58, 2
	s_add_u32 vcc_lo, vcc_lo, 0x100
	s_addc_u32 vcc_hi, vcc_hi, 0
	s_add_u32 s54, s54, 0x100
	s_addc_u32 s55, s55, 0
	s_cmp_gt_u32 s58, 13
	s_cbranch_scc0 .LBB0_1063
	s_and_b64 vcc, exec, s[44:45]
	s_cbranch_vccz .LBB0_1066
	s_barrier

; #define PG8_STAGE(bufoff, gbase, voff) do { _Pragma("unroll") for (int _i = 0; _i < 2; ++_i) \
;         __builtin_amdgcn_global_load_lds((const unsigned*)((const char*)(gbase) + (voff)[_i]), (LAS unsigned*)(lds + (bufoff) + ldsw + _i * 8192), 16, 0, 0); } while (0)
; #define PG8_LDA(dst, b, h) do { _Pragma("unroll") for (int m = 0; m < 4; ++m) _Pragma("unroll") for (int k = 0; k < 2; ++k) dst[m][k] = *(const LAS bf16x8*)(lds + PG8_SA(b, h) + aoff + m * 2048 + k * 1024); } while (0)
; #define PG8_LDB(dst, b, h) do { _Pragma("unroll") for (int n = 0; n < 2; ++n) _Pragma("unroll") for (int k = 0; k < 2; ++k) dst[n][k] = *(const LAS bf16x8*)(lds + PG8_SB(b, h) + boff + n * 2048 + k * 1024); } while (0)
; #define PG8_MMA(ai, bj, At, Bt) do { __builtin_amdgcn_s_setprio(1); _Pragma("unroll") for (int m = 0; m < 4; ++m) _Pragma("unroll") for (int n = 0; n < 2; ++n) _Pragma("unroll") for (int k = 0; k < 2; ++k) \
;         acc[ai][bj][m][n] = __builtin_amdgcn_mfma_f32_16x16x32_bf16(Bt[n][k], At[m][k], acc[ai][bj][m][n], 0, 0, 0); __builtin_amdgcn_s_setprio(0); } while (0)
; #define PG8_WAIT_V(n) asm volatile("s_waitcnt vmcnt(" #n ")" ::: "memory")
; #define PG8_WAIT_L(n) asm volatile("s_waitcnt lgkmcnt(" #n ")" ::: "memory")
; #define PG8_BAR __builtin_amdgcn_s_barrier()
; template <class Epi, class Sched, bool ALIGN_EPI = true, bool SP2 = true>
; __device__ __forceinline__ void gemm_phase(LAS unsigned char* lds, const Gemm g, const Sched& S, const Epi& E) {
;     ...
;         for (int t = 0; t < nt; t += 2) {
;             const bool last = (t == nt - 2);
;             const char* a1 = cA + (size_t)(t + 1) * kstep;
;             const char* a2 = last ? nA : cA + (size_t)(t + 2) * kstep; const char* b2 = last ? nB : cB + (size_t)(t + 2) * kstep;
;             const char* a3 = a2 + kstep; const char* b3 = b2 + kstep;
;             PG8_LDB(B0, 0, 0); PG8_LDB(B1, 0, 1); PG8_SCHED; PG8_LDA(At, 0, 0); PG8_STAGE(PG8_SA(1, 1), a1 + hstepA, voffA);
;             PG8_WAIT_V(8); PG8_WAIT_L(0); PG8_BAR; PG8_MMA(0, 0, At, B0); PG8_MMA(0, 1, At, B1); PG8_BAR; PG8_SCHED;
;             PG8_LDA(At, 0, 1); PG8_STAGE(PG8_SB(0, 0), b2, voffB); PG8_STAGE(PG8_SB(0, 1), b2 + hstepB, voffB); PG8_STAGE(PG8_SA(0, 0), a2, voffA);
;             PG8_WAIT_V(8); PG8_WAIT_L(0); PG8_BAR; PG8_MMA(1, 0, At, B0); PG8_MMA(1, 1, At, B1); PG8_BAR; PG8_SCHED;
.LBB0_1229:
	s_add_u32 s18, s16, 0x100
	s_addc_u32 s19, s17, 0
	s_add_i32 s57, 0, 0x10000
	s_cmp_eq_u32 s56, 40
	s_cselect_b32 s23, s43, s19
	s_cselect_b32 s22, s42, s18
	v_add_u32_e32 v140, s57, v142
	s_cselect_b32 s21, s45, s30
	s_cselect_b32 s20, s44, s2
	s_add_i32 s58, 0, 0x14000
	ds_read_b128 v[144:147], v140
	ds_read_b128 v[148:151], v140 offset:1024
	ds_read_b128 v[152:155], v140 offset:2048
	ds_read_b128 v[156:159], v140 offset:3072
	v_add_u32_e32 v140, s58, v142
	ds_read_b128 v[160:163], v140
	ds_read_b128 v[164:167], v140 offset:1024
	ds_read_b128 v[168:171], v140 offset:2048
	ds_read_b128 v[172:175], v140 offset:3072
	v_lshl_add_u64 v[140:141], s[16:17], 0, v[136:137]
	s_add_i32 m0, s46, 0xc000
	ds_read_b128 v[186:189], v143
	ds_read_b128 v[190:193], v143 offset:1024
	ds_read_b128 v[198:201], v143 offset:2048
	ds_read_b128 v[202:205], v143 offset:3072
	ds_read_b128 v[206:209], v143 offset:4096
	ds_read_b128 v[210:213], v143 offset:5120
	ds_read_b128 v[218:221], v143 offset:6144
	ds_read_b128 v[222:225], v143 offset:7168
	global_load_lds_dwordx4 v[140:141], off
	v_lshl_add_u64 v[140:141], s[16:17], 0, v[138:139]
	s_add_i32 m0, s46, 0xe000
	s_nop 0
	global_load_lds_dwordx4 v[140:141], off
	s_waitcnt vmcnt(8)
	s_waitcnt lgkmcnt(0)
	s_barrier
	s_setprio 1
	v_mfma_f32_16x16x32_bf16 v[128:131], v[144:147], v[186:189], v[128:131]
	v_mfma_f32_16x16x32_bf16 v[124:127], v[152:155], v[186:189], v[124:127]
	v_mfma_f32_16x16x32_bf16 v[120:123], v[144:147], v[198:201], v[120:123]
	v_mfma_f32_16x16x32_bf16 v[112:115], v[152:155], v[198:201], v[112:115]
	v_mfma_f32_16x16x32_bf16 v[104:107], v[144:147], v[206:209], v[104:107]
	v_mfma_f32_16x16x32_bf16 v[96:99], v[152:155], v[206:209], v[96:99]
	v_mfma_f32_16x16x32_bf16 v[88:91], v[144:147], v[218:221], v[88:91]
	v_mfma_f32_16x16x32_bf16 v[80:83], v[152:155], v[218:221], v[80:83]
	v_mfma_f32_16x16x32_bf16 v[128:131], v[148:151], v[190:193], v[128:131]
	v_mfma_f32_16x16x32_bf16 v[124:127], v[156:159], v[190:193], v[124:127]
	v_mfma_f32_16x16x32_bf16 v[120:123], v[148:151], v[202:205], v[120:123]
	v_mfma_f32_16x16x32_bf16 v[112:115], v[156:159], v[202:205], v[112:115]
	v_mfma_f32_16x16x32_bf16 v[104:107], v[148:151], v[210:213], v[104:107]
	v_mfma_f32_16x16x32_bf16 v[96:99], v[156:159], v[210:213], v[96:99]
	v_mfma_f32_16x16x32_bf16 v[88:91], v[148:151], v[222:225], v[88:91]
	v_mfma_f32_16x16x32_bf16 v[80:83], v[156:159], v[222:225], v[80:83]
	s_setprio 0
	s_setprio 1
	v_mfma_f32_16x16x32_bf16 v[116:119], v[160:163], v[186:189], v[116:119]
	v_mfma_f32_16x16x32_bf16 v[108:111], v[168:171], v[186:189], v[108:111]
	v_mfma_f32_16x16x32_bf16 v[100:103], v[160:163], v[198:201], v[100:103]
	v_mfma_f32_16x16x32_bf16 v[92:95], v[168:171], v[198:201], v[92:95]
	v_mfma_f32_16x16x32_bf16 v[84:87], v[160:163], v[206:209], v[84:87]
	v_mfma_f32_16x16x32_bf16 v[76:79], v[168:171], v[206:209], v[76:79]
	v_mfma_f32_16x16x32_bf16 v[72:75], v[160:163], v[218:221], v[72:75]
	v_mfma_f32_16x16x32_bf16 v[68:71], v[168:171], v[218:221], v[68:71]
	v_mfma_f32_16x16x32_bf16 v[116:119], v[164:167], v[190:193], v[116:119]
	v_mfma_f32_16x16x32_bf16 v[108:111], v[172:175], v[190:193], v[108:111]
	v_mfma_f32_16x16x32_bf16 v[100:103], v[164:167], v[202:205], v[100:103]
	v_mfma_f32_16x16x32_bf16 v[92:95], v[172:175], v[202:205], v[92:95]
	v_mfma_f32_16x16x32_bf16 v[84:87], v[164:167], v[210:213], v[84:87]
	v_mfma_f32_16x16x32_bf16 v[76:79], v[172:175], v[210:213], v[76:79]
	v_mfma_f32_16x16x32_bf16 v[72:75], v[164:167], v[222:225], v[72:75]
	v_mfma_f32_16x16x32_bf16 v[68:71], v[172:175], v[222:225], v[68:71]
	s_setprio 0
	s_barrier
	s_add_i32 s16, s57, s38
	v_lshl_add_u64 v[140:141], s[20:21], 0, v[18:19]
	s_mov_b32 m0, s16
	ds_read_b128 v[186:189], v143 offset:16384
	ds_read_b128 v[190:193], v143 offset:17408
	ds_read_b128 v[198:201], v143 offset:18432
	ds_read_b128 v[202:205], v143 offset:19456
	ds_read_b128 v[206:209], v143 offset:20480
	ds_read_b128 v[210:213], v143 offset:21504
	ds_read_b128 v[218:221], v143 offset:22528
	ds_read_b128 v[222:225], v143 offset:23552
	global_load_lds_dwordx4 v[140:141], off
	s_add_i32 m0, s16, 0x2000
	s_add_u32 s16, s20, 0xb0000
	v_lshl_add_u64 v[176:177], s[20:21], 0, v[16:17]
	s_addc_u32 s17, s21, 0
	s_add_i32 s57, s58, s38
	global_load_lds_dwordx4 v[176:177], off
	v_lshl_add_u64 v[178:179], s[16:17], 0, v[18:19]
	s_mov_b32 m0, s57
	v_lshl_add_u64 v[182:183], s[22:23], 0, v[132:133]
	global_load_lds_dwordx4 v[178:179], off
	v_lshl_add_u64 v[178:179], s[16:17], 0, v[16:17]
	s_add_i32 m0, s57, 0x2000
	s_nop 0
	global_load_lds_dwordx4 v[178:179], off
	v_lshl_add_u64 v[178:179], s[22:23], 0, v[134:135]
	s_mov_b32 m0, s46
	s_nop 0
	global_load_lds_dwordx4 v[178:179], off
	s_mov_b32 m0, s47
	s_nop 0
	global_load_lds_dwordx4 v[182:183], off
	s_waitcnt vmcnt(8)
	s_waitcnt lgkmcnt(0)
	s_barrier
; #define PG8_STAGE(bufoff, gbase, voff) do { _Pragma("unroll") for (int _i = 0; _i < 2; ++_i) \
;         __builtin_amdgcn_global_load_lds((const unsigned*)((const char*)(gbase) + (voff)[_i]), (LAS unsigned*)(lds + (bufoff) + ldsw + _i * 8192), 16, 0, 0); } while (0)
; #define PG8_LDA(dst, b, h) do { _Pragma("unroll") for (int m = 0; m < 4; ++m) _Pragma("unroll") for (int k = 0; k < 2; ++k) dst[m][k] = *(const LAS bf16x8*)(lds + PG8_SA(b, h) + aoff + m * 2048 + k * 1024); } while (0)
; #define PG8_LDB(dst, b, h) do { _Pragma("unroll") for (int n = 0; n < 2; ++n) _Pragma("unroll") for (int k = 0; k < 2; ++k) dst[n][k] = *(const LAS bf16x8*)(lds + PG8_SB(b, h) + boff + n * 2048 + k * 1024); } while (0)
; #define PG8_MMA(ai, bj, At, Bt) do { __builtin_amdgcn_s_setprio(1); _Pragma("unroll") for (int m = 0; m < 4; ++m) _Pragma("unroll") for (int n = 0; n < 2; ++n) _Pragma("unroll") for (int k = 0; k < 2; ++k) \
;         acc[ai][bj][m][n] = __builtin_amdgcn_mfma_f32_16x16x32_bf16(Bt[n][k], At[m][k], acc[ai][bj][m][n], 0, 0, 0); __builtin_amdgcn_s_setprio(0); } while (0)
; #define PG8_WAIT_V(n) asm volatile("s_waitcnt vmcnt(" #n ")" ::: "memory")
; #define PG8_WAIT_L(n) asm volatile("s_waitcnt lgkmcnt(" #n ")" ::: "memory")
; #define PG8_BAR __builtin_amdgcn_s_barrier()
; #define PG8_SCHED __builtin_amdgcn_sched_barrier(0)
; template <class Epi, class Sched, bool ALIGN_EPI = true, bool SP2 = true>
; __device__ __forceinline__ void gemm_phase(LAS unsigned char* lds, const Gemm g, const Sched& S, const Epi& E) {
;     ...
;             PG8_LDA(At, 0, 1); PG8_STAGE(PG8_SB(0, 0), b2, voffB); PG8_STAGE(PG8_SB(0, 1), b2 + hstepB, voffB); PG8_STAGE(PG8_SA(0, 0), a2, voffA);
;             PG8_WAIT_V(8); PG8_WAIT_L(0); PG8_BAR; PG8_MMA(1, 0, At, B0); PG8_MMA(1, 1, At, B1); PG8_BAR; PG8_SCHED;
;             PG8_LDB(B0, 1, 0); PG8_LDB(B1, 1, 1); PG8_SCHED; PG8_LDA(At, 1, 0); PG8_STAGE(PG8_SA(0, 1), a2 + hstepA, voffA);
;             PG8_WAIT_V(8); PG8_WAIT_L(0); PG8_BAR; PG8_MMA(0, 0, At, B0); PG8_MMA(0, 1, At, B1); PG8_BAR; PG8_SCHED;
	s_setprio 1
	v_mfma_f32_16x16x32_bf16 v[64:67], v[144:147], v[186:189], v[64:67]
	v_mfma_f32_16x16x32_bf16 v[60:63], v[152:155], v[186:189], v[60:63]
	v_mfma_f32_16x16x32_bf16 v[56:59], v[144:147], v[198:201], v[56:59]
	v_mfma_f32_16x16x32_bf16 v[48:51], v[152:155], v[198:201], v[48:51]
	v_mfma_f32_16x16x32_bf16 v[40:43], v[144:147], v[206:209], v[40:43]
	v_mfma_f32_16x16x32_bf16 v[32:35], v[152:155], v[206:209], v[32:35]
	v_mfma_f32_16x16x32_bf16 v[24:27], v[144:147], v[218:221], v[24:27]
	v_mfma_f32_16x16x32_bf16 v[12:15], v[152:155], v[218:221], v[12:15]
	v_mfma_f32_16x16x32_bf16 v[64:67], v[148:151], v[190:193], v[64:67]
	v_mfma_f32_16x16x32_bf16 v[60:63], v[156:159], v[190:193], v[60:63]
	v_mfma_f32_16x16x32_bf16 v[56:59], v[148:151], v[202:205], v[56:59]
	v_mfma_f32_16x16x32_bf16 v[48:51], v[156:159], v[202:205], v[48:51]
	v_mfma_f32_16x16x32_bf16 v[40:43], v[148:151], v[210:213], v[40:43]
	v_mfma_f32_16x16x32_bf16 v[32:35], v[156:159], v[210:213], v[32:35]
	v_mfma_f32_16x16x32_bf16 v[24:27], v[148:151], v[222:225], v[24:27]
	v_mfma_f32_16x16x32_bf16 v[12:15], v[156:159], v[222:225], v[12:15]
	s_setprio 0
	s_setprio 1
	v_mfma_f32_16x16x32_bf16 v[52:55], v[160:163], v[186:189], v[52:55]
	v_mfma_f32_16x16x32_bf16 v[44:47], v[168:171], v[186:189], v[44:47]
	v_mfma_f32_16x16x32_bf16 v[36:39], v[160:163], v[198:201], v[36:39]
	v_mfma_f32_16x16x32_bf16 v[28:31], v[168:171], v[198:201], v[28:31]
	v_mfma_f32_16x16x32_bf16 v[20:23], v[160:163], v[206:209], v[20:23]
	v_mfma_f32_16x16x32_bf16 v[8:11], v[168:171], v[206:209], v[8:11]
	v_mfma_f32_16x16x32_bf16 v[4:7], v[160:163], v[218:221], v[4:7]
	v_mfma_f32_16x16x32_bf16 v[0:3], v[168:171], v[218:221], v[0:3]
	v_mfma_f32_16x16x32_bf16 v[52:55], v[164:167], v[190:193], v[52:55]
	v_mfma_f32_16x16x32_bf16 v[44:47], v[172:175], v[190:193], v[44:47]
	v_mfma_f32_16x16x32_bf16 v[36:39], v[164:167], v[202:205], v[36:39]
	v_mfma_f32_16x16x32_bf16 v[28:31], v[172:175], v[202:205], v[28:31]
	v_mfma_f32_16x16x32_bf16 v[20:23], v[164:167], v[210:213], v[20:23]
	v_mfma_f32_16x16x32_bf16 v[8:11], v[172:175], v[210:213], v[8:11]
	v_mfma_f32_16x16x32_bf16 v[4:7], v[164:167], v[222:225], v[4:7]
	v_mfma_f32_16x16x32_bf16 v[0:3], v[172:175], v[222:225], v[0:3]
	s_setprio 0
	s_barrier
	s_add_i32 s57, 0, 0x18000
	s_add_i32 s58, 0, 0x1c000
	v_add_u32_e32 v156, s57, v142
	v_add_u32_e32 v172, s58, v142
	ds_read_b128 v[144:147], v156
	ds_read_b128 v[148:151], v156 offset:1024
	ds_read_b128 v[152:155], v156 offset:2048
	ds_read_b128 v[156:159], v156 offset:3072
	ds_read_b128 v[160:163], v172
	ds_read_b128 v[164:167], v172 offset:1024
	ds_read_b128 v[168:171], v172 offset:2048
	ds_read_b128 v[172:175], v172 offset:3072
	s_add_u32 s16, s22, 0xb0000
	s_addc_u32 s17, s23, 0
	s_mov_b32 m0, s50
	v_lshl_add_u64 v[214:215], s[16:17], 0, v[134:135]
	ds_read_b128 v[186:189], v143 offset:32768
	ds_read_b128 v[190:193], v143 offset:33792
	ds_read_b128 v[198:201], v143 offset:34816
	ds_read_b128 v[202:205], v143 offset:35840
	ds_read_b128 v[206:209], v143 offset:36864
	ds_read_b128 v[210:213], v143 offset:37888
	ds_read_b128 v[218:221], v143 offset:38912
	ds_read_b128 v[222:225], v143 offset:39936
	global_load_lds_dwordx4 v[214:215], off
	v_lshl_add_u64 v[214:215], s[16:17], 0, v[132:133]
	s_mov_b32 m0, s51
	s_nop 0
	global_load_lds_dwordx4 v[214:215], off
	s_waitcnt vmcnt(8)
	s_waitcnt lgkmcnt(0)
	s_barrier
	s_setprio 1
	v_mfma_f32_16x16x32_bf16 v[128:131], v[144:147], v[186:189], v[128:131]
	v_mfma_f32_16x16x32_bf16 v[124:127], v[152:155], v[186:189], v[124:127]
	v_mfma_f32_16x16x32_bf16 v[120:123], v[144:147], v[198:201], v[120:123]
	v_mfma_f32_16x16x32_bf16 v[112:115], v[152:155], v[198:201], v[112:115]
	v_mfma_f32_16x16x32_bf16 v[104:107], v[144:147], v[206:209], v[104:107]
	v_mfma_f32_16x16x32_bf16 v[96:99], v[152:155], v[206:209], v[96:99]
	v_mfma_f32_16x16x32_bf16 v[88:91], v[144:147], v[218:221], v[88:91]
	v_mfma_f32_16x16x32_bf16 v[80:83], v[152:155], v[218:221], v[80:83]
	v_mfma_f32_16x16x32_bf16 v[128:131], v[148:151], v[190:193], v[128:131]
	v_mfma_f32_16x16x32_bf16 v[124:127], v[156:159], v[190:193], v[124:127]
	v_mfma_f32_16x16x32_bf16 v[120:123], v[148:151], v[202:205], v[120:123]
	v_mfma_f32_16x16x32_bf16 v[112:115], v[156:159], v[202:205], v[112:115]
	v_mfma_f32_16x16x32_bf16 v[104:107], v[148:151], v[210:213], v[104:107]
	v_mfma_f32_16x16x32_bf16 v[96:99], v[156:159], v[210:213], v[96:99]
	v_mfma_f32_16x16x32_bf16 v[88:91], v[148:151], v[222:225], v[88:91]
	v_mfma_f32_16x16x32_bf16 v[80:83], v[156:159], v[222:225], v[80:83]
	s_setprio 0
	s_setprio 1
	v_mfma_f32_16x16x32_bf16 v[116:119], v[160:163], v[186:189], v[116:119]
	v_mfma_f32_16x16x32_bf16 v[108:111], v[168:171], v[186:189], v[108:111]
	v_mfma_f32_16x16x32_bf16 v[100:103], v[160:163], v[198:201], v[100:103]
	v_mfma_f32_16x16x32_bf16 v[92:95], v[168:171], v[198:201], v[92:95]
	v_mfma_f32_16x16x32_bf16 v[84:87], v[160:163], v[206:209], v[84:87]
	v_mfma_f32_16x16x32_bf16 v[76:79], v[168:171], v[206:209], v[76:79]
	v_mfma_f32_16x16x32_bf16 v[72:75], v[160:163], v[218:221], v[72:75]
	v_mfma_f32_16x16x32_bf16 v[68:71], v[168:171], v[218:221], v[68:71]
	v_mfma_f32_16x16x32_bf16 v[116:119], v[164:167], v[190:193], v[116:119]
	v_mfma_f32_16x16x32_bf16 v[108:111], v[172:175], v[190:193], v[108:111]
	v_mfma_f32_16x16x32_bf16 v[100:103], v[164:167], v[202:205], v[100:103]
	v_mfma_f32_16x16x32_bf16 v[92:95], v[172:175], v[202:205], v[92:95]
	v_mfma_f32_16x16x32_bf16 v[84:87], v[164:167], v[210:213], v[84:87]
	v_mfma_f32_16x16x32_bf16 v[76:79], v[172:175], v[210:213], v[76:79]
	v_mfma_f32_16x16x32_bf16 v[72:75], v[164:167], v[222:225], v[72:75]
	v_mfma_f32_16x16x32_bf16 v[68:71], v[172:175], v[222:225], v[68:71]
	s_setprio 0
	s_barrier
; #define PG8_STAGE(bufoff, gbase, voff) do { _Pragma("unroll") for (int _i = 0; _i < 2; ++_i) \
;         __builtin_amdgcn_global_load_lds((const unsigned*)((const char*)(gbase) + (voff)[_i]), (LAS unsigned*)(lds + (bufoff) + ldsw + _i * 8192), 16, 0, 0); } while (0)
; #define PG8_LDA(dst, b, h) do { _Pragma("unroll") for (int m = 0; m < 4; ++m) _Pragma("unroll") for (int k = 0; k < 2; ++k) dst[m][k] = *(const LAS bf16x8*)(lds + PG8_SA(b, h) + aoff + m * 2048 + k * 1024); } while (0)
; #define PG8_MMA(ai, bj, At, Bt) do { __builtin_amdgcn_s_setprio(1); _Pragma("unroll") for (int m = 0; m < 4; ++m) _Pragma("unroll") for (int n = 0; n < 2; ++n) _Pragma("unroll") for (int k = 0; k < 2; ++k) \
;         acc[ai][bj][m][n] = __builtin_amdgcn_mfma_f32_16x16x32_bf16(Bt[n][k], At[m][k], acc[ai][bj][m][n], 0, 0, 0); __builtin_amdgcn_s_setprio(0); } while (0)
; #define PG8_WAIT_V(n) asm volatile("s_waitcnt vmcnt(" #n ")" ::: "memory")
; #define PG8_WAIT_L(n) asm volatile("s_waitcnt lgkmcnt(" #n ")" ::: "memory")
; #define PG8_BAR __builtin_amdgcn_s_barrier()
; #define PG8_SCHED __builtin_amdgcn_sched_barrier(0)
; template <class Epi, class Sched, bool ALIGN_EPI = true, bool SP2 = true>
; __device__ __forceinline__ void gemm_phase(LAS unsigned char* lds, const Gemm g, const Sched& S, const Epi& E) {
;     ...
;             PG8_LDA(At, 1, 1); PG8_STAGE(PG8_SB(1, 0), b3, voffB); PG8_STAGE(PG8_SB(1, 1), b3 + hstepB, voffB); PG8_STAGE(PG8_SA(1, 0), a3, voffA);
;             PG8_WAIT_V(8); PG8_WAIT_L(0); PG8_BAR; PG8_MMA(1, 0, At, B0); PG8_MMA(1, 1, At, B1); PG8_BAR; PG8_SCHED;
;         }
;         if constexpr (ALIGN_EPI) { if (wr == 0) PG8_BAR; }
	s_add_i32 s16, s57, s38
	v_lshl_add_u64 v[140:141], v[140:141], 0, s[14:15]
	s_mov_b32 m0, s16
	ds_read_b128 v[186:189], v143 offset:49152
	ds_read_b128 v[190:193], v143 offset:50176
	ds_read_b128 v[198:201], v143 offset:51200
	ds_read_b128 v[202:205], v143 offset:52224
	ds_read_b128 v[206:209], v143 offset:53248
	ds_read_b128 v[210:213], v143 offset:54272
	ds_read_b128 v[218:221], v143 offset:55296
	ds_read_b128 v[222:225], v143 offset:56320
	global_load_lds_dwordx4 v[140:141], off
	s_add_i32 m0, s16, 0x2000
	s_add_u32 s16, s20, 0xb0080
	v_lshl_add_u64 v[140:141], v[176:177], 0, s[14:15]
	s_addc_u32 s17, s21, 0
	s_add_i32 s20, s58, s38
	global_load_lds_dwordx4 v[140:141], off
	v_lshl_add_u64 v[140:141], s[16:17], 0, v[18:19]
	s_mov_b32 m0, s20
	s_nop 0
	global_load_lds_dwordx4 v[140:141], off
	v_lshl_add_u64 v[140:141], s[16:17], 0, v[16:17]
	s_add_i32 m0, s20, 0x2000
	s_nop 0
	global_load_lds_dwordx4 v[140:141], off
	v_lshl_add_u64 v[140:141], v[178:179], 0, s[14:15]
	s_mov_b32 m0, s8
	s_nop 0
	global_load_lds_dwordx4 v[140:141], off
	v_lshl_add_u64 v[140:141], v[182:183], 0, s[14:15]
	s_mov_b32 m0, s9
	s_nop 0
	global_load_lds_dwordx4 v[140:141], off
	s_waitcnt vmcnt(8)
	s_waitcnt lgkmcnt(0)
	s_barrier
	s_setprio 1
	v_mfma_f32_16x16x32_bf16 v[64:67], v[144:147], v[186:189], v[64:67]
	v_mfma_f32_16x16x32_bf16 v[60:63], v[152:155], v[186:189], v[60:63]
	v_mfma_f32_16x16x32_bf16 v[56:59], v[144:147], v[198:201], v[56:59]
	v_mfma_f32_16x16x32_bf16 v[48:51], v[152:155], v[198:201], v[48:51]
	v_mfma_f32_16x16x32_bf16 v[40:43], v[144:147], v[206:209], v[40:43]
	v_mfma_f32_16x16x32_bf16 v[32:35], v[152:155], v[206:209], v[32:35]
	v_mfma_f32_16x16x32_bf16 v[24:27], v[144:147], v[218:221], v[24:27]
	v_mfma_f32_16x16x32_bf16 v[12:15], v[152:155], v[218:221], v[12:15]
	v_mfma_f32_16x16x32_bf16 v[64:67], v[148:151], v[190:193], v[64:67]
	v_mfma_f32_16x16x32_bf16 v[60:63], v[156:159], v[190:193], v[60:63]
	v_mfma_f32_16x16x32_bf16 v[56:59], v[148:151], v[202:205], v[56:59]
	v_mfma_f32_16x16x32_bf16 v[48:51], v[156:159], v[202:205], v[48:51]
	v_mfma_f32_16x16x32_bf16 v[40:43], v[148:151], v[210:213], v[40:43]
	v_mfma_f32_16x16x32_bf16 v[32:35], v[156:159], v[210:213], v[32:35]
	v_mfma_f32_16x16x32_bf16 v[24:27], v[148:151], v[222:225], v[24:27]
	v_mfma_f32_16x16x32_bf16 v[12:15], v[156:159], v[222:225], v[12:15]
	s_setprio 0
	s_setprio 1
	v_mfma_f32_16x16x32_bf16 v[52:55], v[160:163], v[186:189], v[52:55]
	v_mfma_f32_16x16x32_bf16 v[44:47], v[168:171], v[186:189], v[44:47]
	v_mfma_f32_16x16x32_bf16 v[36:39], v[160:163], v[198:201], v[36:39]
	v_mfma_f32_16x16x32_bf16 v[28:31], v[168:171], v[198:201], v[28:31]
	v_mfma_f32_16x16x32_bf16 v[20:23], v[160:163], v[206:209], v[20:23]
	v_mfma_f32_16x16x32_bf16 v[8:11], v[168:171], v[206:209], v[8:11]
	v_mfma_f32_16x16x32_bf16 v[4:7], v[160:163], v[218:221], v[4:7]
	v_mfma_f32_16x16x32_bf16 v[0:3], v[168:171], v[218:221], v[0:3]
	v_mfma_f32_16x16x32_bf16 v[52:55], v[164:167], v[190:193], v[52:55]
	v_mfma_f32_16x16x32_bf16 v[44:47], v[172:175], v[190:193], v[44:47]
	v_mfma_f32_16x16x32_bf16 v[36:39], v[164:167], v[202:205], v[36:39]
	v_mfma_f32_16x16x32_bf16 v[28:31], v[172:175], v[202:205], v[28:31]
	v_mfma_f32_16x16x32_bf16 v[20:23], v[164:167], v[210:213], v[20:23]
	v_mfma_f32_16x16x32_bf16 v[8:11], v[172:175], v[210:213], v[8:11]
	v_mfma_f32_16x16x32_bf16 v[4:7], v[164:167], v[222:225], v[4:7]
	v_mfma_f32_16x16x32_bf16 v[0:3], v[172:175], v[222:225], v[0:3]
	s_setprio 0
	s_barrier
	s_add_i32 s56, s56, 2
	s_add_u32 s2, s2, 0x100
	s_addc_u32 s30, s30, 0
	s_cmp_gt_u32 s56, 41
	s_mov_b64 s[16:17], s[18:19]
	s_cbranch_scc0 .LBB0_1229
	s_and_b64 vcc, exec, s[36:37]
	s_cbranch_vccz .LBB0_1232
	s_barrier
